# FFN-up epilogue: removed wait states that guard nothing (s_nop before DPP movs of MFMA accumulators; s_nop between packed-f32 ops and plain VALU consumers); GEMM loops: removed repeated lgkmcnt(0) aft
# speedup vs baseline: 1.0108x; 1.0017x over previous
; #define PG8_STAGE(bufoff, gbase, voff) do { _Pragma("unroll") for (int _i = 0; _i < 2; ++_i) \
;         __builtin_amdgcn_global_load_lds((const GAS unsigned*)((const GAS char*)(gbase) + (size_t)_i * r64##voff + (vo##voff)), (LAS unsigned*)(lds + (bufoff) + ldsw + _i * 8192), 16, 0, 0); } while (0)
; #define PG8_LDA(dst, b, h) do { _Pragma("unroll") for (int m = 0; m < 4; ++m) _Pragma("unroll") for (int k = 0; k < 2; ++k) dst[m][k] = *(const LAS bf16x8*)(lds + PG8_SA(b, h) + aoff + m * 2048 + k * 1024); } while (0)
; #define PG8_LDB(dst, b, h) do { _Pragma("unroll") for (int n = 0; n < 2; ++n) _Pragma("unroll") for (int k = 0; k < 2; ++k) dst[n][k] = *(const LAS bf16x8*)(lds + PG8_SB(b, h) + boff + n * 2048 + k * 1024); } while (0)
; #define PG8_MMA(ai, bj, At, Bt) do { __builtin_amdgcn_s_setprio(1); _Pragma("unroll") for (int m = 0; m < 4; ++m) _Pragma("unroll") for (int n = 0; n < 2; ++n) _Pragma("unroll") for (int k = 0; k < 2; ++k) \
;         acc[ai][bj][m][n] = __builtin_amdgcn_mfma_f32_16x16x32_bf16(Bt[n][k], At[m][k], acc[ai][bj][m][n], 0, 0, 0); __builtin_amdgcn_s_setprio(0); } while (0)
; #define PG8_WAIT_V(n) asm volatile("s_waitcnt vmcnt(" #n ")" ::: "memory")
; #define PG8_WAIT_L(n) asm volatile("s_waitcnt lgkmcnt(" #n ")" ::: "memory")
; template <class Epi, class Map, bool ALIGN_EPI>
; __device__ __forceinline__ void gemm_phase(const int tid, LAS unsigned char* lds, const int lda, const int ldb, const int K, const Map& MP, const StaticOrder& S, const Epi& E) {
;     ...
;         for (int t = 0; t < nt; t += 2) {
;             const bool last = (t == nt - 2);
;             const char* a1 = cA + (size_t)(t + 1) * kstep;
;             const char* a2 = last ? nA : cA + (size_t)(t + 2) * kstep; const char* b2 = last ? nB : cB + (size_t)(t + 2) * kstep;
;             const char* a3 = a2 + kstep; const char* b3 = b2 + kstep;
;             PG8_LDB(B0, 0, 0); PG8_LDB(B1, 0, 1); PG8_SCHED; PG8_LDA(At, 0, 0); PG8_STAGE(PG8_SA(1, 1), a1 + hstepA, A);
;             PG8_WAIT_V(8); PG8_WAIT_L(0); PG8_BAR; PG8_MMA(0, 0, At, B0); PG8_MMA(0, 1, At, B1); PG8_BAR; PG8_SCHED;
;             PG8_LDA(At, 0, 1); PG8_STAGE(PG8_SB(0, 0), b2, B); PG8_STAGE(PG8_SB(0, 1), b2 + hstepB, B); PG8_STAGE(PG8_SA(0, 0), a2, A);
;             PG8_WAIT_V(8); PG8_WAIT_L(0); PG8_BAR; PG8_MMA(1, 0, At, B0); PG8_MMA(1, 1, At, B1); PG8_BAR; PG8_SCHED;
.LBB0_131:
	s_add_u32 s44, s42, 0xfffc0080
	s_addc_u32 s45, s43, -1
	s_add_i32 s49, 0, 0x10000
	s_cmp_eq_u32 s48, 12
	s_cselect_b32 s45, s23, s45
	s_cselect_b32 s44, s22, s44
	s_cselect_b32 s57, s47, s21
	s_cselect_b32 s56, s46, s17
	s_add_i32 s53, 0, 0x14000
	v_add_u32_e32 v108, s49, v214
	v_add_u32_e32 v124, s53, v214
	ds_read_b128 v[80:83], v108
	ds_read_b128 v[96:99], v108 offset:1024
	ds_read_b128 v[104:107], v108 offset:2048
	ds_read_b128 v[108:111], v108 offset:3072
	ds_read_b128 v[112:115], v124
	ds_read_b128 v[116:119], v124 offset:1024
	ds_read_b128 v[120:123], v124 offset:2048
	ds_read_b128 v[124:127], v124 offset:3072
	v_lshl_add_u64 v[192:193], s[42:43], 0, v[202:203]
	s_add_i32 m0, s24, 0xc000
	ds_read_b128 v[160:163], v215
	ds_read_b128 v[164:167], v215 offset:1024
	ds_read_b128 v[168:171], v215 offset:2048
	ds_read_b128 v[172:175], v215 offset:3072
	ds_read_b128 v[176:179], v215 offset:4096
	ds_read_b128 v[180:183], v215 offset:5120
	ds_read_b128 v[184:187], v215 offset:6144
	ds_read_b128 v[188:191], v215 offset:7168
	global_load_lds_dwordx4 v[192:193], off
	v_lshl_add_u64 v[192:193], v[192:193], 0, s[90:91]
	s_add_i32 m0, s24, 0xe000
	s_nop 0
	global_load_lds_dwordx4 v[192:193], off
	s_waitcnt vmcnt(8)
	s_waitcnt lgkmcnt(0)
	s_barrier
	s_setprio 1
	v_mfma_f32_16x16x32_bf16 v[156:159], v[80:83], v[160:163], v[156:159]
	v_mfma_f32_16x16x32_bf16 v[60:63], v[104:107], v[160:163], v[60:63]
	v_mfma_f32_16x16x32_bf16 v[148:151], v[80:83], v[168:171], v[148:151]
	v_mfma_f32_16x16x32_bf16 v[52:55], v[104:107], v[168:171], v[52:55]
	v_mfma_f32_16x16x32_bf16 v[152:155], v[80:83], v[176:179], v[152:155]
	v_mfma_f32_16x16x32_bf16 v[56:59], v[104:107], v[176:179], v[56:59]
	v_mfma_f32_16x16x32_bf16 v[136:139], v[80:83], v[184:187], v[136:139]
	v_mfma_f32_16x16x32_bf16 v[48:51], v[104:107], v[184:187], v[48:51]
	v_mfma_f32_16x16x32_bf16 v[156:159], v[96:99], v[164:167], v[156:159]
	v_mfma_f32_16x16x32_bf16 v[60:63], v[108:111], v[164:167], v[60:63]
	v_mfma_f32_16x16x32_bf16 v[148:151], v[96:99], v[172:175], v[148:151]
	v_mfma_f32_16x16x32_bf16 v[52:55], v[108:111], v[172:175], v[52:55]
	v_mfma_f32_16x16x32_bf16 v[152:155], v[96:99], v[180:183], v[152:155]
	v_mfma_f32_16x16x32_bf16 v[56:59], v[108:111], v[180:183], v[56:59]
	v_mfma_f32_16x16x32_bf16 v[136:139], v[96:99], v[188:191], v[136:139]
	v_mfma_f32_16x16x32_bf16 v[48:51], v[108:111], v[188:191], v[48:51]
	s_setprio 0
	s_setprio 1
	v_mfma_f32_16x16x32_bf16 v[144:147], v[112:115], v[160:163], v[144:147]
	v_mfma_f32_16x16x32_bf16 v[36:39], v[120:123], v[160:163], v[36:39]
	v_mfma_f32_16x16x32_bf16 v[128:131], v[112:115], v[168:171], v[128:131]
	v_mfma_f32_16x16x32_bf16 v[32:35], v[120:123], v[168:171], v[32:35]
	v_mfma_f32_16x16x32_bf16 v[140:143], v[112:115], v[176:179], v[140:143]
	v_mfma_f32_16x16x32_bf16 v[44:47], v[120:123], v[176:179], v[44:47]
	v_mfma_f32_16x16x32_bf16 v[132:135], v[112:115], v[184:187], v[132:135]
	v_mfma_f32_16x16x32_bf16 v[40:43], v[120:123], v[184:187], v[40:43]
	v_mfma_f32_16x16x32_bf16 v[144:147], v[116:119], v[164:167], v[144:147]
	v_mfma_f32_16x16x32_bf16 v[36:39], v[124:127], v[164:167], v[36:39]
	v_mfma_f32_16x16x32_bf16 v[128:131], v[116:119], v[172:175], v[128:131]
	v_mfma_f32_16x16x32_bf16 v[32:35], v[124:127], v[172:175], v[32:35]
	v_mfma_f32_16x16x32_bf16 v[140:143], v[116:119], v[180:183], v[140:143]
	v_mfma_f32_16x16x32_bf16 v[44:47], v[124:127], v[180:183], v[44:47]
	v_mfma_f32_16x16x32_bf16 v[132:135], v[116:119], v[188:191], v[132:135]
	v_mfma_f32_16x16x32_bf16 v[40:43], v[124:127], v[188:191], v[40:43]
	s_setprio 0
	s_barrier
	s_add_i32 s49, s49, s19
	v_lshl_add_u64 v[192:193], s[56:57], 0, v[200:201]
	s_mov_b32 m0, s49
	ds_read_b128 v[160:163], v215 offset:16384
	ds_read_b128 v[164:167], v215 offset:17408
	ds_read_b128 v[168:171], v215 offset:18432
	ds_read_b128 v[172:175], v215 offset:19456
	ds_read_b128 v[176:179], v215 offset:20480
	ds_read_b128 v[180:183], v215 offset:21504
	ds_read_b128 v[184:187], v215 offset:22528
	ds_read_b128 v[188:191], v215 offset:23552
	global_load_lds_dwordx4 v[192:193], off
	v_lshl_add_u64 v[194:195], v[192:193], 0, s[90:91]
	s_add_i32 m0, s49, 0x2000
	s_add_i32 s49, s53, s19
	global_load_lds_dwordx4 v[194:195], off
	v_lshl_add_u64 v[194:195], v[192:193], 0, s[74:75]
	s_mov_b32 m0, s49
	s_nop 0
	global_load_lds_dwordx4 v[194:195], off
	v_lshl_add_u64 v[194:195], v[192:193], 0, s[94:95]
	s_add_i32 m0, s49, 0x2000
	s_nop 0
	global_load_lds_dwordx4 v[194:195], off
	v_lshl_add_u64 v[194:195], s[44:45], 0, v[202:203]
	s_mov_b32 m0, s24
	v_lshl_add_u64 v[196:197], v[194:195], 0, s[90:91]
	global_load_lds_dwordx4 v[194:195], off
	s_mov_b32 m0, s28
	s_nop 0
	global_load_lds_dwordx4 v[196:197], off
	s_waitcnt vmcnt(8)
	s_waitcnt lgkmcnt(0)
	s_barrier
; #define PG8_STAGE(bufoff, gbase, voff) do { _Pragma("unroll") for (int _i = 0; _i < 2; ++_i) \
;         __builtin_amdgcn_global_load_lds((const GAS unsigned*)((const GAS char*)(gbase) + (size_t)_i * r64##voff + (vo##voff)), (LAS unsigned*)(lds + (bufoff) + ldsw + _i * 8192), 16, 0, 0); } while (0)
; #define PG8_LDA(dst, b, h) do { _Pragma("unroll") for (int m = 0; m < 4; ++m) _Pragma("unroll") for (int k = 0; k < 2; ++k) dst[m][k] = *(const LAS bf16x8*)(lds + PG8_SA(b, h) + aoff + m * 2048 + k * 1024); } while (0)
; #define PG8_LDB(dst, b, h) do { _Pragma("unroll") for (int n = 0; n < 2; ++n) _Pragma("unroll") for (int k = 0; k < 2; ++k) dst[n][k] = *(const LAS bf16x8*)(lds + PG8_SB(b, h) + boff + n * 2048 + k * 1024); } while (0)
; #define PG8_MMA(ai, bj, At, Bt) do { __builtin_amdgcn_s_setprio(1); _Pragma("unroll") for (int m = 0; m < 4; ++m) _Pragma("unroll") for (int n = 0; n < 2; ++n) _Pragma("unroll") for (int k = 0; k < 2; ++k) \
;         acc[ai][bj][m][n] = __builtin_amdgcn_mfma_f32_16x16x32_bf16(Bt[n][k], At[m][k], acc[ai][bj][m][n], 0, 0, 0); __builtin_amdgcn_s_setprio(0); } while (0)
; #define PG8_WAIT_V(n) asm volatile("s_waitcnt vmcnt(" #n ")" ::: "memory")
; #define PG8_WAIT_L(n) asm volatile("s_waitcnt lgkmcnt(" #n ")" ::: "memory")
; template <class Epi, class Map, bool ALIGN_EPI>
; __device__ __forceinline__ void gemm_phase(const int tid, LAS unsigned char* lds, const int lda, const int ldb, const int K, const Map& MP, const StaticOrder& S, const Epi& E) {
;     ...
;             PG8_WAIT_V(8); PG8_WAIT_L(0); PG8_BAR; PG8_MMA(0, 0, At, B0); PG8_MMA(0, 1, At, B1); PG8_BAR; PG8_SCHED;
;             PG8_LDA(At, 0, 1); PG8_STAGE(PG8_SB(0, 0), b2, B); PG8_STAGE(PG8_SB(0, 1), b2 + hstepB, B); PG8_STAGE(PG8_SA(0, 0), a2, A);
;             PG8_WAIT_V(8); PG8_WAIT_L(0); PG8_BAR; PG8_MMA(1, 0, At, B0); PG8_MMA(1, 1, At, B1); PG8_BAR; PG8_SCHED;
;             PG8_LDB(B0, 1, 0); PG8_LDB(B1, 1, 1); PG8_SCHED; PG8_LDA(At, 1, 0); PG8_STAGE(PG8_SA(0, 1), a2 + hstepA, A);
;             PG8_WAIT_V(8); PG8_WAIT_L(0); PG8_BAR; PG8_MMA(0, 0, At, B0); PG8_MMA(0, 1, At, B1); PG8_BAR; PG8_SCHED;
;             PG8_LDA(At, 1, 1); PG8_STAGE(PG8_SB(1, 0), b3, B); PG8_STAGE(PG8_SB(1, 1), b3 + hstepB, B); PG8_STAGE(PG8_SA(1, 0), a3, A);
;             PG8_WAIT_V(8); PG8_WAIT_L(0); PG8_BAR; PG8_MMA(1, 0, At, B0); PG8_MMA(1, 1, At, B1); PG8_BAR; PG8_SCHED;
	s_setprio 1
	v_mfma_f32_16x16x32_bf16 v[100:103], v[80:83], v[160:163], v[100:103]
	v_mfma_f32_16x16x32_bf16 v[4:7], v[104:107], v[160:163], v[4:7]
	v_mfma_f32_16x16x32_bf16 v[64:67], v[80:83], v[168:171], v[64:67]
	v_mfma_f32_16x16x32_bf16 v[0:3], v[104:107], v[168:171], v[0:3]
	v_mfma_f32_16x16x32_bf16 v[92:95], v[80:83], v[176:179], v[92:95]
	v_mfma_f32_16x16x32_bf16 v[16:19], v[104:107], v[176:179], v[16:19]
	v_mfma_f32_16x16x32_bf16 v[68:71], v[80:83], v[184:187], v[68:71]
	v_mfma_f32_16x16x32_bf16 v[8:11], v[104:107], v[184:187], v[8:11]
	v_mfma_f32_16x16x32_bf16 v[100:103], v[96:99], v[164:167], v[100:103]
	v_mfma_f32_16x16x32_bf16 v[4:7], v[108:111], v[164:167], v[4:7]
	v_mfma_f32_16x16x32_bf16 v[64:67], v[96:99], v[172:175], v[64:67]
	v_mfma_f32_16x16x32_bf16 v[0:3], v[108:111], v[172:175], v[0:3]
	v_mfma_f32_16x16x32_bf16 v[92:95], v[96:99], v[180:183], v[92:95]
	v_mfma_f32_16x16x32_bf16 v[16:19], v[108:111], v[180:183], v[16:19]
	v_mfma_f32_16x16x32_bf16 v[68:71], v[96:99], v[188:191], v[68:71]
	v_mfma_f32_16x16x32_bf16 v[8:11], v[108:111], v[188:191], v[8:11]
	s_setprio 0
	s_setprio 1
	v_mfma_f32_16x16x32_bf16 v[20:23], v[120:123], v[160:163], v[20:23]
	v_mfma_f32_16x16x32_bf16 v[72:75], v[112:115], v[168:171], v[72:75]
	v_mfma_f32_16x16x32_bf16 v[12:15], v[120:123], v[168:171], v[12:15]
	v_mfma_f32_16x16x32_bf16 v[84:87], v[112:115], v[176:179], v[84:87]
	v_mfma_f32_16x16x32_bf16 v[28:31], v[120:123], v[176:179], v[28:31]
	v_mfma_f32_16x16x32_bf16 v[76:79], v[112:115], v[184:187], v[76:79]
	v_mfma_f32_16x16x32_bf16 v[24:27], v[120:123], v[184:187], v[24:27]
	v_mfma_f32_16x16x32_bf16 v[80:83], v[112:115], v[160:163], v[88:91]
	v_mfma_f32_16x16x32_bf16 v[20:23], v[124:127], v[164:167], v[20:23]
	v_mfma_f32_16x16x32_bf16 v[72:75], v[116:119], v[172:175], v[72:75]
	v_mfma_f32_16x16x32_bf16 v[12:15], v[124:127], v[172:175], v[12:15]
	v_mfma_f32_16x16x32_bf16 v[84:87], v[116:119], v[180:183], v[84:87]
	v_mfma_f32_16x16x32_bf16 v[28:31], v[124:127], v[180:183], v[28:31]
	v_mfma_f32_16x16x32_bf16 v[76:79], v[116:119], v[188:191], v[76:79]
	v_mfma_f32_16x16x32_bf16 v[24:27], v[124:127], v[188:191], v[24:27]
	v_mfma_f32_16x16x32_bf16 v[80:83], v[116:119], v[164:167], v[80:83]
	s_setprio 0
	s_barrier
	s_add_i32 s44, 0, 0x18000
	s_add_i32 s45, 0, 0x1c000
	v_add_u32_e32 v108, s44, v214
	v_add_u32_e32 v124, s45, v214
	ds_read_b128 v[88:91], v108
	ds_read_b128 v[96:99], v108 offset:1024
	ds_read_b128 v[104:107], v108 offset:2048
	ds_read_b128 v[108:111], v108 offset:3072
	ds_read_b128 v[112:115], v124
	ds_read_b128 v[116:119], v124 offset:1024
	ds_read_b128 v[120:123], v124 offset:2048
	ds_read_b128 v[124:127], v124 offset:3072
	s_mov_b32 m0, s29
	v_lshl_add_u64 v[196:197], v[194:195], 0, s[74:75]
	ds_read_b128 v[160:163], v215 offset:32768
	ds_read_b128 v[164:167], v215 offset:33792
	ds_read_b128 v[168:171], v215 offset:34816
	ds_read_b128 v[172:175], v215 offset:35840
	ds_read_b128 v[176:179], v215 offset:36864
	ds_read_b128 v[180:183], v215 offset:37888
	ds_read_b128 v[184:187], v215 offset:38912
	ds_read_b128 v[188:191], v215 offset:39936
	global_load_lds_dwordx4 v[196:197], off
	v_lshl_add_u64 v[196:197], v[194:195], 0, s[94:95]
	s_mov_b32 m0, s30
	s_nop 0
	global_load_lds_dwordx4 v[196:197], off
	s_waitcnt vmcnt(8)
	s_waitcnt lgkmcnt(0)
	s_barrier
	s_setprio 1
	v_mfma_f32_16x16x32_bf16 v[156:159], v[88:91], v[160:163], v[156:159]
	v_mfma_f32_16x16x32_bf16 v[60:63], v[104:107], v[160:163], v[60:63]
	v_mfma_f32_16x16x32_bf16 v[148:151], v[88:91], v[168:171], v[148:151]
	v_mfma_f32_16x16x32_bf16 v[52:55], v[104:107], v[168:171], v[52:55]
	v_mfma_f32_16x16x32_bf16 v[152:155], v[88:91], v[176:179], v[152:155]
	v_mfma_f32_16x16x32_bf16 v[56:59], v[104:107], v[176:179], v[56:59]
	v_mfma_f32_16x16x32_bf16 v[136:139], v[88:91], v[184:187], v[136:139]
	v_mfma_f32_16x16x32_bf16 v[48:51], v[104:107], v[184:187], v[48:51]
	v_mfma_f32_16x16x32_bf16 v[156:159], v[96:99], v[164:167], v[156:159]
	v_mfma_f32_16x16x32_bf16 v[60:63], v[108:111], v[164:167], v[60:63]
	v_mfma_f32_16x16x32_bf16 v[148:151], v[96:99], v[172:175], v[148:151]
	v_mfma_f32_16x16x32_bf16 v[52:55], v[108:111], v[172:175], v[52:55]
	v_mfma_f32_16x16x32_bf16 v[152:155], v[96:99], v[180:183], v[152:155]
	v_mfma_f32_16x16x32_bf16 v[56:59], v[108:111], v[180:183], v[56:59]
	v_mfma_f32_16x16x32_bf16 v[136:139], v[96:99], v[188:191], v[136:139]
	v_mfma_f32_16x16x32_bf16 v[48:51], v[108:111], v[188:191], v[48:51]
	s_setprio 0
	s_setprio 1
	v_mfma_f32_16x16x32_bf16 v[144:147], v[112:115], v[160:163], v[144:147]
	v_mfma_f32_16x16x32_bf16 v[36:39], v[120:123], v[160:163], v[36:39]
	v_mfma_f32_16x16x32_bf16 v[128:131], v[112:115], v[168:171], v[128:131]
	v_mfma_f32_16x16x32_bf16 v[32:35], v[120:123], v[168:171], v[32:35]
	v_mfma_f32_16x16x32_bf16 v[140:143], v[112:115], v[176:179], v[140:143]
	v_mfma_f32_16x16x32_bf16 v[44:47], v[120:123], v[176:179], v[44:47]
	v_mfma_f32_16x16x32_bf16 v[132:135], v[112:115], v[184:187], v[132:135]
	v_mfma_f32_16x16x32_bf16 v[40:43], v[120:123], v[184:187], v[40:43]
	v_mfma_f32_16x16x32_bf16 v[144:147], v[116:119], v[164:167], v[144:147]
	v_mfma_f32_16x16x32_bf16 v[36:39], v[124:127], v[164:167], v[36:39]
	v_mfma_f32_16x16x32_bf16 v[128:131], v[116:119], v[172:175], v[128:131]
	v_mfma_f32_16x16x32_bf16 v[32:35], v[124:127], v[172:175], v[32:35]
	v_mfma_f32_16x16x32_bf16 v[140:143], v[116:119], v[180:183], v[140:143]
	v_mfma_f32_16x16x32_bf16 v[44:47], v[124:127], v[180:183], v[44:47]
	v_mfma_f32_16x16x32_bf16 v[132:135], v[116:119], v[188:191], v[132:135]
	v_mfma_f32_16x16x32_bf16 v[40:43], v[124:127], v[188:191], v[40:43]
	s_setprio 0
	s_barrier
; #define GAS __attribute__((address_space(1)))
; #define PG8_LDA(dst, b, h) do { _Pragma("unroll") for (int m = 0; m < 4; ++m) _Pragma("unroll") for (int k = 0; k < 2; ++k) dst[m][k] = *(const LAS bf16x8*)(lds + PG8_SA(b, h) + aoff + m * 2048 + k * 1024); } while (0)
;     __device__ __forceinline__ void operator()(f32x4 (&acc)[2][2][4][2], const Unit& u, int wr, int wc, int lane) const {
;         const int fr = lane & 15, fq = lane >> 4;
;         const int colu = u.pn * 128 + wc * 32;
;         const GAS float* cwu = cw + colu; const GAS float* cbu = cb + colu;
;         u32x2 keep[2][4];
;         f32x4 wgt[2][8];
; #pragma unroll
;         for (int n = 0; n < 2; ++n) { const unsigned co = (unsigned)(8 * fq + 4 * n) * 4u;
;             wgt[n][0] = gld<f32x4>(cwu, co); wgt[n][1] = gld<f32x4>(cwu + NUP, co); wgt[n][2] = gld<f32x4>(cwu + 2 * NUP, co); wgt[n][3] = gld<f32x4>(cbu, co);
;             wgt[n][4] = gld<f32x4>(cwu + DFF, co); wgt[n][5] = gld<f32x4>(cwu + NUP + DFF, co); wgt[n][6] = gld<f32x4>(cwu + 2 * NUP + DFF, co); wgt[n][7] = gld<f32x4>(cbu + DFF, co); }
; template <class Epi, class Map, bool ALIGN_EPI>
; __device__ __forceinline__ void gemm_phase(const int tid, LAS unsigned char* lds, const int lda, const int ldb, const int K, const Map& MP, const StaticOrder& S, const Epi& E) {
;     ...
;             PG8_LDB(B0, 0, 0); PG8_LDB(B1, 0, 1); PG8_SCHED; PG8_LDA(At, 0, 0); PG8_STAGE(PG8_SA(1, 1), a1 + hstepA, A);
;             PG8_WAIT_V(8); PG8_WAIT_L(0); PG8_BAR; PG8_MMA(0, 0, At, B0); PG8_MMA(0, 1, At, B1); PG8_BAR; PG8_SCHED;
;             PG8_LDA(At, 0, 1); PG8_STAGE(PG8_SB(0, 0), b2, B); PG8_STAGE(PG8_SB(0, 1), b2 + hstepB, B); PG8_STAGE(PG8_SA(0, 0), a2, A);
;             PG8_WAIT_V(8); PG8_WAIT_L(0); PG8_BAR; PG8_MMA(1, 0, At, B0); PG8_MMA(1, 1, At, B1); PG8_BAR; PG8_SCHED;
;             PG8_LDB(B0, 1, 0); PG8_LDB(B1, 1, 1); PG8_SCHED; PG8_LDA(At, 1, 0); PG8_STAGE(PG8_SA(0, 1), a2 + hstepA, A);
;             PG8_WAIT_V(8); PG8_WAIT_L(0); PG8_BAR; PG8_MMA(0, 0, At, B0); PG8_MMA(0, 1, At, B1); PG8_BAR; PG8_SCHED;
;             PG8_LDA(At, 1, 1); PG8_STAGE(PG8_SB(1, 0), b3, B); PG8_STAGE(PG8_SB(1, 1), b3 + hstepB, B); PG8_STAGE(PG8_SA(1, 0), a3, A);
;             PG8_WAIT_V(8); PG8_WAIT_L(0); PG8_BAR; PG8_MMA(1, 0, At, B0); PG8_MMA(1, 1, At, B1); PG8_BAR; PG8_SCHED;
;         }
;         if constexpr (ALIGN_EPI) { if (wr == 0) PG8_BAR; }
	s_add_i32 s44, s44, s19
	v_lshl_add_u64 v[196:197], v[192:193], 0, s[50:51]
	s_mov_b32 m0, s44
	ds_read_b128 v[160:163], v215 offset:49152
	ds_read_b128 v[164:167], v215 offset:50176
	ds_read_b128 v[168:171], v215 offset:51200
	ds_read_b128 v[172:175], v215 offset:52224
	ds_read_b128 v[176:179], v215 offset:53248
	ds_read_b128 v[180:183], v215 offset:54272
	ds_read_b128 v[184:187], v215 offset:55296
	ds_read_b128 v[188:191], v215 offset:56320
	global_load_lds_dwordx4 v[196:197], off
	v_lshl_add_u64 v[196:197], v[192:193], 0, s[54:55]
	s_add_i32 m0, s44, 0x2000
	s_add_i32 s44, s45, s19
	global_load_lds_dwordx4 v[196:197], off
	v_lshl_add_u64 v[196:197], v[192:193], 0, s[96:97]
	s_mov_b32 m0, s44
	v_lshl_add_u64 v[192:193], v[192:193], 0, s[6:7]
	global_load_lds_dwordx4 v[196:197], off
	s_add_i32 m0, s44, 0x2000
	s_nop 0
	global_load_lds_dwordx4 v[192:193], off
	v_lshl_add_u64 v[192:193], v[194:195], 0, s[50:51]
	s_mov_b32 m0, s39
	s_nop 0
	global_load_lds_dwordx4 v[192:193], off
	v_lshl_add_u64 v[192:193], v[194:195], 0, s[54:55]
	s_mov_b32 m0, s58
	s_nop 0
	global_load_lds_dwordx4 v[192:193], off
	s_waitcnt vmcnt(8)
	s_waitcnt lgkmcnt(0)
	s_barrier
	s_setprio 1
	v_mfma_f32_16x16x32_bf16 v[100:103], v[88:91], v[160:163], v[100:103]
	v_mfma_f32_16x16x32_bf16 v[4:7], v[104:107], v[160:163], v[4:7]
	v_mfma_f32_16x16x32_bf16 v[64:67], v[88:91], v[168:171], v[64:67]
	v_mfma_f32_16x16x32_bf16 v[0:3], v[104:107], v[168:171], v[0:3]
	v_mfma_f32_16x16x32_bf16 v[92:95], v[88:91], v[176:179], v[92:95]
	v_mfma_f32_16x16x32_bf16 v[16:19], v[104:107], v[176:179], v[16:19]
	v_mfma_f32_16x16x32_bf16 v[68:71], v[88:91], v[184:187], v[68:71]
	v_mfma_f32_16x16x32_bf16 v[8:11], v[104:107], v[184:187], v[8:11]
	v_mfma_f32_16x16x32_bf16 v[100:103], v[96:99], v[164:167], v[100:103]
	v_mfma_f32_16x16x32_bf16 v[4:7], v[108:111], v[164:167], v[4:7]
	v_mfma_f32_16x16x32_bf16 v[64:67], v[96:99], v[172:175], v[64:67]
	v_mfma_f32_16x16x32_bf16 v[0:3], v[108:111], v[172:175], v[0:3]
	v_mfma_f32_16x16x32_bf16 v[92:95], v[96:99], v[180:183], v[92:95]
	v_mfma_f32_16x16x32_bf16 v[16:19], v[108:111], v[180:183], v[16:19]
	v_mfma_f32_16x16x32_bf16 v[68:71], v[96:99], v[188:191], v[68:71]
	v_mfma_f32_16x16x32_bf16 v[8:11], v[108:111], v[188:191], v[8:11]
	s_setprio 0
	s_setprio 1
	v_mfma_f32_16x16x32_bf16 v[80:83], v[112:115], v[160:163], v[80:83]
	v_mfma_f32_16x16x32_bf16 v[88:91], v[116:119], v[164:167], v[80:83]
	v_mfma_f32_16x16x32_bf16 v[20:23], v[120:123], v[160:163], v[20:23]
	v_mfma_f32_16x16x32_bf16 v[72:75], v[112:115], v[168:171], v[72:75]
	v_mfma_f32_16x16x32_bf16 v[12:15], v[120:123], v[168:171], v[12:15]
	v_mfma_f32_16x16x32_bf16 v[80:83], v[112:115], v[176:179], v[84:87]
	v_mfma_f32_16x16x32_bf16 v[28:31], v[120:123], v[176:179], v[28:31]
	v_mfma_f32_16x16x32_bf16 v[76:79], v[112:115], v[184:187], v[76:79]
	v_mfma_f32_16x16x32_bf16 v[24:27], v[120:123], v[184:187], v[24:27]
	v_mfma_f32_16x16x32_bf16 v[20:23], v[124:127], v[164:167], v[20:23]
	v_mfma_f32_16x16x32_bf16 v[72:75], v[116:119], v[172:175], v[72:75]
	v_mfma_f32_16x16x32_bf16 v[12:15], v[124:127], v[172:175], v[12:15]
	v_mfma_f32_16x16x32_bf16 v[84:87], v[116:119], v[180:183], v[80:83]
	v_mfma_f32_16x16x32_bf16 v[28:31], v[124:127], v[180:183], v[28:31]
	v_mfma_f32_16x16x32_bf16 v[76:79], v[116:119], v[188:191], v[76:79]
	v_mfma_f32_16x16x32_bf16 v[24:27], v[124:127], v[188:191], v[24:27]
	s_setprio 0
	s_barrier
	s_add_i32 s48, s48, 2
	s_add_u32 s17, s17, 0x100
	s_addc_u32 s21, s21, 0
	s_add_u32 s42, s42, 0x100
	s_addc_u32 s43, s43, 0
	s_cmp_gt_u32 s48, 13
	s_cbranch_scc0 .LBB0_131
	s_and_b64 vcc, exec, s[10:11]
	s_cbranch_vccz .LBB0_134
	s_barrier
.LBB0_134:
	s_lshl_b32 s17, s52, 7
	s_or_b32 s48, s17, s37
	s_ashr_i32 s49, s48, 31
	s_lshl_b64 s[42:43], s[48:49], 2
	v_mbcnt_lo_u32_b32 v230, -1, 0
	v_mbcnt_hi_u32_b32 v230, -1, v230
	s_add_u32 s44, s0, s42
	v_lshlrev_b32_e32 v80, 1, v230
	s_addc_u32 s45, s1, s43
	v_and_b32_e32 v216, 0xffffffe0, v80
	v_lshl_add_u64 v[120:121], s[44:45], 0, v[216:217]
	s_movk_i32 s17, 0x5000
	v_add_co_u32_e32 v98, vcc, s17, v120
	global_load_dwordx4 v[80:83], v216, s[44:45] offset:16
	global_load_dwordx4 v[168:171], v216, s[44:45]
	s_mov_b64 s[44:45], 0x5800
	v_addc_co_u32_e32 v99, vcc, 0, v121, vcc
	s_mov_b32 s17, 0xb000
	s_add_u32 s42, s4, s42
	v_lshl_add_u64 v[96:97], v[120:121], 0, s[44:45]
	s_mov_b64 s[44:45], 0xb000
	v_add_co_u32_e32 v106, vcc, s17, v120
	s_addc_u32 s43, s5, s43
	v_lshl_add_u64 v[104:105], v[120:121], 0, s[44:45]
	v_addc_co_u32_e32 v107, vcc, 0, v121, vcc
	global_load_dwordx4 v[172:175], v[98:99], off offset:2048
	s_nop 0
	global_load_dwordx4 v[96:99], v[96:97], off offset:16
	s_nop 0
	global_load_dwordx4 v[176:179], v[106:107], off
	s_nop 0
	global_load_dwordx4 v[104:107], v[104:105], off offset:16
	s_nop 0
	global_load_dwordx4 v[108:111], v216, s[42:43] offset:16
	global_load_dwordx4 v[184:187], v216, s[42:43]
	v_add_co_u32_e32 v114, vcc, s88, v120
	s_mov_b32 s17, 0x8000
	s_nop 0
	v_addc_co_u32_e32 v115, vcc, 0, v121, vcc
	v_lshl_add_u64 v[124:125], s[42:43], 0, v[216:217]
	s_mov_b64 s[42:43], 0x8400
	v_add_co_u32_e32 v118, vcc, s17, v120
	v_lshl_add_u64 v[116:117], v[120:121], 0, s[42:43]
	s_nop 0
	v_addc_co_u32_e32 v119, vcc, 0, v121, vcc
	s_mov_b64 s[42:43], 0xdc00
	s_mov_b32 s17, 0xd000
	v_lshl_add_u64 v[112:113], v[120:121], 0, s[68:69]
	v_lshl_add_u64 v[122:123], v[120:121], 0, s[42:43]
	v_add_co_u32_e32 v120, vcc, s17, v120
	v_lshl_add_u64 v[126:127], v[124:125], 0, s[68:69]
	s_nop 0
	v_addc_co_u32_e32 v121, vcc, 0, v121, vcc
	v_add_co_u32_e32 v124, vcc, s88, v124
	global_load_dwordx4 v[180:183], v[114:115], off offset:3072
	s_nop 0
	global_load_dwordx4 v[112:115], v[112:113], off offset:16
	v_addc_co_u32_e32 v125, vcc, 0, v125, vcc
	global_load_dwordx4 v[188:191], v[118:119], off offset:1024
	s_nop 0
	global_load_dwordx4 v[116:119], v[116:117], off offset:16
	s_nop 0
	global_load_dwordx4 v[192:195], v[120:121], off offset:3072
	s_nop 0
	global_load_dwordx4 v[120:123], v[122:123], off offset:16
	s_nop 0
	global_load_dwordx4 v[196:199], v[124:125], off offset:3072
	s_nop 0
	global_load_dwordx4 v[124:127], v[126:127], off offset:16
	v_mov_b32_dpp v160, v136 row_shr:1 row_mask:0xf bank_mask:0xf bound_ctrl:1
	v_mov_b32_dpp v161, v137 row_shr:1 row_mask:0xf bank_mask:0xf bound_ctrl:1
	v_mov_b32_dpp v204, v156 row_shl:1 row_mask:0xf bank_mask:0xf bound_ctrl:1
	v_mov_b32_dpp v205, v157 row_shl:1 row_mask:0xf bank_mask:0xf bound_ctrl:1
	s_mov_b64 s[44:45], -1
	s_waitcnt vmcnt(0)
;     __device__ __forceinline__ void conv4(const f32x4& a0, const f32x4& a1, const f32x4& a2, const f32x4& a3, const f32x4& w0, const f32x4& w1, const f32x4& w2, const f32x4& b, f32x2 (&h)[4][2]) const {
; #pragma unroll
;         for (int p = 0; p < 2; ++p) {
;             float u0, u1, d0, d1;
;             asm volatile("s_nop 1\n\tv_mov_b32_dpp %0, %1 row_shr:1 row_mask:0xf bank_mask:0xf bound_ctrl:1" : "=&v"(u0) : "v"(a3[2 * p]));
;             asm volatile("s_nop 1\n\tv_mov_b32_dpp %0, %1 row_shr:1 row_mask:0xf bank_mask:0xf bound_ctrl:1" : "=&v"(u1) : "v"(a3[2 * p + 1]));
;             asm volatile("s_nop 1\n\tv_mov_b32_dpp %0, %1 row_shl:1 row_mask:0xf bank_mask:0xf bound_ctrl:1" : "=&v"(d0) : "v"(a0[2 * p]));
;             asm volatile("s_nop 1\n\tv_mov_b32_dpp %0, %1 row_shl:1 row_mask:0xf bank_mask:0xf bound_ctrl:1" : "=&v"(d1) : "v"(a0[2 * p + 1]));
;             const f32x2 UP = {u0, u1}, DN = {d0, d1};
;             const f32x2 A0 = {a0[2 * p], a0[2 * p + 1]}, A1 = {a1[2 * p], a1[2 * p + 1]}, A2 = {a2[2 * p], a2[2 * p + 1]}, A3 = {a3[2 * p], a3[2 * p + 1]};
;             const f32x2 W0 = {w0[2 * p], w0[2 * p + 1]}, W1 = {w1[2 * p], w1[2 * p + 1]}, W2 = {w2[2 * p], w2[2 * p + 1]}, B = {b[2 * p], b[2 * p + 1]};
;             h[0][p] = B + W0 * UP + W1 * A0 + W2 * A1;
;             h[1][p] = B + W0 * A0 + W1 * A1 + W2 * A2;
;             h[2][p] = B + W0 * A1 + W1 * A2 + W2 * A3;
;             h[3][p] = B + W0 * A2 + W1 * A3 + W2 * DN;
;         }
;     }
;     static __device__ __forceinline__ unsigned silu_pk(const f32x2 g, const f32x2 v) {
;         const f32x2 t = g * -1.4426950408889634f;
;         const f32x2 d = (f32x2){__builtin_amdgcn_exp2f(t.x), __builtin_amdgcn_exp2f(t.y)} + 1.0f;
;         const f32x2 o = g * v * (f32x2){__builtin_amdgcn_rcpf(d.x), __builtin_amdgcn_rcpf(d.y)};
;         return cvt_pk_bf16(o.x, o.y);
;     }
;     __device__ __forceinline__ void operator()(f32x4 (&acc)[2][2][4][2], const Unit& u, int wr, int wc, int lane) const {
;     ...
;                 conv4(acc[ai][0][0][n], acc[ai][0][1][n], acc[ai][0][2][n], acc[ai][0][3][n], wg0, wg1, wg2, bg, hg);
;                 conv4(acc[ai][1][0][n], acc[ai][1][1][n], acc[ai][1][2][n], acc[ai][1][3][n], wv0, wv1, wv2, bvv, hv);
; #pragma unroll
;                 for (int m = 0; m < 4; ++m) {
	v_pk_fma_f32 v[160:161], v[168:169], v[160:161], v[184:185]
	v_pk_fma_f32 v[160:161], v[156:157], v[172:173], v[160:161]
	v_pk_fma_f32 v[166:167], v[148:149], v[176:177], v[160:161]
	v_pk_fma_f32 v[160:161], v[156:157], v[168:169], v[184:185]
	v_pk_fma_f32 v[160:161], v[148:149], v[172:173], v[160:161]
	v_pk_fma_f32 v[164:165], v[152:153], v[176:177], v[160:161]
	v_pk_fma_f32 v[160:161], v[148:149], v[168:169], v[184:185]
	v_pk_fma_f32 v[160:161], v[152:153], v[172:173], v[160:161]
	v_pk_fma_f32 v[162:163], v[136:137], v[176:177], v[160:161]
	v_pk_fma_f32 v[160:161], v[152:153], v[168:169], v[184:185]
	v_pk_fma_f32 v[160:161], v[136:137], v[172:173], v[160:161]
	v_pk_fma_f32 v[160:161], v[176:177], v[204:205], v[160:161]
	v_mov_b32_dpp v204, v138 row_shr:1 row_mask:0xf bank_mask:0xf bound_ctrl:1
	v_mov_b32_dpp v205, v139 row_shr:1 row_mask:0xf bank_mask:0xf bound_ctrl:1
	v_mov_b32_dpp v208, v158 row_shl:1 row_mask:0xf bank_mask:0xf bound_ctrl:1
	v_mov_b32_dpp v209, v159 row_shl:1 row_mask:0xf bank_mask:0xf bound_ctrl:1
	v_pk_fma_f32 v[204:205], v[170:171], v[204:205], v[186:187]
	v_pk_fma_f32 v[204:205], v[158:159], v[174:175], v[204:205]
	v_pk_fma_f32 v[218:219], v[150:151], v[178:179], v[204:205]
	v_pk_fma_f32 v[204:205], v[158:159], v[170:171], v[186:187]
	v_pk_fma_f32 v[204:205], v[150:151], v[174:175], v[204:205]
	v_pk_fma_f32 v[212:213], v[154:155], v[178:179], v[204:205]
	v_pk_fma_f32 v[204:205], v[150:151], v[170:171], v[186:187]
	v_pk_fma_f32 v[204:205], v[154:155], v[174:175], v[204:205]
	v_pk_fma_f32 v[206:207], v[138:139], v[178:179], v[204:205]
	v_pk_fma_f32 v[204:205], v[154:155], v[170:171], v[186:187]
	v_pk_fma_f32 v[204:205], v[138:139], v[174:175], v[204:205]
	v_pk_fma_f32 v[204:205], v[178:179], v[208:209], v[204:205]
	v_mov_b32_dpp v208, v132 row_shr:1 row_mask:0xf bank_mask:0xf bound_ctrl:1
	v_mov_b32_dpp v209, v133 row_shr:1 row_mask:0xf bank_mask:0xf bound_ctrl:1
	v_mov_b32_dpp v210, v144 row_shl:1 row_mask:0xf bank_mask:0xf bound_ctrl:1
	v_mov_b32_dpp v211, v145 row_shl:1 row_mask:0xf bank_mask:0xf bound_ctrl:1
	v_pk_fma_f32 v[208:209], v[180:181], v[208:209], v[196:197]
	v_pk_fma_f32 v[208:209], v[144:145], v[188:189], v[208:209]
	v_pk_fma_f32 v[220:221], v[128:129], v[192:193], v[208:209]
	v_pk_fma_f32 v[208:209], v[144:145], v[180:181], v[196:197]
	v_pk_fma_f32 v[208:209], v[128:129], v[188:189], v[208:209]
	v_pk_fma_f32 v[222:223], v[140:141], v[192:193], v[208:209]
	v_pk_fma_f32 v[208:209], v[128:129], v[180:181], v[196:197]
	v_pk_fma_f32 v[208:209], v[140:141], v[188:189], v[208:209]
	v_pk_fma_f32 v[226:227], v[132:133], v[192:193], v[208:209]
	v_pk_fma_f32 v[208:209], v[140:141], v[180:181], v[196:197]
	v_pk_fma_f32 v[208:209], v[132:133], v[188:189], v[208:209]
	v_pk_fma_f32 v[210:211], v[192:193], v[210:211], v[208:209]
	v_mov_b32_dpp v208, v134 row_shr:1 row_mask:0xf bank_mask:0xf bound_ctrl:1
	v_mov_b32_dpp v209, v135 row_shr:1 row_mask:0xf bank_mask:0xf bound_ctrl:1
	v_mov_b32_dpp v228, v146 row_shl:1 row_mask:0xf bank_mask:0xf bound_ctrl:1
	v_mov_b32_dpp v229, v147 row_shl:1 row_mask:0xf bank_mask:0xf bound_ctrl:1
	v_pk_fma_f32 v[208:209], v[182:183], v[208:209], v[198:199]
	v_pk_fma_f32 v[208:209], v[146:147], v[190:191], v[208:209]
	v_pk_fma_f32 v[236:237], v[130:131], v[194:195], v[208:209]
	v_pk_fma_f32 v[208:209], v[146:147], v[182:183], v[198:199]
	v_pk_fma_f32 v[208:209], v[130:131], v[190:191], v[208:209]
	v_pk_fma_f32 v[238:239], v[142:143], v[194:195], v[208:209]
	v_pk_fma_f32 v[208:209], v[130:131], v[182:183], v[198:199]
	v_pk_fma_f32 v[208:209], v[142:143], v[190:191], v[208:209]
	v_pk_fma_f32 v[240:241], v[134:135], v[194:195], v[208:209]
	v_pk_fma_f32 v[208:209], v[142:143], v[182:183], v[198:199]
	v_pk_fma_f32 v[208:209], v[134:135], v[190:191], v[208:209]
	v_pk_fma_f32 v[208:209], v[194:195], v[228:229], v[208:209]
	v_pk_mul_f32 v[228:229], v[166:167], s[12:13] op_sel_hi:[1,0]
	v_pk_mul_f32 v[166:167], v[166:167], v[220:221]
	v_exp_f32_e32 v228, v228
	v_exp_f32_e32 v229, v229
	s_nop 0
	v_pk_add_f32 v[228:229], v[228:229], 1.0 op_sel_hi:[1,0]
	v_rcp_f32_e32 v220, v228
	v_rcp_f32_e32 v221, v229
	s_nop 0
	v_pk_mul_f32 v[166:167], v[166:167], v[220:221]
	v_pk_mul_f32 v[220:221], v[218:219], s[12:13] op_sel_hi:[1,0]
	v_pk_mul_f32 v[218:219], v[218:219], v[236:237]
	v_exp_f32_e32 v220, v220
	v_exp_f32_e32 v221, v221
	v_cvt_pk_bf16_f32 v166, v166, v167
	v_pk_add_f32 v[220:221], v[220:221], 1.0 op_sel_hi:[1,0]
	v_rcp_f32_e32 v220, v220
	v_rcp_f32_e32 v221, v221
	s_nop 0
	v_pk_mul_f32 v[218:219], v[218:219], v[220:221]
	v_cvt_pk_bf16_f32 v167, v218, v219
	v_pk_mul_f32 v[218:219], v[164:165], s[12:13] op_sel_hi:[1,0]
	v_pk_mul_f32 v[164:165], v[164:165], v[222:223]
	v_exp_f32_e32 v218, v218
	v_exp_f32_e32 v219, v219
	s_nop 0
	v_pk_add_f32 v[218:219], v[218:219], 1.0 op_sel_hi:[1,0]
	v_rcp_f32_e32 v218, v218
	v_rcp_f32_e32 v219, v219
	s_nop 0
	v_pk_mul_f32 v[164:165], v[164:165], v[218:219]
	v_pk_mul_f32 v[218:219], v[212:213], s[12:13] op_sel_hi:[1,0]
	v_pk_mul_f32 v[212:213], v[212:213], v[238:239]
	v_exp_f32_e32 v218, v218
	v_exp_f32_e32 v219, v219
	v_cvt_pk_bf16_f32 v164, v164, v165
	v_pk_add_f32 v[218:219], v[218:219], 1.0 op_sel_hi:[1,0]
	v_rcp_f32_e32 v218, v218
	v_rcp_f32_e32 v219, v219
	s_nop 0
	v_pk_mul_f32 v[212:213], v[212:213], v[218:219]
	v_cvt_pk_bf16_f32 v165, v212, v213
	v_pk_mul_f32 v[212:213], v[162:163], s[12:13] op_sel_hi:[1,0]
	v_pk_mul_f32 v[162:163], v[162:163], v[226:227]
	v_exp_f32_e32 v212, v212
	v_exp_f32_e32 v213, v213
	s_nop 0
	v_pk_add_f32 v[212:213], v[212:213], 1.0 op_sel_hi:[1,0]
	v_rcp_f32_e32 v212, v212
	v_rcp_f32_e32 v213, v213
	s_nop 0
;     __device__ __forceinline__ void conv4(const f32x4& a0, const f32x4& a1, const f32x4& a2, const f32x4& a3, const f32x4& w0, const f32x4& w1, const f32x4& w2, const f32x4& b, f32x2 (&h)[4][2]) const {
;     ...
;             asm volatile("s_nop 1\n\tv_mov_b32_dpp %0, %1 row_shr:1 row_mask:0xf bank_mask:0xf bound_ctrl:1" : "=&v"(u0) : "v"(a3[2 * p]));
;             asm volatile("s_nop 1\n\tv_mov_b32_dpp %0, %1 row_shr:1 row_mask:0xf bank_mask:0xf bound_ctrl:1" : "=&v"(u1) : "v"(a3[2 * p + 1]));
;             asm volatile("s_nop 1\n\tv_mov_b32_dpp %0, %1 row_shl:1 row_mask:0xf bank_mask:0xf bound_ctrl:1" : "=&v"(d0) : "v"(a0[2 * p]));
;             asm volatile("s_nop 1\n\tv_mov_b32_dpp %0, %1 row_shl:1 row_mask:0xf bank_mask:0xf bound_ctrl:1" : "=&v"(d1) : "v"(a0[2 * p + 1]));
;             const f32x2 UP = {u0, u1}, DN = {d0, d1};
;             const f32x2 A0 = {a0[2 * p], a0[2 * p + 1]}, A1 = {a1[2 * p], a1[2 * p + 1]}, A2 = {a2[2 * p], a2[2 * p + 1]}, A3 = {a3[2 * p], a3[2 * p + 1]};
;             const f32x2 W0 = {w0[2 * p], w0[2 * p + 1]}, W1 = {w1[2 * p], w1[2 * p + 1]}, W2 = {w2[2 * p], w2[2 * p + 1]}, B = {b[2 * p], b[2 * p + 1]};
;             h[0][p] = B + W0 * UP + W1 * A0 + W2 * A1;
;             h[1][p] = B + W0 * A0 + W1 * A1 + W2 * A2;
;     __device__ __forceinline__ void operator()(f32x4 (&acc)[2][2][4][2], const Unit& u, int wr, int wc, int lane) const {
;     ...
;                 for (int m = 0; m < 4; ++m) {
;                     u32x2 w; w.x = silu_pk(hg[m][0], hv[m][0]); w.y = silu_pk(hg[m][1], hv[m][1]);
;                     if (n == 0) keep[ai][m] = w;
;                     else { u32x4 w4; w4.x = keep[ai][m].x; w4.y = keep[ai][m].y; w4.z = w.x; w4.w = w.y; gst<u32x4>(gu, ((unsigned)(4 * fr + m) * DFF + 8u * fq) * 2u, w4); }
;                 }
;                 if (fr == 0 || fr == 15) {
;                     const int mb = fr == 0 ? 0 : 2;
; #pragma unroll
;                     for (int e = 0; e < 2; ++e) { const unsigned eo = ((unsigned)(mb + e) * NUP + 8u * fq + 4u * n) * 2u;
;                         const f32x4 eg = fr == 0 ? acc[ai][0][e][n] : acc[ai][0][2 + e][n], ev = fr == 0 ? acc[ai][1][e][n] : acc[ai][1][2 + e][n];
;                         gst<u32x2>(eu, eo, (u32x2){cvt_pk_f16(eg[0], eg[1]), cvt_pk_f16(eg[2], eg[3])}); gst<u32x2>(eu + DFF, eo, (u32x2){cvt_pk_f16(ev[0], ev[1]), cvt_pk_f16(ev[2], ev[3])}); }
;                 }
	v_pk_mul_f32 v[162:163], v[162:163], v[212:213]
	v_pk_mul_f32 v[212:213], v[206:207], s[12:13] op_sel_hi:[1,0]
	v_pk_mul_f32 v[206:207], v[206:207], v[240:241]
	v_exp_f32_e32 v212, v212
	v_exp_f32_e32 v213, v213
	v_cvt_pk_bf16_f32 v162, v162, v163
	v_pk_add_f32 v[212:213], v[212:213], 1.0 op_sel_hi:[1,0]
	v_rcp_f32_e32 v212, v212
	v_rcp_f32_e32 v213, v213
	s_nop 0
	v_pk_mul_f32 v[206:207], v[206:207], v[212:213]
	v_cvt_pk_bf16_f32 v163, v206, v207
	v_pk_mul_f32 v[206:207], v[160:161], s[12:13] op_sel_hi:[1,0]
	v_pk_mul_f32 v[160:161], v[160:161], v[210:211]
	v_exp_f32_e32 v206, v206
	v_exp_f32_e32 v207, v207
	s_nop 0
	v_pk_add_f32 v[206:207], v[206:207], 1.0 op_sel_hi:[1,0]
	v_rcp_f32_e32 v206, v206
	v_rcp_f32_e32 v207, v207
	s_nop 0
	v_pk_mul_f32 v[160:161], v[160:161], v[206:207]
	v_pk_mul_f32 v[206:207], v[204:205], s[12:13] op_sel_hi:[1,0]
	v_pk_mul_f32 v[204:205], v[204:205], v[208:209]
	v_exp_f32_e32 v206, v206
	v_exp_f32_e32 v207, v207
	v_cvt_pk_bf16_f32 v160, v160, v161
	v_pk_add_f32 v[206:207], v[206:207], 1.0 op_sel_hi:[1,0]
	v_rcp_f32_e32 v206, v206
	v_rcp_f32_e32 v207, v207
	s_nop 0
	v_pk_mul_f32 v[204:205], v[204:205], v[206:207]
	v_cvt_pk_bf16_f32 v161, v204, v205
	v_and_b32_e32 v204, 15, v230
	v_cmp_eq_u32_e32 vcc, 0, v204
	v_cmp_gt_i32_e64 s[42:43], 15, v204
	s_and_saveexec_b64 s[52:53], s[42:43]
	v_cmp_eq_u32_e64 s[42:43], 0, v204
	s_orn2_b64 s[44:45], s[42:43], exec
	s_or_b64 exec, exec, s[52:53]
	s_lshl_b32 s17, s60, 2
	s_add_i32 s17, s17, s18
	v_and_b32_e32 v205, -16, v230
	v_cndmask_b32_e64 v206, 2, 0, vcc
	s_mul_hi_i32 s61, s17, 0xb000
	s_mul_i32 s62, s17, 0xb000
	v_mad_u32_u24 v207, v206, s89, v205
	s_and_saveexec_b64 s[42:43], s[44:45]
	s_cbranch_execz .LBB0_138
	s_add_u32 s21, s34, s62
	s_addc_u32 s52, s35, s61
	s_lshl_b64 s[44:45], s[48:49], 1
	s_add_u32 s44, s21, s44
	s_addc_u32 s45, s52, s45
	s_add_u32 s52, s44, 0x1600
	v_cndmask_b32_e32 v152, v152, v156, vcc
	v_cndmask_b32_e32 v153, v153, v157, vcc
	v_cndmask_b32_e32 v144, v140, v144, vcc
	v_cvt_pk_f16_f32 v140, v152, v153
	s_addc_u32 s53, s45, 0
	v_cndmask_b32_e32 v154, v154, v158, vcc
	v_cndmask_b32_e32 v155, v155, v159, vcc
	v_cndmask_b32_e32 v145, v141, v145, vcc
	v_cvt_pk_f16_f32 v141, v154, v155
	global_store_dwordx2 v207, v[140:141], s[44:45]
	v_cvt_pk_f16_f32 v140, v144, v145
	v_cndmask_b32_e32 v142, v142, v146, vcc
	v_cndmask_b32_e32 v143, v143, v147, vcc
	v_cvt_pk_f16_f32 v141, v142, v143
	global_store_dwordx2 v207, v[140:141], s[52:53]
	v_add_u32_e32 v140, 0x2c00, v207
	v_cndmask_b32_e32 v138, v138, v150, vcc
	v_cndmask_b32_e32 v139, v139, v151, vcc
	v_cndmask_b32_e32 v136, v136, v148, vcc
	v_cndmask_b32_e32 v137, v137, v149, vcc
	v_cndmask_b32_e32 v132, v132, v128, vcc
	v_cndmask_b32_e32 v133, v133, v129, vcc
	v_cvt_pk_f16_f32 v128, v136, v137
	v_cvt_pk_f16_f32 v129, v138, v139
	v_cndmask_b32_e32 v130, v134, v130, vcc
	v_cndmask_b32_e32 v131, v135, v131, vcc
	global_store_dwordx2 v140, v[128:129], s[44:45]
	v_cvt_pk_f16_f32 v128, v132, v133
	v_cvt_pk_f16_f32 v129, v130, v131
	global_store_dwordx2 v140, v[128:129], s[52:53]
.LBB0_138:
	s_or_b64 exec, exec, s[42:43]
	v_mov_b32_dpp v128, v68 row_shr:1 row_mask:0xf bank_mask:0xf bound_ctrl:1
	v_mov_b32_dpp v129, v69 row_shr:1 row_mask:0xf bank_mask:0xf bound_ctrl:1
	v_pk_fma_f32 v[138:139], v[102:103], v[170:171], v[186:187]
	v_pk_fma_f32 v[128:129], v[168:169], v[128:129], v[184:185]
	v_pk_fma_f32 v[138:139], v[66:67], v[174:175], v[138:139]
	v_pk_fma_f32 v[128:129], v[100:101], v[172:173], v[128:129]
	v_pk_fma_f32 v[146:147], v[94:95], v[178:179], v[138:139]
	v_pk_fma_f32 v[134:135], v[64:65], v[176:177], v[128:129]
	v_pk_fma_f32 v[128:129], v[100:101], v[168:169], v[184:185]
	v_pk_fma_f32 v[138:139], v[66:67], v[170:171], v[186:187]
	v_pk_fma_f32 v[128:129], v[64:65], v[172:173], v[128:129]
	v_pk_fma_f32 v[138:139], v[94:95], v[174:175], v[138:139]
	v_pk_fma_f32 v[144:145], v[92:93], v[176:177], v[128:129]
	v_pk_fma_f32 v[128:129], v[64:65], v[168:169], v[184:185]
	v_mov_b32_dpp v132, v100 row_shl:1 row_mask:0xf bank_mask:0xf bound_ctrl:1
	v_mov_b32_dpp v133, v101 row_shl:1 row_mask:0xf bank_mask:0xf bound_ctrl:1
	v_pk_fma_f32 v[142:143], v[70:71], v[178:179], v[138:139]
	v_pk_fma_f32 v[128:129], v[92:93], v[172:173], v[128:129]
	v_pk_fma_f32 v[138:139], v[94:95], v[170:171], v[186:187]
	v_pk_fma_f32 v[130:131], v[68:69], v[176:177], v[128:129]
	v_pk_fma_f32 v[128:129], v[92:93], v[168:169], v[184:185]
	v_pk_fma_f32 v[138:139], v[70:71], v[174:175], v[138:139]
	v_pk_fma_f32 v[128:129], v[68:69], v[172:173], v[128:129]
	v_cmp_gt_i32_e64 s[42:43], 15, v204
	v_pk_fma_f32 v[128:129], v[176:177], v[132:133], v[128:129]
	v_mov_b32_dpp v132, v70 row_shr:1 row_mask:0xf bank_mask:0xf bound_ctrl:1
	v_mov_b32_dpp v133, v71 row_shr:1 row_mask:0xf bank_mask:0xf bound_ctrl:1
	v_mov_b32_dpp v136, v102 row_shl:1 row_mask:0xf bank_mask:0xf bound_ctrl:1
	v_mov_b32_dpp v137, v103 row_shl:1 row_mask:0xf bank_mask:0xf bound_ctrl:1
	s_mov_b64 s[44:45], -1
	v_pk_fma_f32 v[136:137], v[178:179], v[136:137], v[138:139]
	v_mov_b32_dpp v138, v76 row_shr:1 row_mask:0xf bank_mask:0xf bound_ctrl:1
	v_mov_b32_dpp v139, v77 row_shr:1 row_mask:0xf bank_mask:0xf bound_ctrl:1
	v_mov_b32_dpp v140, v88 row_shl:1 row_mask:0xf bank_mask:0xf bound_ctrl:1
;     __device__ __forceinline__ void conv4(const f32x4& a0, const f32x4& a1, const f32x4& a2, const f32x4& a3, const f32x4& w0, const f32x4& w1, const f32x4& w2, const f32x4& b, f32x2 (&h)[4][2]) const {
;     ...
;             asm volatile("s_nop 1\n\tv_mov_b32_dpp %0, %1 row_shr:1 row_mask:0xf bank_mask:0xf bound_ctrl:1" : "=&v"(u0) : "v"(a3[2 * p]));
;             asm volatile("s_nop 1\n\tv_mov_b32_dpp %0, %1 row_shr:1 row_mask:0xf bank_mask:0xf bound_ctrl:1" : "=&v"(u1) : "v"(a3[2 * p + 1]));
;             asm volatile("s_nop 1\n\tv_mov_b32_dpp %0, %1 row_shl:1 row_mask:0xf bank_mask:0xf bound_ctrl:1" : "=&v"(d0) : "v"(a0[2 * p]));
;             asm volatile("s_nop 1\n\tv_mov_b32_dpp %0, %1 row_shl:1 row_mask:0xf bank_mask:0xf bound_ctrl:1" : "=&v"(d1) : "v"(a0[2 * p + 1]));
;             const f32x2 UP = {u0, u1}, DN = {d0, d1};
;             const f32x2 A0 = {a0[2 * p], a0[2 * p + 1]}, A1 = {a1[2 * p], a1[2 * p + 1]}, A2 = {a2[2 * p], a2[2 * p + 1]}, A3 = {a3[2 * p], a3[2 * p + 1]};
;             const f32x2 W0 = {w0[2 * p], w0[2 * p + 1]}, W1 = {w1[2 * p], w1[2 * p + 1]}, W2 = {w2[2 * p], w2[2 * p + 1]}, B = {b[2 * p], b[2 * p + 1]};
;             h[0][p] = B + W0 * UP + W1 * A0 + W2 * A1;
;             h[1][p] = B + W0 * A0 + W1 * A1 + W2 * A2;
;             h[2][p] = B + W0 * A1 + W1 * A2 + W2 * A3;
;             h[3][p] = B + W0 * A2 + W1 * A3 + W2 * DN;
;         }
;     }
;     static __device__ __forceinline__ unsigned silu_pk(const f32x2 g, const f32x2 v) {
;         const f32x2 t = g * -1.4426950408889634f;
;         const f32x2 d = (f32x2){__builtin_amdgcn_exp2f(t.x), __builtin_amdgcn_exp2f(t.y)} + 1.0f;
;         const f32x2 o = g * v * (f32x2){__builtin_amdgcn_rcpf(d.x), __builtin_amdgcn_rcpf(d.y)};
;         return cvt_pk_bf16(o.x, o.y);
;     }
;     __device__ __forceinline__ void operator()(f32x4 (&acc)[2][2][4][2], const Unit& u, int wr, int wc, int lane) const {
;     ...
;                 for (int m = 0; m < 4; ++m) {
;                     u32x2 w; w.x = silu_pk(hg[m][0], hv[m][0]); w.y = silu_pk(hg[m][1], hv[m][1]);
;                     if (n == 0) keep[ai][m] = w;
;                     else { u32x4 w4; w4.x = keep[ai][m].x; w4.y = keep[ai][m].y; w4.z = w.x; w4.w = w.y; gst<u32x4>(gu, ((unsigned)(4 * fr + m) * DFF + 8u * fq) * 2u, w4); }
;                 }
;                 if (fr == 0 || fr == 15) {
	v_mov_b32_dpp v141, v89 row_shl:1 row_mask:0xf bank_mask:0xf bound_ctrl:1
	v_pk_fma_f32 v[132:133], v[170:171], v[132:133], v[186:187]
	v_pk_fma_f32 v[138:139], v[180:181], v[138:139], v[196:197]
	v_pk_fma_f32 v[132:133], v[102:103], v[174:175], v[132:133]
	v_pk_fma_f32 v[138:139], v[88:89], v[188:189], v[138:139]
	v_pk_fma_f32 v[132:133], v[66:67], v[178:179], v[132:133]
	v_pk_fma_f32 v[148:149], v[72:73], v[192:193], v[138:139]
	v_pk_fma_f32 v[138:139], v[88:89], v[180:181], v[196:197]
	v_pk_fma_f32 v[138:139], v[72:73], v[188:189], v[138:139]
	v_pk_fma_f32 v[150:151], v[84:85], v[192:193], v[138:139]
	v_pk_fma_f32 v[138:139], v[72:73], v[180:181], v[196:197]
	v_pk_fma_f32 v[138:139], v[84:85], v[188:189], v[138:139]
	v_pk_fma_f32 v[152:153], v[76:77], v[192:193], v[138:139]
	v_pk_fma_f32 v[138:139], v[84:85], v[180:181], v[196:197]
	v_pk_fma_f32 v[138:139], v[76:77], v[188:189], v[138:139]
	v_pk_fma_f32 v[140:141], v[192:193], v[140:141], v[138:139]
	v_mov_b32_dpp v138, v78 row_shr:1 row_mask:0xf bank_mask:0xf bound_ctrl:1
	v_mov_b32_dpp v139, v79 row_shr:1 row_mask:0xf bank_mask:0xf bound_ctrl:1
	v_mov_b32_dpp v154, v90 row_shl:1 row_mask:0xf bank_mask:0xf bound_ctrl:1
	v_mov_b32_dpp v155, v91 row_shl:1 row_mask:0xf bank_mask:0xf bound_ctrl:1
	v_pk_fma_f32 v[138:139], v[182:183], v[138:139], v[198:199]
	v_pk_fma_f32 v[138:139], v[90:91], v[190:191], v[138:139]
	v_pk_fma_f32 v[156:157], v[74:75], v[194:195], v[138:139]
	v_pk_fma_f32 v[138:139], v[90:91], v[182:183], v[198:199]
	v_pk_fma_f32 v[138:139], v[74:75], v[190:191], v[138:139]
	v_pk_fma_f32 v[158:159], v[86:87], v[194:195], v[138:139]
	v_pk_fma_f32 v[138:139], v[74:75], v[182:183], v[198:199]
	v_pk_fma_f32 v[138:139], v[86:87], v[190:191], v[138:139]
	v_pk_fma_f32 v[168:169], v[78:79], v[194:195], v[138:139]
	v_pk_fma_f32 v[138:139], v[86:87], v[182:183], v[198:199]
	v_pk_fma_f32 v[138:139], v[78:79], v[190:191], v[138:139]
	v_pk_fma_f32 v[138:139], v[194:195], v[154:155], v[138:139]
	v_pk_mul_f32 v[154:155], v[134:135], s[12:13] op_sel_hi:[1,0]
	v_pk_mul_f32 v[134:135], v[134:135], v[148:149]
	v_exp_f32_e32 v154, v154
	v_exp_f32_e32 v155, v155
	s_nop 0
	v_pk_add_f32 v[154:155], v[154:155], 1.0 op_sel_hi:[1,0]
	v_rcp_f32_e32 v148, v154
	v_rcp_f32_e32 v149, v155
	s_nop 0
	v_pk_mul_f32 v[134:135], v[134:135], v[148:149]
	v_pk_mul_f32 v[148:149], v[132:133], s[12:13] op_sel_hi:[1,0]
	v_pk_mul_f32 v[132:133], v[132:133], v[156:157]
	v_exp_f32_e32 v148, v148
	v_exp_f32_e32 v149, v149
	v_cvt_pk_bf16_f32 v134, v134, v135
	v_pk_add_f32 v[148:149], v[148:149], 1.0 op_sel_hi:[1,0]
	v_rcp_f32_e32 v148, v148
	v_rcp_f32_e32 v149, v149
	s_nop 0
	v_pk_mul_f32 v[132:133], v[132:133], v[148:149]
	v_cvt_pk_bf16_f32 v135, v132, v133
	v_pk_mul_f32 v[132:133], v[144:145], s[12:13] op_sel_hi:[1,0]
	v_pk_mul_f32 v[144:145], v[144:145], v[150:151]
	v_exp_f32_e32 v132, v132
	v_exp_f32_e32 v133, v133
	s_nop 0
	v_pk_add_f32 v[132:133], v[132:133], 1.0 op_sel_hi:[1,0]
	v_rcp_f32_e32 v132, v132
	v_rcp_f32_e32 v133, v133
	s_nop 0
	v_pk_mul_f32 v[132:133], v[144:145], v[132:133]
	v_pk_mul_f32 v[144:145], v[146:147], s[12:13] op_sel_hi:[1,0]
	v_pk_mul_f32 v[146:147], v[146:147], v[158:159]
	v_exp_f32_e32 v144, v144
	v_exp_f32_e32 v145, v145
	v_cvt_pk_bf16_f32 v132, v132, v133
	v_pk_add_f32 v[144:145], v[144:145], 1.0 op_sel_hi:[1,0]
	v_rcp_f32_e32 v144, v144
	v_rcp_f32_e32 v145, v145
	s_nop 0
	v_pk_mul_f32 v[144:145], v[146:147], v[144:145]
	v_cvt_pk_bf16_f32 v133, v144, v145
	v_pk_mul_f32 v[144:145], v[130:131], s[12:13] op_sel_hi:[1,0]
	v_pk_mul_f32 v[130:131], v[130:131], v[152:153]
	v_exp_f32_e32 v144, v144
	v_exp_f32_e32 v145, v145
	s_nop 0
	v_pk_add_f32 v[144:145], v[144:145], 1.0 op_sel_hi:[1,0]
	v_rcp_f32_e32 v144, v144
	v_rcp_f32_e32 v145, v145
	s_nop 0
	v_pk_mul_f32 v[130:131], v[130:131], v[144:145]
	v_pk_mul_f32 v[144:145], v[142:143], s[12:13] op_sel_hi:[1,0]
	v_pk_mul_f32 v[142:143], v[142:143], v[168:169]
	v_exp_f32_e32 v144, v144
	v_exp_f32_e32 v145, v145
	v_cvt_pk_bf16_f32 v130, v130, v131
	v_pk_add_f32 v[144:145], v[144:145], 1.0 op_sel_hi:[1,0]
	v_rcp_f32_e32 v144, v144
	v_rcp_f32_e32 v145, v145
	s_nop 0
	v_pk_mul_f32 v[142:143], v[142:143], v[144:145]
	v_cvt_pk_bf16_f32 v131, v142, v143
	v_pk_mul_f32 v[142:143], v[128:129], s[12:13] op_sel_hi:[1,0]
	v_pk_mul_f32 v[128:129], v[128:129], v[140:141]
	v_exp_f32_e32 v142, v142
	v_exp_f32_e32 v143, v143
	s_nop 0
	v_pk_add_f32 v[142:143], v[142:143], 1.0 op_sel_hi:[1,0]
	v_rcp_f32_e32 v140, v142
	v_rcp_f32_e32 v141, v143
	s_nop 0
	v_pk_mul_f32 v[128:129], v[128:129], v[140:141]
	v_pk_mul_f32 v[140:141], v[136:137], s[12:13] op_sel_hi:[1,0]
	v_pk_mul_f32 v[136:137], v[136:137], v[138:139]
	v_exp_f32_e32 v140, v140
	v_exp_f32_e32 v141, v141
	v_cvt_pk_bf16_f32 v128, v128, v129
	v_pk_add_f32 v[140:141], v[140:141], 1.0 op_sel_hi:[1,0]
	v_rcp_f32_e32 v138, v140
	v_rcp_f32_e32 v139, v141
	s_nop 0
	v_pk_mul_f32 v[136:137], v[136:137], v[138:139]
	v_cvt_pk_bf16_f32 v129, v136, v137
	s_and_saveexec_b64 s[52:53], s[42:43]
	s_cbranch_execz .LBB0_142
	v_cmp_eq_u32_e64 s[42:43], 0, v204
	v_cmp_ne_u32_e64 s[44:45], 0, v204
	s_and_saveexec_b64 s[56:57], s[44:45]
	v_add_u32_e32 v136, 0x2c00, v205
	s_or_b64 exec, exec, s[56:57]
	s_orn2_b64 s[44:45], s[42:43], exec

;     __device__ __forceinline__ void conv4(const f32x4& a0, const f32x4& a1, const f32x4& a2, const f32x4& a3, const f32x4& w0, const f32x4& w1, const f32x4& w2, const f32x4& b, f32x2 (&h)[4][2]) const {
;     ...
;             asm volatile("s_nop 1\n\tv_mov_b32_dpp %0, %1 row_shr:1 row_mask:0xf bank_mask:0xf bound_ctrl:1" : "=&v"(u0) : "v"(a3[2 * p]));
;             asm volatile("s_nop 1\n\tv_mov_b32_dpp %0, %1 row_shr:1 row_mask:0xf bank_mask:0xf bound_ctrl:1" : "=&v"(u1) : "v"(a3[2 * p + 1]));
;             asm volatile("s_nop 1\n\tv_mov_b32_dpp %0, %1 row_shl:1 row_mask:0xf bank_mask:0xf bound_ctrl:1" : "=&v"(d0) : "v"(a0[2 * p]));
;             asm volatile("s_nop 1\n\tv_mov_b32_dpp %0, %1 row_shl:1 row_mask:0xf bank_mask:0xf bound_ctrl:1" : "=&v"(d1) : "v"(a0[2 * p + 1]));
;             const f32x2 UP = {u0, u1}, DN = {d0, d1};
;             const f32x2 A0 = {a0[2 * p], a0[2 * p + 1]}, A1 = {a1[2 * p], a1[2 * p + 1]}, A2 = {a2[2 * p], a2[2 * p + 1]}, A3 = {a3[2 * p], a3[2 * p + 1]};
;             const f32x2 W0 = {w0[2 * p], w0[2 * p + 1]}, W1 = {w1[2 * p], w1[2 * p + 1]}, W2 = {w2[2 * p], w2[2 * p + 1]}, B = {b[2 * p], b[2 * p + 1]};
;             h[0][p] = B + W0 * UP + W1 * A0 + W2 * A1;
;             h[1][p] = B + W0 * A0 + W1 * A1 + W2 * A2;
;             h[2][p] = B + W0 * A1 + W1 * A2 + W2 * A3;
;             h[3][p] = B + W0 * A2 + W1 * A3 + W2 * DN;
;         }
;     }
;     static __device__ __forceinline__ unsigned silu_pk(const f32x2 g, const f32x2 v) {
;         const f32x2 t = g * -1.4426950408889634f;
;         const f32x2 d = (f32x2){__builtin_amdgcn_exp2f(t.x), __builtin_amdgcn_exp2f(t.y)} + 1.0f;
;         const f32x2 o = g * v * (f32x2){__builtin_amdgcn_rcpf(d.x), __builtin_amdgcn_rcpf(d.y)};
;         return cvt_pk_bf16(o.x, o.y);
;     }
;     __device__ __forceinline__ void operator()(f32x4 (&acc)[2][2][4][2], const Unit& u, int wr, int wc, int lane) const {
;     ...
;                 for (int m = 0; m < 4; ++m) {
;                     u32x2 w; w.x = silu_pk(hg[m][0], hv[m][0]); w.y = silu_pk(hg[m][1], hv[m][1]);
;                     if (n == 0) keep[ai][m] = w;
;                     else { u32x4 w4; w4.x = keep[ai][m].x; w4.y = keep[ai][m].y; w4.z = w.x; w4.w = w.y; gst<u32x4>(gu, ((unsigned)(4 * fr + m) * DFF + 8u * fq) * 2u, w4); }
.LBB0_144:
	s_or_b64 exec, exec, s[42:43]
	v_pk_fma_f32 v[68:69], v[60:61], v[80:81], v[108:109]
	v_mov_b32_dpp v64, v48 row_shr:1 row_mask:0xf bank_mask:0xf bound_ctrl:1
	v_mov_b32_dpp v65, v49 row_shr:1 row_mask:0xf bank_mask:0xf bound_ctrl:1
	v_mov_b32_dpp v66, v60 row_shl:1 row_mask:0xf bank_mask:0xf bound_ctrl:1
	v_mov_b32_dpp v67, v61 row_shl:1 row_mask:0xf bank_mask:0xf bound_ctrl:1
	s_lshl_b32 s56, s60, 8
	v_pk_fma_f32 v[68:69], v[52:53], v[96:97], v[68:69]
	v_pk_fma_f32 v[64:65], v[80:81], v[64:65], v[108:109]
	v_pk_fma_f32 v[86:87], v[56:57], v[104:105], v[68:69]
	v_pk_fma_f32 v[68:69], v[52:53], v[80:81], v[108:109]
	v_pk_fma_f32 v[64:65], v[60:61], v[96:97], v[64:65]
	v_pk_fma_f32 v[68:69], v[56:57], v[96:97], v[68:69]
	v_pk_fma_f32 v[64:65], v[52:53], v[104:105], v[64:65]
	v_pk_fma_f32 v[76:77], v[48:49], v[104:105], v[68:69]
	v_pk_fma_f32 v[68:69], v[56:57], v[80:81], v[108:109]
	s_add_i32 s56, s56, s36
	v_pk_fma_f32 v[68:69], v[48:49], v[96:97], v[68:69]
	s_mul_i32 s43, s56, 0x1600
	v_pk_fma_f32 v[70:71], v[104:105], v[66:67], v[68:69]
	v_mov_b32_dpp v66, v50 row_shr:1 row_mask:0xf bank_mask:0xf bound_ctrl:1
	v_mov_b32_dpp v67, v51 row_shr:1 row_mask:0xf bank_mask:0xf bound_ctrl:1
	v_mov_b32_dpp v72, v62 row_shl:1 row_mask:0xf bank_mask:0xf bound_ctrl:1
	v_mov_b32_dpp v73, v63 row_shl:1 row_mask:0xf bank_mask:0xf bound_ctrl:1
	s_mul_hi_i32 s42, s56, 0x1600
	v_pk_fma_f32 v[66:67], v[82:83], v[66:67], v[110:111]
	s_add_u32 s43, s31, s43
	v_pk_fma_f32 v[66:67], v[62:63], v[98:99], v[66:67]
	s_addc_u32 s52, s33, s42
	v_pk_fma_f32 v[88:89], v[54:55], v[106:107], v[66:67]
	v_pk_fma_f32 v[66:67], v[62:63], v[82:83], v[110:111]
	s_lshl_b64 s[44:45], s[48:49], 1
	v_pk_fma_f32 v[66:67], v[54:55], v[98:99], v[66:67]
	s_add_u32 s42, s43, s44
	v_pk_fma_f32 v[90:91], v[58:59], v[106:107], v[66:67]
	v_pk_fma_f32 v[66:67], v[54:55], v[82:83], v[110:111]
	s_addc_u32 s43, s52, s45
	v_pk_fma_f32 v[66:67], v[58:59], v[98:99], v[66:67]
	v_mad_u32_u24 v216, v204, s92, v205
	v_pk_fma_f32 v[68:69], v[50:51], v[106:107], v[66:67]
	v_pk_fma_f32 v[66:67], v[58:59], v[82:83], v[110:111]
	s_mov_b64 s[48:49], -1
	v_pk_fma_f32 v[66:67], v[50:51], v[98:99], v[66:67]
	v_pk_fma_f32 v[66:67], v[106:107], v[72:73], v[66:67]
	v_mov_b32_dpp v72, v40 row_shr:1 row_mask:0xf bank_mask:0xf bound_ctrl:1
	v_mov_b32_dpp v73, v41 row_shr:1 row_mask:0xf bank_mask:0xf bound_ctrl:1
	v_mov_b32_dpp v74, v36 row_shl:1 row_mask:0xf bank_mask:0xf bound_ctrl:1
	v_mov_b32_dpp v75, v37 row_shl:1 row_mask:0xf bank_mask:0xf bound_ctrl:1
	v_pk_fma_f32 v[72:73], v[112:113], v[72:73], v[124:125]
	v_pk_fma_f32 v[72:73], v[36:37], v[116:117], v[72:73]
	v_pk_fma_f32 v[92:93], v[32:33], v[120:121], v[72:73]
	v_pk_fma_f32 v[72:73], v[36:37], v[112:113], v[124:125]
	v_pk_fma_f32 v[72:73], v[32:33], v[116:117], v[72:73]
	v_pk_fma_f32 v[94:95], v[44:45], v[120:121], v[72:73]
	v_pk_fma_f32 v[72:73], v[32:33], v[112:113], v[124:125]
	v_pk_fma_f32 v[72:73], v[44:45], v[116:117], v[72:73]
	v_pk_fma_f32 v[84:85], v[40:41], v[120:121], v[72:73]
	v_pk_fma_f32 v[72:73], v[44:45], v[112:113], v[124:125]
	v_pk_fma_f32 v[72:73], v[40:41], v[116:117], v[72:73]
	v_pk_fma_f32 v[74:75], v[120:121], v[74:75], v[72:73]
	v_mov_b32_dpp v72, v42 row_shr:1 row_mask:0xf bank_mask:0xf bound_ctrl:1
	v_mov_b32_dpp v73, v43 row_shr:1 row_mask:0xf bank_mask:0xf bound_ctrl:1
	v_mov_b32_dpp v100, v38 row_shl:1 row_mask:0xf bank_mask:0xf bound_ctrl:1
	v_mov_b32_dpp v101, v39 row_shl:1 row_mask:0xf bank_mask:0xf bound_ctrl:1
	v_pk_fma_f32 v[72:73], v[114:115], v[72:73], v[126:127]
	v_pk_fma_f32 v[72:73], v[38:39], v[118:119], v[72:73]
	v_pk_fma_f32 v[102:103], v[34:35], v[122:123], v[72:73]
	v_pk_fma_f32 v[72:73], v[38:39], v[114:115], v[126:127]
	v_pk_fma_f32 v[72:73], v[34:35], v[118:119], v[72:73]
	v_pk_fma_f32 v[138:139], v[46:47], v[122:123], v[72:73]
	v_pk_fma_f32 v[72:73], v[34:35], v[114:115], v[126:127]
	v_pk_fma_f32 v[72:73], v[46:47], v[118:119], v[72:73]
	v_pk_fma_f32 v[78:79], v[42:43], v[122:123], v[72:73]
	v_pk_fma_f32 v[72:73], v[46:47], v[114:115], v[126:127]
	v_pk_fma_f32 v[72:73], v[42:43], v[118:119], v[72:73]
	v_pk_fma_f32 v[72:73], v[122:123], v[100:101], v[72:73]
	v_pk_mul_f32 v[100:101], v[64:65], s[12:13] op_sel_hi:[1,0]
	v_pk_mul_f32 v[64:65], v[64:65], v[92:93]
	v_exp_f32_e32 v100, v100
	v_exp_f32_e32 v101, v101
	s_nop 0
	v_pk_add_f32 v[100:101], v[100:101], 1.0 op_sel_hi:[1,0]
	v_rcp_f32_e32 v92, v100
	v_rcp_f32_e32 v93, v101
	s_nop 0
	v_pk_mul_f32 v[64:65], v[64:65], v[92:93]
	v_cvt_pk_bf16_f32 v168, v64, v65
	v_pk_mul_f32 v[64:65], v[88:89], s[12:13] op_sel_hi:[1,0]
	v_pk_mul_f32 v[88:89], v[88:89], v[102:103]
	v_exp_f32_e32 v64, v64
	v_exp_f32_e32 v65, v65
	s_nop 0
	v_pk_add_f32 v[64:65], v[64:65], 1.0 op_sel_hi:[1,0]
	v_rcp_f32_e32 v64, v64
	v_rcp_f32_e32 v65, v65
	s_nop 0
	v_pk_mul_f32 v[64:65], v[88:89], v[64:65]
	v_cvt_pk_bf16_f32 v169, v64, v65
	v_pk_mul_f32 v[64:65], v[86:87], s[12:13] op_sel_hi:[1,0]
	v_pk_mul_f32 v[86:87], v[86:87], v[94:95]
	v_exp_f32_e32 v64, v64
	v_exp_f32_e32 v65, v65
	global_store_dwordx4 v216, v[166:169], s[42:43]
	v_pk_add_f32 v[64:65], v[64:65], 1.0 op_sel_hi:[1,0]
	v_rcp_f32_e32 v64, v64
	v_rcp_f32_e32 v65, v65
	s_nop 0
	v_pk_mul_f32 v[64:65], v[86:87], v[64:65]
	v_cvt_pk_bf16_f32 v166, v64, v65
	v_pk_mul_f32 v[64:65], v[90:91], s[12:13] op_sel_hi:[1,0]
	v_pk_mul_f32 v[86:87], v[90:91], v[138:139]
	v_exp_f32_e32 v64, v64
	v_exp_f32_e32 v65, v65
	s_nop 0
	v_pk_add_f32 v[64:65], v[64:65], 1.0 op_sel_hi:[1,0]
	v_rcp_f32_e32 v64, v64
	v_rcp_f32_e32 v65, v65
	s_nop 0
	v_pk_mul_f32 v[64:65], v[86:87], v[64:65]
	v_pk_mul_f32 v[86:87], v[76:77], s[12:13] op_sel_hi:[1,0]
;     __device__ __forceinline__ void conv4(const f32x4& a0, const f32x4& a1, const f32x4& a2, const f32x4& a3, const f32x4& w0, const f32x4& w1, const f32x4& w2, const f32x4& b, f32x2 (&h)[4][2]) const {
;     ...
;             asm volatile("s_nop 1\n\tv_mov_b32_dpp %0, %1 row_shr:1 row_mask:0xf bank_mask:0xf bound_ctrl:1" : "=&v"(u0) : "v"(a3[2 * p]));
;             asm volatile("s_nop 1\n\tv_mov_b32_dpp %0, %1 row_shr:1 row_mask:0xf bank_mask:0xf bound_ctrl:1" : "=&v"(u1) : "v"(a3[2 * p + 1]));
;             asm volatile("s_nop 1\n\tv_mov_b32_dpp %0, %1 row_shl:1 row_mask:0xf bank_mask:0xf bound_ctrl:1" : "=&v"(d0) : "v"(a0[2 * p]));
;             asm volatile("s_nop 1\n\tv_mov_b32_dpp %0, %1 row_shl:1 row_mask:0xf bank_mask:0xf bound_ctrl:1" : "=&v"(d1) : "v"(a0[2 * p + 1]));
;             const f32x2 UP = {u0, u1}, DN = {d0, d1};
;             const f32x2 A0 = {a0[2 * p], a0[2 * p + 1]}, A1 = {a1[2 * p], a1[2 * p + 1]}, A2 = {a2[2 * p], a2[2 * p + 1]}, A3 = {a3[2 * p], a3[2 * p + 1]};
;             const f32x2 W0 = {w0[2 * p], w0[2 * p + 1]}, W1 = {w1[2 * p], w1[2 * p + 1]}, W2 = {w2[2 * p], w2[2 * p + 1]}, B = {b[2 * p], b[2 * p + 1]};
;             h[0][p] = B + W0 * UP + W1 * A0 + W2 * A1;
;             h[1][p] = B + W0 * A0 + W1 * A1 + W2 * A2;
;     __device__ __forceinline__ void operator()(f32x4 (&acc)[2][2][4][2], const Unit& u, int wr, int wc, int lane) const {
;     ...
;                 for (int m = 0; m < 4; ++m) {
;                     u32x2 w; w.x = silu_pk(hg[m][0], hv[m][0]); w.y = silu_pk(hg[m][1], hv[m][1]);
;                     if (n == 0) keep[ai][m] = w;
;                     else { u32x4 w4; w4.x = keep[ai][m].x; w4.y = keep[ai][m].y; w4.z = w.x; w4.w = w.y; gst<u32x4>(gu, ((unsigned)(4 * fr + m) * DFF + 8u * fq) * 2u, w4); }
;                 }
;                 if (fr == 0 || fr == 15) {
;                     const int mb = fr == 0 ? 0 : 2;
; #pragma unroll
;                     for (int e = 0; e < 2; ++e) { const unsigned eo = ((unsigned)(mb + e) * NUP + 8u * fq + 4u * n) * 2u;
;                         const f32x4 eg = fr == 0 ? acc[ai][0][e][n] : acc[ai][0][2 + e][n], ev = fr == 0 ? acc[ai][1][e][n] : acc[ai][1][2 + e][n];
;                         gst<u32x2>(eu, eo, (u32x2){cvt_pk_f16(eg[0], eg[1]), cvt_pk_f16(eg[2], eg[3])}); gst<u32x2>(eu + DFF, eo, (u32x2){cvt_pk_f16(ev[0], ev[1]), cvt_pk_f16(ev[2], ev[3])}); }
;                 }
	v_pk_mul_f32 v[76:77], v[76:77], v[84:85]
	v_exp_f32_e32 v86, v86
	v_exp_f32_e32 v87, v87
	v_cvt_pk_bf16_f32 v167, v64, v65
	v_add_u32_e32 v64, 0x1600, v216
	global_store_dwordx4 v64, v[164:167], s[42:43]
	v_pk_add_f32 v[86:87], v[86:87], 1.0 op_sel_hi:[1,0]
	v_mov_b32_e32 v65, v217
	v_rcp_f32_e32 v84, v86
	v_rcp_f32_e32 v85, v87
	s_nop 0
	v_pk_mul_f32 v[76:77], v[76:77], v[84:85]
	v_cvt_pk_bf16_f32 v164, v76, v77
	v_pk_mul_f32 v[76:77], v[68:69], s[12:13] op_sel_hi:[1,0]
	v_pk_mul_f32 v[68:69], v[68:69], v[78:79]
	v_exp_f32_e32 v76, v76
	v_exp_f32_e32 v77, v77
	s_nop 0
	v_pk_add_f32 v[76:77], v[76:77], 1.0 op_sel_hi:[1,0]
	v_rcp_f32_e32 v76, v76
	v_rcp_f32_e32 v77, v77
	s_nop 0
	v_pk_mul_f32 v[68:69], v[68:69], v[76:77]
	v_pk_mul_f32 v[76:77], v[70:71], s[12:13] op_sel_hi:[1,0]
	v_pk_mul_f32 v[70:71], v[70:71], v[74:75]
	v_exp_f32_e32 v76, v76
	v_exp_f32_e32 v77, v77
	v_cvt_pk_bf16_f32 v165, v68, v69
	v_mad_u32_u24 v68, v204, s92, v136
	global_store_dwordx4 v68, v[162:165], s[42:43]
	v_pk_add_f32 v[76:77], v[76:77], 1.0 op_sel_hi:[1,0]
	v_mov_b32_e32 v69, v217
	v_rcp_f32_e32 v74, v76
	v_rcp_f32_e32 v75, v77
	s_nop 0
	v_pk_mul_f32 v[70:71], v[70:71], v[74:75]
	v_cvt_pk_bf16_f32 v162, v70, v71
	v_pk_mul_f32 v[70:71], v[66:67], s[12:13] op_sel_hi:[1,0]
	v_pk_mul_f32 v[66:67], v[66:67], v[72:73]
	v_exp_f32_e32 v70, v70
	v_exp_f32_e32 v71, v71
	s_nop 0
	v_pk_add_f32 v[70:71], v[70:71], 1.0 op_sel_hi:[1,0]
	v_rcp_f32_e32 v70, v70
	v_rcp_f32_e32 v71, v71
	s_nop 0
	v_pk_mul_f32 v[66:67], v[66:67], v[70:71]
	v_cvt_pk_bf16_f32 v163, v66, v67
	v_add_u32_e32 v66, 0x4200, v216
	global_store_dwordx4 v66, v[160:163], s[42:43]
	v_mov_b32_e32 v67, v217
	v_cmp_gt_i32_e64 s[42:43], 15, v204
	s_and_saveexec_b64 s[52:53], s[42:43]
	v_cmp_eq_u32_e64 s[42:43], 0, v204
	s_orn2_b64 s[48:49], s[42:43], exec
	s_or_b64 exec, exec, s[52:53]
	v_or_b32_e32 v70, 8, v205
	v_mul_u32_u24_e32 v72, 0x2c00, v206
	s_movk_i32 s42, 0x2c08
	v_mad_u32_u24 v71, v206, s89, v70
	v_add3_u32 v70, v205, v72, s42
	s_and_saveexec_b64 s[42:43], s[48:49]
	s_cbranch_execz .LBB0_148
	s_add_u32 s48, s34, s62
	s_addc_u32 s49, s35, s61
	s_add_u32 s48, s48, s44
	s_addc_u32 s49, s49, s45
	s_add_u32 s52, s48, 0x1600
	v_cndmask_b32_e32 v58, v58, v62, vcc
	v_cndmask_b32_e32 v59, v59, v63, vcc
	v_cndmask_b32_e32 v56, v56, v60, vcc
	v_cndmask_b32_e32 v57, v57, v61, vcc
	v_cndmask_b32_e32 v44, v44, v36, vcc
	v_cndmask_b32_e32 v45, v45, v37, vcc
	v_cvt_pk_f16_f32 v36, v56, v57
	v_cvt_pk_f16_f32 v37, v58, v59
	s_addc_u32 s53, s49, 0
	v_cndmask_b32_e32 v38, v46, v38, vcc
	v_cndmask_b32_e32 v39, v47, v39, vcc
	global_store_dwordx2 v71, v[36:37], s[48:49]
	v_cvt_pk_f16_f32 v36, v44, v45
	v_cvt_pk_f16_f32 v37, v38, v39
	global_store_dwordx2 v71, v[36:37], s[52:53]
	v_cndmask_b32_e32 v36, v50, v54, vcc
	v_cndmask_b32_e32 v37, v51, v55, vcc
	v_cndmask_b32_e32 v38, v48, v52, vcc
	v_cndmask_b32_e32 v39, v49, v53, vcc
	v_cndmask_b32_e32 v40, v40, v32, vcc
	v_cndmask_b32_e32 v41, v41, v33, vcc
	v_cvt_pk_f16_f32 v32, v38, v39
	v_cvt_pk_f16_f32 v33, v36, v37
	v_cndmask_b32_e32 v34, v42, v34, vcc
	v_cndmask_b32_e32 v35, v43, v35, vcc
	global_store_dwordx2 v70, v[32:33], s[48:49]
	v_cvt_pk_f16_f32 v32, v40, v41
	v_cvt_pk_f16_f32 v33, v34, v35
	global_store_dwordx2 v70, v[32:33], s[52:53]
.LBB0_148:
	s_or_b64 exec, exec, s[42:43]
	v_mov_b32_dpp v32, v8 row_shr:1 row_mask:0xf bank_mask:0xf bound_ctrl:1
	v_mov_b32_dpp v33, v9 row_shr:1 row_mask:0xf bank_mask:0xf bound_ctrl:1
	v_mov_b32_dpp v34, v4 row_shl:1 row_mask:0xf bank_mask:0xf bound_ctrl:1
	v_mov_b32_dpp v35, v5 row_shl:1 row_mask:0xf bank_mask:0xf bound_ctrl:1
	s_add_i32 s42, s56, 0x80
	v_pk_fma_f32 v[32:33], v[80:81], v[32:33], v[108:109]
	s_mul_hi_i32 s43, s42, 0x1600
	v_pk_fma_f32 v[32:33], v[4:5], v[96:97], v[32:33]
	s_mulk_i32 s42, 0x1600
	v_pk_fma_f32 v[48:49], v[0:1], v[104:105], v[32:33]
	v_pk_fma_f32 v[32:33], v[4:5], v[80:81], v[108:109]
	s_add_u32 s42, s31, s42
	v_pk_fma_f32 v[32:33], v[0:1], v[96:97], v[32:33]
	s_addc_u32 s43, s33, s43
	v_pk_fma_f32 v[50:51], v[16:17], v[104:105], v[32:33]
	v_pk_fma_f32 v[32:33], v[0:1], v[80:81], v[108:109]
	s_add_u32 s42, s42, s44
	v_pk_fma_f32 v[32:33], v[16:17], v[96:97], v[32:33]
	s_addc_u32 s43, s43, s45
	v_pk_fma_f32 v[42:43], v[8:9], v[104:105], v[32:33]
	v_pk_fma_f32 v[32:33], v[16:17], v[80:81], v[108:109]
	s_mov_b64 s[48:49], -1
	v_pk_fma_f32 v[32:33], v[8:9], v[96:97], v[32:33]
	v_pk_fma_f32 v[34:35], v[104:105], v[34:35], v[32:33]
	v_mov_b32_dpp v32, v10 row_shr:1 row_mask:0xf bank_mask:0xf bound_ctrl:1
	v_mov_b32_dpp v33, v11 row_shr:1 row_mask:0xf bank_mask:0xf bound_ctrl:1
	v_mov_b32_dpp v36, v6 row_shl:1 row_mask:0xf bank_mask:0xf bound_ctrl:1
	v_mov_b32_dpp v37, v7 row_shl:1 row_mask:0xf bank_mask:0xf bound_ctrl:1
	v_pk_fma_f32 v[32:33], v[82:83], v[32:33], v[110:111]
	v_pk_fma_f32 v[32:33], v[6:7], v[98:99], v[32:33]
	v_pk_fma_f32 v[52:53], v[2:3], v[106:107], v[32:33]
	v_pk_fma_f32 v[32:33], v[6:7], v[82:83], v[110:111]
	v_pk_fma_f32 v[32:33], v[2:3], v[98:99], v[32:33]
	v_pk_fma_f32 v[54:55], v[18:19], v[106:107], v[32:33]
	v_pk_fma_f32 v[32:33], v[2:3], v[82:83], v[110:111]
	v_pk_fma_f32 v[32:33], v[18:19], v[98:99], v[32:33]
	v_pk_fma_f32 v[40:41], v[10:11], v[106:107], v[32:33]
	v_pk_fma_f32 v[32:33], v[18:19], v[82:83], v[110:111]
	v_pk_fma_f32 v[32:33], v[10:11], v[98:99], v[32:33]
	v_pk_fma_f32 v[32:33], v[106:107], v[36:37], v[32:33]
;     __device__ __forceinline__ void conv4(const f32x4& a0, const f32x4& a1, const f32x4& a2, const f32x4& a3, const f32x4& w0, const f32x4& w1, const f32x4& w2, const f32x4& b, f32x2 (&h)[4][2]) const {
;     ...
;             asm volatile("s_nop 1\n\tv_mov_b32_dpp %0, %1 row_shr:1 row_mask:0xf bank_mask:0xf bound_ctrl:1" : "=&v"(u0) : "v"(a3[2 * p]));
;             asm volatile("s_nop 1\n\tv_mov_b32_dpp %0, %1 row_shr:1 row_mask:0xf bank_mask:0xf bound_ctrl:1" : "=&v"(u1) : "v"(a3[2 * p + 1]));
;             asm volatile("s_nop 1\n\tv_mov_b32_dpp %0, %1 row_shl:1 row_mask:0xf bank_mask:0xf bound_ctrl:1" : "=&v"(d0) : "v"(a0[2 * p]));
;             asm volatile("s_nop 1\n\tv_mov_b32_dpp %0, %1 row_shl:1 row_mask:0xf bank_mask:0xf bound_ctrl:1" : "=&v"(d1) : "v"(a0[2 * p + 1]));
;             const f32x2 UP = {u0, u1}, DN = {d0, d1};
;             const f32x2 A0 = {a0[2 * p], a0[2 * p + 1]}, A1 = {a1[2 * p], a1[2 * p + 1]}, A2 = {a2[2 * p], a2[2 * p + 1]}, A3 = {a3[2 * p], a3[2 * p + 1]};
;             const f32x2 W0 = {w0[2 * p], w0[2 * p + 1]}, W1 = {w1[2 * p], w1[2 * p + 1]}, W2 = {w2[2 * p], w2[2 * p + 1]}, B = {b[2 * p], b[2 * p + 1]};
;             h[0][p] = B + W0 * UP + W1 * A0 + W2 * A1;
;             h[1][p] = B + W0 * A0 + W1 * A1 + W2 * A2;
;             h[2][p] = B + W0 * A1 + W1 * A2 + W2 * A3;
;             h[3][p] = B + W0 * A2 + W1 * A3 + W2 * DN;
;         }
;     }
;     static __device__ __forceinline__ unsigned silu_pk(const f32x2 g, const f32x2 v) {
;         const f32x2 t = g * -1.4426950408889634f;
;         const f32x2 d = (f32x2){__builtin_amdgcn_exp2f(t.x), __builtin_amdgcn_exp2f(t.y)} + 1.0f;
;         const f32x2 o = g * v * (f32x2){__builtin_amdgcn_rcpf(d.x), __builtin_amdgcn_rcpf(d.y)};
;         return cvt_pk_bf16(o.x, o.y);
;     }
;     __device__ __forceinline__ void operator()(f32x4 (&acc)[2][2][4][2], const Unit& u, int wr, int wc, int lane) const {
;     ...
;                 for (int m = 0; m < 4; ++m) {
;                     u32x2 w; w.x = silu_pk(hg[m][0], hv[m][0]); w.y = silu_pk(hg[m][1], hv[m][1]);
;                     if (n == 0) keep[ai][m] = w;
;                     else { u32x4 w4; w4.x = keep[ai][m].x; w4.y = keep[ai][m].y; w4.z = w.x; w4.w = w.y; gst<u32x4>(gu, ((unsigned)(4 * fr + m) * DFF + 8u * fq) * 2u, w4); }
;                 }
;                 if (fr == 0 || fr == 15) {
	v_mov_b32_dpp v36, v24 row_shr:1 row_mask:0xf bank_mask:0xf bound_ctrl:1
	v_mov_b32_dpp v37, v25 row_shr:1 row_mask:0xf bank_mask:0xf bound_ctrl:1
	v_mov_b32_dpp v38, v20 row_shl:1 row_mask:0xf bank_mask:0xf bound_ctrl:1
	v_mov_b32_dpp v39, v21 row_shl:1 row_mask:0xf bank_mask:0xf bound_ctrl:1
	v_pk_fma_f32 v[36:37], v[112:113], v[36:37], v[124:125]
	v_pk_fma_f32 v[36:37], v[20:21], v[116:117], v[36:37]
	v_pk_fma_f32 v[56:57], v[12:13], v[120:121], v[36:37]
	v_pk_fma_f32 v[36:37], v[20:21], v[112:113], v[124:125]
	v_pk_fma_f32 v[36:37], v[12:13], v[116:117], v[36:37]
	v_pk_fma_f32 v[58:59], v[28:29], v[120:121], v[36:37]
	v_pk_fma_f32 v[36:37], v[12:13], v[112:113], v[124:125]
	v_pk_fma_f32 v[36:37], v[28:29], v[116:117], v[36:37]
	v_pk_fma_f32 v[46:47], v[24:25], v[120:121], v[36:37]
	v_pk_fma_f32 v[36:37], v[28:29], v[112:113], v[124:125]
	v_pk_fma_f32 v[36:37], v[24:25], v[116:117], v[36:37]
	v_pk_fma_f32 v[38:39], v[120:121], v[38:39], v[36:37]
	v_mov_b32_dpp v36, v26 row_shr:1 row_mask:0xf bank_mask:0xf bound_ctrl:1
	v_mov_b32_dpp v37, v27 row_shr:1 row_mask:0xf bank_mask:0xf bound_ctrl:1
	v_mov_b32_dpp v60, v22 row_shl:1 row_mask:0xf bank_mask:0xf bound_ctrl:1
	v_mov_b32_dpp v61, v23 row_shl:1 row_mask:0xf bank_mask:0xf bound_ctrl:1
	v_pk_fma_f32 v[36:37], v[114:115], v[36:37], v[126:127]
	v_pk_fma_f32 v[36:37], v[22:23], v[118:119], v[36:37]
	v_pk_fma_f32 v[62:63], v[14:15], v[122:123], v[36:37]
	v_pk_fma_f32 v[36:37], v[22:23], v[114:115], v[126:127]
	v_pk_fma_f32 v[36:37], v[14:15], v[118:119], v[36:37]
	v_pk_fma_f32 v[72:73], v[30:31], v[122:123], v[36:37]
	v_pk_fma_f32 v[36:37], v[14:15], v[114:115], v[126:127]
	v_pk_fma_f32 v[36:37], v[30:31], v[118:119], v[36:37]
	v_pk_fma_f32 v[44:45], v[26:27], v[122:123], v[36:37]
	v_pk_fma_f32 v[36:37], v[30:31], v[114:115], v[126:127]
	v_pk_fma_f32 v[36:37], v[26:27], v[118:119], v[36:37]
	v_pk_fma_f32 v[36:37], v[122:123], v[60:61], v[36:37]
	v_pk_mul_f32 v[60:61], v[48:49], s[12:13] op_sel_hi:[1,0]
	v_pk_mul_f32 v[48:49], v[48:49], v[56:57]
	v_exp_f32_e32 v60, v60
	v_exp_f32_e32 v61, v61
	s_nop 0
	v_pk_add_f32 v[60:61], v[60:61], 1.0 op_sel_hi:[1,0]
	v_rcp_f32_e32 v56, v60
	v_rcp_f32_e32 v57, v61
	s_nop 0
	v_pk_mul_f32 v[48:49], v[48:49], v[56:57]
	v_cvt_pk_bf16_f32 v136, v48, v49
	v_pk_mul_f32 v[48:49], v[52:53], s[12:13] op_sel_hi:[1,0]
	v_pk_mul_f32 v[52:53], v[52:53], v[62:63]
	v_exp_f32_e32 v48, v48
	v_exp_f32_e32 v49, v49
	s_nop 0
	v_pk_add_f32 v[48:49], v[48:49], 1.0 op_sel_hi:[1,0]
	v_rcp_f32_e32 v48, v48
	v_rcp_f32_e32 v49, v49
	s_nop 0
	v_pk_mul_f32 v[48:49], v[52:53], v[48:49]
	v_cvt_pk_bf16_f32 v137, v48, v49
	v_lshl_add_u64 v[48:49], s[42:43], 0, v[216:217]
	global_store_dwordx4 v[48:49], v[134:137], off
	v_pk_mul_f32 v[48:49], v[50:51], s[12:13] op_sel_hi:[1,0]
	v_pk_mul_f32 v[50:51], v[50:51], v[58:59]
	v_exp_f32_e32 v48, v48
	v_exp_f32_e32 v49, v49
	s_nop 0
	v_pk_add_f32 v[48:49], v[48:49], 1.0 op_sel_hi:[1,0]
	v_rcp_f32_e32 v48, v48
	v_rcp_f32_e32 v49, v49
	s_nop 0
	v_pk_mul_f32 v[48:49], v[50:51], v[48:49]
	v_cvt_pk_bf16_f32 v134, v48, v49
	v_pk_mul_f32 v[48:49], v[54:55], s[12:13] op_sel_hi:[1,0]
	v_pk_mul_f32 v[50:51], v[54:55], v[72:73]
	v_exp_f32_e32 v48, v48
	v_exp_f32_e32 v49, v49
	s_nop 0
	v_pk_add_f32 v[48:49], v[48:49], 1.0 op_sel_hi:[1,0]
	v_rcp_f32_e32 v48, v48
	v_rcp_f32_e32 v49, v49
	s_nop 0
	v_pk_mul_f32 v[48:49], v[50:51], v[48:49]
	v_cvt_pk_bf16_f32 v135, v48, v49
	v_lshl_add_u64 v[48:49], s[42:43], 0, v[64:65]
	global_store_dwordx4 v[48:49], v[132:135], off
	v_pk_mul_f32 v[48:49], v[42:43], s[12:13] op_sel_hi:[1,0]
	v_pk_mul_f32 v[42:43], v[42:43], v[46:47]
	v_exp_f32_e32 v48, v48
	v_exp_f32_e32 v49, v49
	s_nop 0
	v_pk_add_f32 v[48:49], v[48:49], 1.0 op_sel_hi:[1,0]
	v_rcp_f32_e32 v46, v48
	v_rcp_f32_e32 v47, v49
	s_nop 0
	v_pk_mul_f32 v[42:43], v[42:43], v[46:47]
	v_cvt_pk_bf16_f32 v132, v42, v43
	v_pk_mul_f32 v[42:43], v[40:41], s[12:13] op_sel_hi:[1,0]
	v_pk_mul_f32 v[40:41], v[40:41], v[44:45]
	v_exp_f32_e32 v42, v42
	v_exp_f32_e32 v43, v43
	s_nop 0
	v_pk_add_f32 v[42:43], v[42:43], 1.0 op_sel_hi:[1,0]
	v_rcp_f32_e32 v42, v42
	v_rcp_f32_e32 v43, v43
	s_nop 0
	v_pk_mul_f32 v[40:41], v[40:41], v[42:43]
	v_cvt_pk_bf16_f32 v133, v40, v41
	v_lshl_add_u64 v[40:41], s[42:43], 0, v[68:69]
	global_store_dwordx4 v[40:41], v[130:133], off
	v_pk_mul_f32 v[40:41], v[34:35], s[12:13] op_sel_hi:[1,0]
	v_pk_mul_f32 v[34:35], v[34:35], v[38:39]
	v_exp_f32_e32 v40, v40
	v_exp_f32_e32 v41, v41
	s_nop 0
	v_pk_add_f32 v[40:41], v[40:41], 1.0 op_sel_hi:[1,0]
	v_rcp_f32_e32 v38, v40
	v_rcp_f32_e32 v39, v41
	s_nop 0
	v_pk_mul_f32 v[34:35], v[34:35], v[38:39]
	v_cvt_pk_bf16_f32 v130, v34, v35
	v_pk_mul_f32 v[34:35], v[32:33], s[12:13] op_sel_hi:[1,0]
	v_pk_mul_f32 v[32:33], v[32:33], v[36:37]
	v_exp_f32_e32 v34, v34
	v_exp_f32_e32 v35, v35
	s_nop 0
	v_pk_add_f32 v[34:35], v[34:35], 1.0 op_sel_hi:[1,0]
	v_rcp_f32_e32 v34, v34
	v_rcp_f32_e32 v35, v35
	s_nop 0
	v_pk_mul_f32 v[32:33], v[32:33], v[34:35]
	v_cvt_pk_bf16_f32 v131, v32, v33
	v_lshl_add_u64 v[32:33], s[42:43], 0, v[66:67]
	v_cmp_gt_i32_e64 s[42:43], 15, v204
	global_store_dwordx4 v[32:33], v[128:131], off
	s_and_saveexec_b64 s[52:53], s[42:43]
	s_cbranch_execz .LBB0_151
	v_cmp_eq_u32_e64 s[42:43], 0, v204
	s_orn2_b64 s[48:49], s[42:43], exec
	s_or_b64 exec, exec, s[52:53]
	s_and_saveexec_b64 s[42:43], s[48:49]
	s_cbranch_execnz .LBB0_152

; #define PG8_STAGE(bufoff, gbase, voff) do { _Pragma("unroll") for (int _i = 0; _i < 2; ++_i) \
;         __builtin_amdgcn_global_load_lds((const GAS unsigned*)((const GAS char*)(gbase) + (size_t)_i * r64##voff + (vo##voff)), (LAS unsigned*)(lds + (bufoff) + ldsw + _i * 8192), 16, 0, 0); } while (0)
; #define PG8_LDA(dst, b, h) do { _Pragma("unroll") for (int m = 0; m < 4; ++m) _Pragma("unroll") for (int k = 0; k < 2; ++k) dst[m][k] = *(const LAS bf16x8*)(lds + PG8_SA(b, h) + aoff + m * 2048 + k * 1024); } while (0)
; #define PG8_LDB(dst, b, h) do { _Pragma("unroll") for (int n = 0; n < 2; ++n) _Pragma("unroll") for (int k = 0; k < 2; ++k) dst[n][k] = *(const LAS bf16x8*)(lds + PG8_SB(b, h) + boff + n * 2048 + k * 1024); } while (0)
; #define PG8_MMA(ai, bj, At, Bt) do { __builtin_amdgcn_s_setprio(1); _Pragma("unroll") for (int m = 0; m < 4; ++m) _Pragma("unroll") for (int n = 0; n < 2; ++n) _Pragma("unroll") for (int k = 0; k < 2; ++k) \
;         acc[ai][bj][m][n] = __builtin_amdgcn_mfma_f32_16x16x32_bf16(Bt[n][k], At[m][k], acc[ai][bj][m][n], 0, 0, 0); __builtin_amdgcn_s_setprio(0); } while (0)
; #define PG8_WAIT_V(n) asm volatile("s_waitcnt vmcnt(" #n ")" ::: "memory")
; #define PG8_WAIT_L(n) asm volatile("s_waitcnt lgkmcnt(" #n ")" ::: "memory")
; #define PG8_BAR __builtin_amdgcn_s_barrier()
; template <class Epi, class Map, bool ALIGN_EPI>
; __device__ __forceinline__ void gemm_phase(const int tid, LAS unsigned char* lds, const int lda, const int ldb, const int K, const Map& MP, const StaticOrder& S, const Epi& E) {
;     ...
;             const bool last = (t == nt - 2);
;             const char* a1 = cA + (size_t)(t + 1) * kstep;
;             const char* a2 = last ? nA : cA + (size_t)(t + 2) * kstep; const char* b2 = last ? nB : cB + (size_t)(t + 2) * kstep;
;             const char* a3 = a2 + kstep; const char* b3 = b2 + kstep;
;             PG8_LDB(B0, 0, 0); PG8_LDB(B1, 0, 1); PG8_SCHED; PG8_LDA(At, 0, 0); PG8_STAGE(PG8_SA(1, 1), a1 + hstepA, A);
;             PG8_WAIT_V(8); PG8_WAIT_L(0); PG8_BAR; PG8_MMA(0, 0, At, B0); PG8_MMA(0, 1, At, B1); PG8_BAR; PG8_SCHED;
;             PG8_LDA(At, 0, 1); PG8_STAGE(PG8_SB(0, 0), b2, B); PG8_STAGE(PG8_SB(0, 1), b2 + hstepB, B); PG8_STAGE(PG8_SA(0, 0), a2, A);
;             PG8_WAIT_V(8); PG8_WAIT_L(0); PG8_BAR; PG8_MMA(1, 0, At, B0); PG8_MMA(1, 1, At, B1); PG8_BAR; PG8_SCHED;
.LBB0_284:
	s_add_u32 s42, s10, 0xfffc0080
	s_addc_u32 s43, s11, -1
	s_add_i32 s45, 0, 0x10000
	s_cmp_eq_u32 s44, 12
	s_cselect_b32 s43, s53, s43
	s_cselect_b32 s42, s52, s42
	s_cselect_b32 s59, s57, s47
	s_cselect_b32 s58, s56, s23
	s_add_i32 s49, 0, 0x14000
	v_add_u32_e32 v144, s45, v148
	v_add_u32_e32 v162, s49, v148
	ds_read_b128 v[132:135], v144
	ds_read_b128 v[136:139], v144 offset:1024
	ds_read_b128 v[140:143], v144 offset:2048
	ds_read_b128 v[144:147], v144 offset:3072
	ds_read_b128 v[150:153], v162
	ds_read_b128 v[154:157], v162 offset:1024
	ds_read_b128 v[158:161], v162 offset:2048
	ds_read_b128 v[162:165], v162 offset:3072
	v_lshl_add_u64 v[198:199], s[10:11], 0, v[130:131]
	s_add_i32 m0, s19, 0xc000
	ds_read_b128 v[166:169], v149
	ds_read_b128 v[170:173], v149 offset:1024
	ds_read_b128 v[174:177], v149 offset:2048
	ds_read_b128 v[178:181], v149 offset:3072
	ds_read_b128 v[182:185], v149 offset:4096
	ds_read_b128 v[186:189], v149 offset:5120
	ds_read_b128 v[190:193], v149 offset:6144
	ds_read_b128 v[194:197], v149 offset:7168
	global_load_lds_dwordx4 v[198:199], off
	v_lshl_add_u64 v[198:199], v[198:199], 0, s[90:91]
	s_add_i32 m0, s19, 0xe000
	s_nop 0
	global_load_lds_dwordx4 v[198:199], off
	s_waitcnt vmcnt(8)
	s_waitcnt lgkmcnt(0)
	s_barrier
	s_setprio 1
	v_mfma_f32_16x16x32_bf16 v[124:127], v[132:135], v[166:169], v[124:127]
	v_mfma_f32_16x16x32_bf16 v[120:123], v[140:143], v[166:169], v[120:123]
	v_mfma_f32_16x16x32_bf16 v[108:111], v[132:135], v[174:177], v[108:111]
	v_mfma_f32_16x16x32_bf16 v[104:107], v[140:143], v[174:177], v[104:107]
	v_mfma_f32_16x16x32_bf16 v[92:95], v[132:135], v[182:185], v[92:95]
	v_mfma_f32_16x16x32_bf16 v[88:91], v[140:143], v[182:185], v[88:91]
	v_mfma_f32_16x16x32_bf16 v[76:79], v[132:135], v[190:193], v[76:79]
	v_mfma_f32_16x16x32_bf16 v[72:75], v[140:143], v[190:193], v[72:75]
	v_mfma_f32_16x16x32_bf16 v[124:127], v[136:139], v[170:173], v[124:127]
	v_mfma_f32_16x16x32_bf16 v[120:123], v[144:147], v[170:173], v[120:123]
	v_mfma_f32_16x16x32_bf16 v[108:111], v[136:139], v[178:181], v[108:111]
	v_mfma_f32_16x16x32_bf16 v[104:107], v[144:147], v[178:181], v[104:107]
	v_mfma_f32_16x16x32_bf16 v[92:95], v[136:139], v[186:189], v[92:95]
	v_mfma_f32_16x16x32_bf16 v[88:91], v[144:147], v[186:189], v[88:91]
	v_mfma_f32_16x16x32_bf16 v[76:79], v[136:139], v[194:197], v[76:79]
	v_mfma_f32_16x16x32_bf16 v[72:75], v[144:147], v[194:197], v[72:75]
	s_setprio 0
	s_setprio 1
	v_mfma_f32_16x16x32_bf16 v[116:119], v[150:153], v[166:169], v[116:119]
	v_mfma_f32_16x16x32_bf16 v[112:115], v[158:161], v[166:169], v[112:115]
	v_mfma_f32_16x16x32_bf16 v[100:103], v[150:153], v[174:177], v[100:103]
	v_mfma_f32_16x16x32_bf16 v[96:99], v[158:161], v[174:177], v[96:99]
	v_mfma_f32_16x16x32_bf16 v[84:87], v[150:153], v[182:185], v[84:87]
	v_mfma_f32_16x16x32_bf16 v[80:83], v[158:161], v[182:185], v[80:83]
	v_mfma_f32_16x16x32_bf16 v[68:71], v[150:153], v[190:193], v[68:71]
	v_mfma_f32_16x16x32_bf16 v[64:67], v[158:161], v[190:193], v[64:67]
	v_mfma_f32_16x16x32_bf16 v[116:119], v[154:157], v[170:173], v[116:119]
	v_mfma_f32_16x16x32_bf16 v[112:115], v[162:165], v[170:173], v[112:115]
	v_mfma_f32_16x16x32_bf16 v[100:103], v[154:157], v[178:181], v[100:103]
	v_mfma_f32_16x16x32_bf16 v[96:99], v[162:165], v[178:181], v[96:99]
	v_mfma_f32_16x16x32_bf16 v[84:87], v[154:157], v[186:189], v[84:87]
	v_mfma_f32_16x16x32_bf16 v[80:83], v[162:165], v[186:189], v[80:83]
	v_mfma_f32_16x16x32_bf16 v[68:71], v[154:157], v[194:197], v[68:71]
	v_mfma_f32_16x16x32_bf16 v[64:67], v[162:165], v[194:197], v[64:67]
	s_setprio 0
	s_barrier
	s_add_i32 s45, s45, s18
	v_lshl_add_u64 v[198:199], s[58:59], 0, v[128:129]
	s_mov_b32 m0, s45
	ds_read_b128 v[166:169], v149 offset:16384
	ds_read_b128 v[170:173], v149 offset:17408
	ds_read_b128 v[174:177], v149 offset:18432
	ds_read_b128 v[178:181], v149 offset:19456
	ds_read_b128 v[182:185], v149 offset:20480
	ds_read_b128 v[186:189], v149 offset:21504
	ds_read_b128 v[190:193], v149 offset:22528
	ds_read_b128 v[194:197], v149 offset:23552
	global_load_lds_dwordx4 v[198:199], off
	v_lshl_add_u64 v[200:201], v[198:199], 0, s[90:91]
	s_add_i32 m0, s45, 0x2000
	s_add_i32 s45, s49, s18
	global_load_lds_dwordx4 v[200:201], off
	v_lshl_add_u64 v[200:201], v[198:199], 0, s[74:75]
	s_mov_b32 m0, s45
	s_nop 0
	global_load_lds_dwordx4 v[200:201], off
	v_lshl_add_u64 v[200:201], v[198:199], 0, s[94:95]
	s_add_i32 m0, s45, 0x2000
	s_nop 0
	global_load_lds_dwordx4 v[200:201], off
	v_lshl_add_u64 v[200:201], s[42:43], 0, v[130:131]
	s_mov_b32 m0, s19
	v_lshl_add_u64 v[202:203], v[200:201], 0, s[90:91]
	global_load_lds_dwordx4 v[200:201], off
	s_mov_b32 m0, s24
	s_nop 0
	global_load_lds_dwordx4 v[202:203], off
	s_waitcnt vmcnt(8)
	s_waitcnt lgkmcnt(0)
	s_barrier
; #define PG8_STAGE(bufoff, gbase, voff) do { _Pragma("unroll") for (int _i = 0; _i < 2; ++_i) \
;         __builtin_amdgcn_global_load_lds((const GAS unsigned*)((const GAS char*)(gbase) + (size_t)_i * r64##voff + (vo##voff)), (LAS unsigned*)(lds + (bufoff) + ldsw + _i * 8192), 16, 0, 0); } while (0)
; #define PG8_LDA(dst, b, h) do { _Pragma("unroll") for (int m = 0; m < 4; ++m) _Pragma("unroll") for (int k = 0; k < 2; ++k) dst[m][k] = *(const LAS bf16x8*)(lds + PG8_SA(b, h) + aoff + m * 2048 + k * 1024); } while (0)
; #define PG8_LDB(dst, b, h) do { _Pragma("unroll") for (int n = 0; n < 2; ++n) _Pragma("unroll") for (int k = 0; k < 2; ++k) dst[n][k] = *(const LAS bf16x8*)(lds + PG8_SB(b, h) + boff + n * 2048 + k * 1024); } while (0)
; #define PG8_MMA(ai, bj, At, Bt) do { __builtin_amdgcn_s_setprio(1); _Pragma("unroll") for (int m = 0; m < 4; ++m) _Pragma("unroll") for (int n = 0; n < 2; ++n) _Pragma("unroll") for (int k = 0; k < 2; ++k) \
;         acc[ai][bj][m][n] = __builtin_amdgcn_mfma_f32_16x16x32_bf16(Bt[n][k], At[m][k], acc[ai][bj][m][n], 0, 0, 0); __builtin_amdgcn_s_setprio(0); } while (0)
; #define PG8_WAIT_V(n) asm volatile("s_waitcnt vmcnt(" #n ")" ::: "memory")
; #define PG8_WAIT_L(n) asm volatile("s_waitcnt lgkmcnt(" #n ")" ::: "memory")
; #define PG8_BAR __builtin_amdgcn_s_barrier()
; #define PG8_SCHED __builtin_amdgcn_sched_barrier(0)
; template <class Epi, class Map, bool ALIGN_EPI>
; __device__ __forceinline__ void gemm_phase(const int tid, LAS unsigned char* lds, const int lda, const int ldb, const int K, const Map& MP, const StaticOrder& S, const Epi& E) {
;     ...
;             PG8_WAIT_V(8); PG8_WAIT_L(0); PG8_BAR; PG8_MMA(1, 0, At, B0); PG8_MMA(1, 1, At, B1); PG8_BAR; PG8_SCHED;
;             PG8_LDB(B0, 1, 0); PG8_LDB(B1, 1, 1); PG8_SCHED; PG8_LDA(At, 1, 0); PG8_STAGE(PG8_SA(0, 1), a2 + hstepA, A);
;             PG8_WAIT_V(8); PG8_WAIT_L(0); PG8_BAR; PG8_MMA(0, 0, At, B0); PG8_MMA(0, 1, At, B1); PG8_BAR; PG8_SCHED;
;             PG8_LDA(At, 1, 1); PG8_STAGE(PG8_SB(1, 0), b3, B); PG8_STAGE(PG8_SB(1, 1), b3 + hstepB, B); PG8_STAGE(PG8_SA(1, 0), a3, A);
	s_setprio 1
	v_mfma_f32_16x16x32_bf16 v[60:63], v[132:135], v[166:169], v[60:63]
	v_mfma_f32_16x16x32_bf16 v[56:59], v[140:143], v[166:169], v[56:59]
	v_mfma_f32_16x16x32_bf16 v[44:47], v[132:135], v[174:177], v[44:47]
	v_mfma_f32_16x16x32_bf16 v[40:43], v[140:143], v[174:177], v[40:43]
	v_mfma_f32_16x16x32_bf16 v[28:31], v[132:135], v[182:185], v[28:31]
	v_mfma_f32_16x16x32_bf16 v[24:27], v[140:143], v[182:185], v[24:27]
	v_mfma_f32_16x16x32_bf16 v[12:15], v[132:135], v[190:193], v[12:15]
	v_mfma_f32_16x16x32_bf16 v[8:11], v[140:143], v[190:193], v[8:11]
	v_mfma_f32_16x16x32_bf16 v[60:63], v[136:139], v[170:173], v[60:63]
	v_mfma_f32_16x16x32_bf16 v[56:59], v[144:147], v[170:173], v[56:59]
	v_mfma_f32_16x16x32_bf16 v[44:47], v[136:139], v[178:181], v[44:47]
	v_mfma_f32_16x16x32_bf16 v[40:43], v[144:147], v[178:181], v[40:43]
	v_mfma_f32_16x16x32_bf16 v[28:31], v[136:139], v[186:189], v[28:31]
	v_mfma_f32_16x16x32_bf16 v[24:27], v[144:147], v[186:189], v[24:27]
	v_mfma_f32_16x16x32_bf16 v[12:15], v[136:139], v[194:197], v[12:15]
	v_mfma_f32_16x16x32_bf16 v[8:11], v[144:147], v[194:197], v[8:11]
	s_setprio 0
	s_setprio 1
	v_mfma_f32_16x16x32_bf16 v[52:55], v[150:153], v[166:169], v[52:55]
	v_mfma_f32_16x16x32_bf16 v[48:51], v[158:161], v[166:169], v[48:51]
	v_mfma_f32_16x16x32_bf16 v[36:39], v[150:153], v[174:177], v[36:39]
	v_mfma_f32_16x16x32_bf16 v[32:35], v[158:161], v[174:177], v[32:35]
	v_mfma_f32_16x16x32_bf16 v[20:23], v[150:153], v[182:185], v[20:23]
	v_mfma_f32_16x16x32_bf16 v[16:19], v[158:161], v[182:185], v[16:19]
	v_mfma_f32_16x16x32_bf16 v[4:7], v[150:153], v[190:193], v[4:7]
	v_mfma_f32_16x16x32_bf16 v[0:3], v[158:161], v[190:193], v[0:3]
	v_mfma_f32_16x16x32_bf16 v[52:55], v[154:157], v[170:173], v[52:55]
	v_mfma_f32_16x16x32_bf16 v[48:51], v[162:165], v[170:173], v[48:51]
	v_mfma_f32_16x16x32_bf16 v[36:39], v[154:157], v[178:181], v[36:39]
	v_mfma_f32_16x16x32_bf16 v[32:35], v[162:165], v[178:181], v[32:35]
	v_mfma_f32_16x16x32_bf16 v[20:23], v[154:157], v[186:189], v[20:23]
	v_mfma_f32_16x16x32_bf16 v[16:19], v[162:165], v[186:189], v[16:19]
	v_mfma_f32_16x16x32_bf16 v[4:7], v[154:157], v[194:197], v[4:7]
	v_mfma_f32_16x16x32_bf16 v[0:3], v[162:165], v[194:197], v[0:3]
	s_setprio 0
	s_barrier
	s_add_i32 s42, 0, 0x18000
	s_add_i32 s43, 0, 0x1c000
	v_add_u32_e32 v144, s42, v148
	v_add_u32_e32 v162, s43, v148
	ds_read_b128 v[132:135], v144
	ds_read_b128 v[136:139], v144 offset:1024
	ds_read_b128 v[140:143], v144 offset:2048
	ds_read_b128 v[144:147], v144 offset:3072
	ds_read_b128 v[150:153], v162
	ds_read_b128 v[154:157], v162 offset:1024
	ds_read_b128 v[158:161], v162 offset:2048
	ds_read_b128 v[162:165], v162 offset:3072
	s_mov_b32 m0, s28
	v_lshl_add_u64 v[202:203], v[200:201], 0, s[74:75]
	ds_read_b128 v[166:169], v149 offset:32768
	ds_read_b128 v[170:173], v149 offset:33792
	ds_read_b128 v[174:177], v149 offset:34816
	ds_read_b128 v[178:181], v149 offset:35840
	ds_read_b128 v[182:185], v149 offset:36864
	ds_read_b128 v[186:189], v149 offset:37888
	ds_read_b128 v[190:193], v149 offset:38912
	ds_read_b128 v[194:197], v149 offset:39936
	global_load_lds_dwordx4 v[202:203], off
	v_lshl_add_u64 v[202:203], v[200:201], 0, s[94:95]
	s_mov_b32 m0, s29
	s_nop 0
	global_load_lds_dwordx4 v[202:203], off
	s_waitcnt vmcnt(8)
	s_waitcnt lgkmcnt(0)
	s_barrier
	s_setprio 1
	v_mfma_f32_16x16x32_bf16 v[124:127], v[132:135], v[166:169], v[124:127]
	v_mfma_f32_16x16x32_bf16 v[120:123], v[140:143], v[166:169], v[120:123]
	v_mfma_f32_16x16x32_bf16 v[108:111], v[132:135], v[174:177], v[108:111]
	v_mfma_f32_16x16x32_bf16 v[104:107], v[140:143], v[174:177], v[104:107]
	v_mfma_f32_16x16x32_bf16 v[92:95], v[132:135], v[182:185], v[92:95]
	v_mfma_f32_16x16x32_bf16 v[88:91], v[140:143], v[182:185], v[88:91]
	v_mfma_f32_16x16x32_bf16 v[76:79], v[132:135], v[190:193], v[76:79]
	v_mfma_f32_16x16x32_bf16 v[72:75], v[140:143], v[190:193], v[72:75]
	v_mfma_f32_16x16x32_bf16 v[124:127], v[136:139], v[170:173], v[124:127]
	v_mfma_f32_16x16x32_bf16 v[120:123], v[144:147], v[170:173], v[120:123]
	v_mfma_f32_16x16x32_bf16 v[108:111], v[136:139], v[178:181], v[108:111]
	v_mfma_f32_16x16x32_bf16 v[104:107], v[144:147], v[178:181], v[104:107]
	v_mfma_f32_16x16x32_bf16 v[92:95], v[136:139], v[186:189], v[92:95]
	v_mfma_f32_16x16x32_bf16 v[88:91], v[144:147], v[186:189], v[88:91]
	v_mfma_f32_16x16x32_bf16 v[76:79], v[136:139], v[194:197], v[76:79]
	v_mfma_f32_16x16x32_bf16 v[72:75], v[144:147], v[194:197], v[72:75]
	s_setprio 0
	s_setprio 1
	v_mfma_f32_16x16x32_bf16 v[116:119], v[150:153], v[166:169], v[116:119]
	v_mfma_f32_16x16x32_bf16 v[112:115], v[158:161], v[166:169], v[112:115]
	v_mfma_f32_16x16x32_bf16 v[100:103], v[150:153], v[174:177], v[100:103]
	v_mfma_f32_16x16x32_bf16 v[96:99], v[158:161], v[174:177], v[96:99]
	v_mfma_f32_16x16x32_bf16 v[84:87], v[150:153], v[182:185], v[84:87]
	v_mfma_f32_16x16x32_bf16 v[80:83], v[158:161], v[182:185], v[80:83]
	v_mfma_f32_16x16x32_bf16 v[68:71], v[150:153], v[190:193], v[68:71]
	v_mfma_f32_16x16x32_bf16 v[64:67], v[158:161], v[190:193], v[64:67]
	v_mfma_f32_16x16x32_bf16 v[116:119], v[154:157], v[170:173], v[116:119]
	v_mfma_f32_16x16x32_bf16 v[112:115], v[162:165], v[170:173], v[112:115]
	v_mfma_f32_16x16x32_bf16 v[100:103], v[154:157], v[178:181], v[100:103]
	v_mfma_f32_16x16x32_bf16 v[96:99], v[162:165], v[178:181], v[96:99]
	v_mfma_f32_16x16x32_bf16 v[84:87], v[154:157], v[186:189], v[84:87]
	v_mfma_f32_16x16x32_bf16 v[80:83], v[162:165], v[186:189], v[80:83]
	v_mfma_f32_16x16x32_bf16 v[68:71], v[154:157], v[194:197], v[68:71]
	v_mfma_f32_16x16x32_bf16 v[64:67], v[162:165], v[194:197], v[64:67]
	s_setprio 0
	s_barrier
; #define PG8_STAGE(bufoff, gbase, voff) do { _Pragma("unroll") for (int _i = 0; _i < 2; ++_i) \
;         __builtin_amdgcn_global_load_lds((const GAS unsigned*)((const GAS char*)(gbase) + (size_t)_i * r64##voff + (vo##voff)), (LAS unsigned*)(lds + (bufoff) + ldsw + _i * 8192), 16, 0, 0); } while (0)
; #define PG8_LDA(dst, b, h) do { _Pragma("unroll") for (int m = 0; m < 4; ++m) _Pragma("unroll") for (int k = 0; k < 2; ++k) dst[m][k] = *(const LAS bf16x8*)(lds + PG8_SA(b, h) + aoff + m * 2048 + k * 1024); } while (0)
; #define PG8_MMA(ai, bj, At, Bt) do { __builtin_amdgcn_s_setprio(1); _Pragma("unroll") for (int m = 0; m < 4; ++m) _Pragma("unroll") for (int n = 0; n < 2; ++n) _Pragma("unroll") for (int k = 0; k < 2; ++k) \
;         acc[ai][bj][m][n] = __builtin_amdgcn_mfma_f32_16x16x32_bf16(Bt[n][k], At[m][k], acc[ai][bj][m][n], 0, 0, 0); __builtin_amdgcn_s_setprio(0); } while (0)
; #define PG8_WAIT_V(n) asm volatile("s_waitcnt vmcnt(" #n ")" ::: "memory")
; #define PG8_WAIT_L(n) asm volatile("s_waitcnt lgkmcnt(" #n ")" ::: "memory")
; #define PG8_BAR __builtin_amdgcn_s_barrier()
; #define PG8_SCHED __builtin_amdgcn_sched_barrier(0)
; template <class Epi, class Map, bool ALIGN_EPI>
; __device__ __forceinline__ void gemm_phase(const int tid, LAS unsigned char* lds, const int lda, const int ldb, const int K, const Map& MP, const StaticOrder& S, const Epi& E) {
;     ...
;             PG8_LDA(At, 1, 1); PG8_STAGE(PG8_SB(1, 0), b3, B); PG8_STAGE(PG8_SB(1, 1), b3 + hstepB, B); PG8_STAGE(PG8_SA(1, 0), a3, A);
;             PG8_WAIT_V(8); PG8_WAIT_L(0); PG8_BAR; PG8_MMA(1, 0, At, B0); PG8_MMA(1, 1, At, B1); PG8_BAR; PG8_SCHED;
;         }
;         if constexpr (ALIGN_EPI) { if (wr == 0) PG8_BAR; }
	s_add_i32 s42, s42, s18
	v_lshl_add_u64 v[202:203], v[198:199], 0, s[50:51]
	s_mov_b32 m0, s42
	ds_read_b128 v[166:169], v149 offset:49152
	ds_read_b128 v[170:173], v149 offset:50176
	ds_read_b128 v[174:177], v149 offset:51200
	ds_read_b128 v[178:181], v149 offset:52224
	ds_read_b128 v[182:185], v149 offset:53248
	ds_read_b128 v[186:189], v149 offset:54272
	ds_read_b128 v[190:193], v149 offset:55296
	ds_read_b128 v[194:197], v149 offset:56320
	global_load_lds_dwordx4 v[202:203], off
	v_lshl_add_u64 v[202:203], v[198:199], 0, s[54:55]
	s_add_i32 m0, s42, 0x2000
	s_add_i32 s42, s43, s18
	global_load_lds_dwordx4 v[202:203], off
	v_lshl_add_u64 v[202:203], v[198:199], 0, s[96:97]
	s_mov_b32 m0, s42
	v_lshl_add_u64 v[198:199], v[198:199], 0, s[6:7]
	global_load_lds_dwordx4 v[202:203], off
	s_add_i32 m0, s42, 0x2000
	s_nop 0
	global_load_lds_dwordx4 v[198:199], off
	v_lshl_add_u64 v[198:199], v[200:201], 0, s[50:51]
	s_mov_b32 m0, s34
	s_nop 0
	global_load_lds_dwordx4 v[198:199], off
	v_lshl_add_u64 v[198:199], v[200:201], 0, s[54:55]
	s_mov_b32 m0, s35
	s_nop 0
	global_load_lds_dwordx4 v[198:199], off
	s_waitcnt vmcnt(8)
	s_waitcnt lgkmcnt(0)
	s_barrier
	s_setprio 1
	v_mfma_f32_16x16x32_bf16 v[60:63], v[132:135], v[166:169], v[60:63]
	v_mfma_f32_16x16x32_bf16 v[56:59], v[140:143], v[166:169], v[56:59]
	v_mfma_f32_16x16x32_bf16 v[44:47], v[132:135], v[174:177], v[44:47]
	v_mfma_f32_16x16x32_bf16 v[40:43], v[140:143], v[174:177], v[40:43]
	v_mfma_f32_16x16x32_bf16 v[28:31], v[132:135], v[182:185], v[28:31]
	v_mfma_f32_16x16x32_bf16 v[24:27], v[140:143], v[182:185], v[24:27]
	v_mfma_f32_16x16x32_bf16 v[12:15], v[132:135], v[190:193], v[12:15]
	v_mfma_f32_16x16x32_bf16 v[8:11], v[140:143], v[190:193], v[8:11]
	v_mfma_f32_16x16x32_bf16 v[60:63], v[136:139], v[170:173], v[60:63]
	v_mfma_f32_16x16x32_bf16 v[56:59], v[144:147], v[170:173], v[56:59]
	v_mfma_f32_16x16x32_bf16 v[44:47], v[136:139], v[178:181], v[44:47]
	v_mfma_f32_16x16x32_bf16 v[40:43], v[144:147], v[178:181], v[40:43]
	v_mfma_f32_16x16x32_bf16 v[28:31], v[136:139], v[186:189], v[28:31]
	v_mfma_f32_16x16x32_bf16 v[24:27], v[144:147], v[186:189], v[24:27]
	v_mfma_f32_16x16x32_bf16 v[12:15], v[136:139], v[194:197], v[12:15]
	v_mfma_f32_16x16x32_bf16 v[8:11], v[144:147], v[194:197], v[8:11]
	s_setprio 0
	s_setprio 1
	v_mfma_f32_16x16x32_bf16 v[52:55], v[150:153], v[166:169], v[52:55]
	v_mfma_f32_16x16x32_bf16 v[48:51], v[158:161], v[166:169], v[48:51]
	v_mfma_f32_16x16x32_bf16 v[36:39], v[150:153], v[174:177], v[36:39]
	v_mfma_f32_16x16x32_bf16 v[32:35], v[158:161], v[174:177], v[32:35]
	v_mfma_f32_16x16x32_bf16 v[20:23], v[150:153], v[182:185], v[20:23]
	v_mfma_f32_16x16x32_bf16 v[16:19], v[158:161], v[182:185], v[16:19]
	v_mfma_f32_16x16x32_bf16 v[4:7], v[150:153], v[190:193], v[4:7]
	v_mfma_f32_16x16x32_bf16 v[0:3], v[158:161], v[190:193], v[0:3]
	v_mfma_f32_16x16x32_bf16 v[52:55], v[154:157], v[170:173], v[52:55]
	v_mfma_f32_16x16x32_bf16 v[48:51], v[162:165], v[170:173], v[48:51]
	v_mfma_f32_16x16x32_bf16 v[36:39], v[154:157], v[178:181], v[36:39]
	v_mfma_f32_16x16x32_bf16 v[32:35], v[162:165], v[178:181], v[32:35]
	v_mfma_f32_16x16x32_bf16 v[20:23], v[154:157], v[186:189], v[20:23]
	v_mfma_f32_16x16x32_bf16 v[16:19], v[162:165], v[186:189], v[16:19]
	v_mfma_f32_16x16x32_bf16 v[4:7], v[154:157], v[194:197], v[4:7]
	v_mfma_f32_16x16x32_bf16 v[0:3], v[162:165], v[194:197], v[0:3]
	s_setprio 0
	s_barrier
	s_add_i32 s44, s44, 2
	s_add_u32 s23, s23, 0x100
	s_addc_u32 s47, s47, 0
	s_add_u32 s10, s10, 0x100
	s_addc_u32 s11, s11, 0
	s_cmp_gt_u32 s44, 13
	s_cbranch_scc0 .LBB0_284
	s_and_b64 vcc, exec, s[16:17]
	s_cbranch_vccz .LBB0_287
	s_barrier

; #define PG8_STAGE(bufoff, gbase, voff) do { _Pragma("unroll") for (int _i = 0; _i < 2; ++_i) \
;         __builtin_amdgcn_global_load_lds((const GAS unsigned*)((const GAS char*)(gbase) + (size_t)_i * r64##voff + (vo##voff)), (LAS unsigned*)(lds + (bufoff) + ldsw + _i * 8192), 16, 0, 0); } while (0)
; #define PG8_LDA(dst, b, h) do { _Pragma("unroll") for (int m = 0; m < 4; ++m) _Pragma("unroll") for (int k = 0; k < 2; ++k) dst[m][k] = *(const LAS bf16x8*)(lds + PG8_SA(b, h) + aoff + m * 2048 + k * 1024); } while (0)
; #define PG8_LDB(dst, b, h) do { _Pragma("unroll") for (int n = 0; n < 2; ++n) _Pragma("unroll") for (int k = 0; k < 2; ++k) dst[n][k] = *(const LAS bf16x8*)(lds + PG8_SB(b, h) + boff + n * 2048 + k * 1024); } while (0)
; #define PG8_MMA(ai, bj, At, Bt) do { __builtin_amdgcn_s_setprio(1); _Pragma("unroll") for (int m = 0; m < 4; ++m) _Pragma("unroll") for (int n = 0; n < 2; ++n) _Pragma("unroll") for (int k = 0; k < 2; ++k) \
;         acc[ai][bj][m][n] = __builtin_amdgcn_mfma_f32_16x16x32_bf16(Bt[n][k], At[m][k], acc[ai][bj][m][n], 0, 0, 0); __builtin_amdgcn_s_setprio(0); } while (0)
; #define PG8_WAIT_V(n) asm volatile("s_waitcnt vmcnt(" #n ")" ::: "memory")
; #define PG8_WAIT_L(n) asm volatile("s_waitcnt lgkmcnt(" #n ")" ::: "memory")
; #define PG8_BAR __builtin_amdgcn_s_barrier()
; #define PG8_SCHED __builtin_amdgcn_sched_barrier(0)
; template <class Epi, class Map, bool ALIGN_EPI>
; __device__ __forceinline__ void gemm_phase(const int tid, LAS unsigned char* lds, const int lda, const int ldb, const int K, const Map& MP, const StaticOrder& S, const Epi& E) {
;     ...
;             PG8_LDB(B0, 0, 0); PG8_LDB(B1, 0, 1); PG8_SCHED; PG8_LDA(At, 0, 0); PG8_STAGE(PG8_SA(1, 1), a1 + hstepA, A);
;             PG8_WAIT_V(8); PG8_WAIT_L(0); PG8_BAR; PG8_MMA(0, 0, At, B0); PG8_MMA(0, 1, At, B1); PG8_BAR; PG8_SCHED;
;             PG8_LDA(At, 0, 1); PG8_STAGE(PG8_SB(0, 0), b2, B); PG8_STAGE(PG8_SB(0, 1), b2 + hstepB, B); PG8_STAGE(PG8_SA(0, 0), a2, A);
;             PG8_WAIT_V(8); PG8_WAIT_L(0); PG8_BAR; PG8_MMA(1, 0, At, B0); PG8_MMA(1, 1, At, B1); PG8_BAR; PG8_SCHED;
.LBB0_673:
	s_add_i32 s52, 0, 0x10000
	s_add_i32 s56, 0, 0x14000
	v_add_u32_e32 v202, s52, v130
	v_add_u32_e32 v203, s56, v130
	ds_read_b128 v[2:5], v202
	ds_read_b128 v[6:9], v202 offset:1024
	ds_read_b128 v[10:13], v202 offset:2048
	ds_read_b128 v[14:17], v202 offset:3072
	ds_read_b128 v[18:21], v203
	ds_read_b128 v[22:25], v203 offset:1024
	ds_read_b128 v[26:29], v203 offset:2048
	ds_read_b128 v[30:33], v203 offset:3072
	v_lshl_add_u64 v[0:1], s[48:49], 0, v[128:129]
	s_mov_b64 s[44:45], 0x10080
	s_add_i32 s48, s19, 0xc000
	v_lshl_add_u64 v[66:67], v[0:1], 0, s[44:45]
	s_mov_b32 m0, s48
	s_mov_b64 s[44:45], 0x18080
	s_add_i32 s17, s19, 0xe000
	ds_read_b128 v[34:37], v131
	ds_read_b128 v[38:41], v131 offset:1024
	ds_read_b128 v[42:45], v131 offset:2048
	ds_read_b128 v[46:49], v131 offset:3072
	ds_read_b128 v[50:53], v131 offset:4096
	ds_read_b128 v[54:57], v131 offset:5120
	ds_read_b128 v[58:61], v131 offset:6144
	ds_read_b128 v[62:65], v131 offset:7168
	global_load_lds_dwordx4 v[66:67], off
	v_lshl_add_u64 v[66:67], v[0:1], 0, s[44:45]
	s_mov_b32 m0, s17
	s_nop 0
	global_load_lds_dwordx4 v[66:67], off
	s_waitcnt vmcnt(8)
	s_waitcnt lgkmcnt(0)
	s_barrier
	s_setprio 1
	v_mfma_f32_16x16x32_bf16 v[66:69], v[2:5], v[34:37], 0
	v_mfma_f32_16x16x32_bf16 v[70:73], v[10:13], v[34:37], 0
	v_mfma_f32_16x16x32_bf16 v[74:77], v[2:5], v[42:45], 0
	v_mfma_f32_16x16x32_bf16 v[78:81], v[10:13], v[42:45], 0
	v_mfma_f32_16x16x32_bf16 v[82:85], v[2:5], v[50:53], 0
	v_mfma_f32_16x16x32_bf16 v[86:89], v[10:13], v[50:53], 0
	v_mfma_f32_16x16x32_bf16 v[90:93], v[2:5], v[58:61], 0
	v_mfma_f32_16x16x32_bf16 v[94:97], v[10:13], v[58:61], 0
	v_mfma_f32_16x16x32_bf16 v[66:69], v[6:9], v[38:41], v[66:69]
	v_mfma_f32_16x16x32_bf16 v[70:73], v[14:17], v[38:41], v[70:73]
	v_mfma_f32_16x16x32_bf16 v[74:77], v[6:9], v[46:49], v[74:77]
	v_mfma_f32_16x16x32_bf16 v[78:81], v[14:17], v[46:49], v[78:81]
	v_mfma_f32_16x16x32_bf16 v[82:85], v[6:9], v[54:57], v[82:85]
	v_mfma_f32_16x16x32_bf16 v[86:89], v[14:17], v[54:57], v[86:89]
	v_mfma_f32_16x16x32_bf16 v[90:93], v[6:9], v[62:65], v[90:93]
	v_mfma_f32_16x16x32_bf16 v[94:97], v[14:17], v[62:65], v[94:97]
	s_setprio 0
	s_setprio 1
	v_mfma_f32_16x16x32_bf16 v[98:101], v[18:21], v[34:37], 0
	v_mfma_f32_16x16x32_bf16 v[34:37], v[26:29], v[34:37], 0
	v_mfma_f32_16x16x32_bf16 v[98:101], v[22:25], v[38:41], v[98:101]
	v_mfma_f32_16x16x32_bf16 v[34:37], v[30:33], v[38:41], v[34:37]
	v_mfma_f32_16x16x32_bf16 v[38:41], v[18:21], v[42:45], 0
	v_mfma_f32_16x16x32_bf16 v[42:45], v[26:29], v[42:45], 0
	v_mfma_f32_16x16x32_bf16 v[38:41], v[22:25], v[46:49], v[38:41]
	v_mfma_f32_16x16x32_bf16 v[42:45], v[30:33], v[46:49], v[42:45]
	v_mfma_f32_16x16x32_bf16 v[46:49], v[18:21], v[50:53], 0
	v_mfma_f32_16x16x32_bf16 v[50:53], v[26:29], v[50:53], 0
	v_mfma_f32_16x16x32_bf16 v[46:49], v[22:25], v[54:57], v[46:49]
	v_mfma_f32_16x16x32_bf16 v[50:53], v[30:33], v[54:57], v[50:53]
	v_mfma_f32_16x16x32_bf16 v[54:57], v[18:21], v[58:61], 0
	v_mfma_f32_16x16x32_bf16 v[58:61], v[26:29], v[58:61], 0
	v_mfma_f32_16x16x32_bf16 v[54:57], v[22:25], v[62:65], v[54:57]
	v_mfma_f32_16x16x32_bf16 v[58:61], v[30:33], v[62:65], v[58:61]
	s_setprio 0
	s_barrier
	v_lshl_add_u64 v[126:127], s[46:47], 0, v[216:217]
	s_mov_b64 s[58:59], 0x100
	s_add_i32 s47, s52, s18
	v_lshl_add_u64 v[136:137], v[126:127], 0, s[58:59]
	s_mov_b32 m0, s47
	s_mov_b64 s[44:45], 0x20100
	ds_read_b128 v[62:65], v131 offset:16384
	ds_read_b128 v[102:105], v131 offset:17408
	ds_read_b128 v[106:109], v131 offset:18432
	ds_read_b128 v[110:113], v131 offset:19456
	ds_read_b128 v[114:117], v131 offset:20480
	ds_read_b128 v[118:121], v131 offset:21504
	ds_read_b128 v[122:125], v131 offset:22528
	ds_read_b128 v[132:135], v131 offset:23552
	global_load_lds_dwordx4 v[136:137], off
	v_lshl_add_u64 v[136:137], v[126:127], 0, s[44:45]
	s_add_i32 s44, s47, 0x2000
	s_mov_b32 m0, s44
	s_mov_b64 s[52:53], 0x40100
	s_add_i32 s45, s56, s18
	global_load_lds_dwordx4 v[136:137], off
	v_lshl_add_u64 v[136:137], v[126:127], 0, s[52:53]
	s_mov_b32 m0, s45
	s_mov_b64 s[52:53], 0x60100
	s_add_i32 s46, s45, 0x2000
	global_load_lds_dwordx4 v[136:137], off
	v_lshl_add_u64 v[136:137], v[126:127], 0, s[52:53]
	s_mov_b32 m0, s46
	s_mov_b64 s[52:53], 0x8100
	global_load_lds_dwordx4 v[136:137], off
	v_lshl_add_u64 v[136:137], v[0:1], 0, s[58:59]
	s_mov_b32 m0, s19
	s_nop 0
	global_load_lds_dwordx4 v[136:137], off
	v_lshl_add_u64 v[136:137], v[0:1], 0, s[52:53]
	s_mov_b32 m0, s24
	s_nop 0
	global_load_lds_dwordx4 v[136:137], off
	s_waitcnt vmcnt(8)
	s_waitcnt lgkmcnt(0)
	s_barrier
	s_setprio 1
	v_mfma_f32_16x16x32_bf16 v[136:139], v[2:5], v[62:65], 0
	v_mfma_f32_16x16x32_bf16 v[144:147], v[2:5], v[106:109], 0
	v_mfma_f32_16x16x32_bf16 v[152:155], v[2:5], v[114:117], 0
	v_mfma_f32_16x16x32_bf16 v[2:5], v[2:5], v[122:125], 0
	v_mfma_f32_16x16x32_bf16 v[136:139], v[6:9], v[102:105], v[136:139]
	v_mfma_f32_16x16x32_bf16 v[144:147], v[6:9], v[110:113], v[144:147]
	v_mfma_f32_16x16x32_bf16 v[152:155], v[6:9], v[118:121], v[152:155]
	v_mfma_f32_16x16x32_bf16 v[2:5], v[6:9], v[132:135], v[2:5]
	v_mfma_f32_16x16x32_bf16 v[6:9], v[10:13], v[122:125], 0
	v_mfma_f32_16x16x32_bf16 v[140:143], v[10:13], v[62:65], 0
	v_mfma_f32_16x16x32_bf16 v[148:151], v[10:13], v[106:109], 0
	v_mfma_f32_16x16x32_bf16 v[156:159], v[10:13], v[114:117], 0
	v_mfma_f32_16x16x32_bf16 v[6:9], v[14:17], v[132:135], v[6:9]
	v_mfma_f32_16x16x32_bf16 v[140:143], v[14:17], v[102:105], v[140:143]
	v_mfma_f32_16x16x32_bf16 v[148:151], v[14:17], v[110:113], v[148:151]
	v_mfma_f32_16x16x32_bf16 v[156:159], v[14:17], v[118:121], v[156:159]
	s_setprio 0
	s_setprio 1
	v_mfma_f32_16x16x32_bf16 v[10:13], v[18:21], v[62:65], 0
	v_mfma_f32_16x16x32_bf16 v[14:17], v[26:29], v[62:65], 0
	v_mfma_f32_16x16x32_bf16 v[10:13], v[22:25], v[102:105], v[10:13]
	v_mfma_f32_16x16x32_bf16 v[14:17], v[30:33], v[102:105], v[14:17]
	v_mfma_f32_16x16x32_bf16 v[62:65], v[18:21], v[106:109], 0
	v_mfma_f32_16x16x32_bf16 v[102:105], v[26:29], v[106:109], 0
	v_mfma_f32_16x16x32_bf16 v[106:109], v[18:21], v[114:117], 0
	v_mfma_f32_16x16x32_bf16 v[18:21], v[18:21], v[122:125], 0
	v_mfma_f32_16x16x32_bf16 v[62:65], v[22:25], v[110:113], v[62:65]
	v_mfma_f32_16x16x32_bf16 v[102:105], v[30:33], v[110:113], v[102:105]
	v_mfma_f32_16x16x32_bf16 v[106:109], v[22:25], v[118:121], v[106:109]
	v_mfma_f32_16x16x32_bf16 v[110:113], v[26:29], v[114:117], 0
	v_mfma_f32_16x16x32_bf16 v[18:21], v[22:25], v[132:135], v[18:21]
	v_mfma_f32_16x16x32_bf16 v[22:25], v[26:29], v[122:125], 0
	v_mfma_f32_16x16x32_bf16 v[110:113], v[30:33], v[118:121], v[110:113]
	v_mfma_f32_16x16x32_bf16 v[22:25], v[30:33], v[132:135], v[22:25]
	s_setprio 0
	s_barrier
; #define PG8_STAGE(bufoff, gbase, voff) do { _Pragma("unroll") for (int _i = 0; _i < 2; ++_i) \
;         __builtin_amdgcn_global_load_lds((const GAS unsigned*)((const GAS char*)(gbase) + (size_t)_i * r64##voff + (vo##voff)), (LAS unsigned*)(lds + (bufoff) + ldsw + _i * 8192), 16, 0, 0); } while (0)
; #define PG8_LDA(dst, b, h) do { _Pragma("unroll") for (int m = 0; m < 4; ++m) _Pragma("unroll") for (int k = 0; k < 2; ++k) dst[m][k] = *(const LAS bf16x8*)(lds + PG8_SA(b, h) + aoff + m * 2048 + k * 1024); } while (0)
; #define PG8_LDB(dst, b, h) do { _Pragma("unroll") for (int n = 0; n < 2; ++n) _Pragma("unroll") for (int k = 0; k < 2; ++k) dst[n][k] = *(const LAS bf16x8*)(lds + PG8_SB(b, h) + boff + n * 2048 + k * 1024); } while (0)
; #define PG8_MMA(ai, bj, At, Bt) do { __builtin_amdgcn_s_setprio(1); _Pragma("unroll") for (int m = 0; m < 4; ++m) _Pragma("unroll") for (int n = 0; n < 2; ++n) _Pragma("unroll") for (int k = 0; k < 2; ++k) \
;         acc[ai][bj][m][n] = __builtin_amdgcn_mfma_f32_16x16x32_bf16(Bt[n][k], At[m][k], acc[ai][bj][m][n], 0, 0, 0); __builtin_amdgcn_s_setprio(0); } while (0)
; #define PG8_WAIT_V(n) asm volatile("s_waitcnt vmcnt(" #n ")" ::: "memory")
; #define PG8_WAIT_L(n) asm volatile("s_waitcnt lgkmcnt(" #n ")" ::: "memory")
; #define PG8_BAR __builtin_amdgcn_s_barrier()
; #define PG8_SCHED __builtin_amdgcn_sched_barrier(0)
; template <class Epi, class Map, bool ALIGN_EPI>
; __device__ __forceinline__ void gemm_phase(const int tid, LAS unsigned char* lds, const int lda, const int ldb, const int K, const Map& MP, const StaticOrder& S, const Epi& E) {
;     ...
;             PG8_LDB(B0, 1, 0); PG8_LDB(B1, 1, 1); PG8_SCHED; PG8_LDA(At, 1, 0); PG8_STAGE(PG8_SA(0, 1), a2 + hstepA, A);
;             PG8_WAIT_V(8); PG8_WAIT_L(0); PG8_BAR; PG8_MMA(0, 0, At, B0); PG8_MMA(0, 1, At, B1); PG8_BAR; PG8_SCHED;
;             PG8_LDA(At, 1, 1); PG8_STAGE(PG8_SB(1, 0), b3, B); PG8_STAGE(PG8_SB(1, 1), b3 + hstepB, B); PG8_STAGE(PG8_SA(1, 0), a3, A);
;             PG8_WAIT_V(8); PG8_WAIT_L(0); PG8_BAR; PG8_MMA(1, 0, At, B0); PG8_MMA(1, 1, At, B1); PG8_BAR; PG8_SCHED;
	s_add_i32 s56, 0, 0x18000
	s_add_i32 s57, 0, 0x1c000
	v_add_u32_e32 v218, s56, v130
	v_add_u32_e32 v219, s57, v130
	ds_read_b128 v[26:29], v218
	ds_read_b128 v[30:33], v218 offset:1024
	ds_read_b128 v[114:117], v218 offset:2048
	ds_read_b128 v[118:121], v218 offset:3072
	ds_read_b128 v[122:125], v219
	ds_read_b128 v[132:135], v219 offset:1024
	ds_read_b128 v[160:163], v219 offset:2048
	ds_read_b128 v[164:167], v219 offset:3072
	s_mov_b64 s[52:53], 0x10100
	s_mov_b32 m0, s28
	v_lshl_add_u64 v[200:201], v[0:1], 0, s[52:53]
	s_mov_b64 s[52:53], 0x18100
	ds_read_b128 v[168:171], v131 offset:32768
	ds_read_b128 v[172:175], v131 offset:33792
	ds_read_b128 v[176:179], v131 offset:34816
	ds_read_b128 v[180:183], v131 offset:35840
	ds_read_b128 v[184:187], v131 offset:36864
	ds_read_b128 v[188:191], v131 offset:37888
	ds_read_b128 v[192:195], v131 offset:38912
	ds_read_b128 v[196:199], v131 offset:39936
	global_load_lds_dwordx4 v[200:201], off
	v_lshl_add_u64 v[200:201], v[0:1], 0, s[52:53]
	s_mov_b32 m0, s29
	s_nop 0
	global_load_lds_dwordx4 v[200:201], off
	s_waitcnt vmcnt(8)
	s_waitcnt lgkmcnt(0)
	s_barrier
	s_setprio 1
	v_mfma_f32_16x16x32_bf16 v[66:69], v[26:29], v[168:171], v[66:69]
	v_mfma_f32_16x16x32_bf16 v[70:73], v[114:117], v[168:171], v[70:73]
	v_mfma_f32_16x16x32_bf16 v[74:77], v[26:29], v[176:179], v[74:77]
	v_mfma_f32_16x16x32_bf16 v[78:81], v[114:117], v[176:179], v[78:81]
	v_mfma_f32_16x16x32_bf16 v[82:85], v[26:29], v[184:187], v[82:85]
	v_mfma_f32_16x16x32_bf16 v[86:89], v[114:117], v[184:187], v[86:89]
	v_mfma_f32_16x16x32_bf16 v[90:93], v[26:29], v[192:195], v[90:93]
	v_mfma_f32_16x16x32_bf16 v[94:97], v[114:117], v[192:195], v[94:97]
	v_mfma_f32_16x16x32_bf16 v[66:69], v[30:33], v[172:175], v[66:69]
	v_mfma_f32_16x16x32_bf16 v[70:73], v[118:121], v[172:175], v[70:73]
	v_mfma_f32_16x16x32_bf16 v[74:77], v[30:33], v[180:183], v[74:77]
	v_mfma_f32_16x16x32_bf16 v[78:81], v[118:121], v[180:183], v[78:81]
	v_mfma_f32_16x16x32_bf16 v[82:85], v[30:33], v[188:191], v[82:85]
	v_mfma_f32_16x16x32_bf16 v[86:89], v[118:121], v[188:191], v[86:89]
	v_mfma_f32_16x16x32_bf16 v[90:93], v[30:33], v[196:199], v[90:93]
	v_mfma_f32_16x16x32_bf16 v[94:97], v[118:121], v[196:199], v[94:97]
	s_setprio 0
	s_setprio 1
	v_mfma_f32_16x16x32_bf16 v[98:101], v[122:125], v[168:171], v[98:101]
	v_mfma_f32_16x16x32_bf16 v[34:37], v[160:163], v[168:171], v[34:37]
	v_mfma_f32_16x16x32_bf16 v[38:41], v[122:125], v[176:179], v[38:41]
	v_mfma_f32_16x16x32_bf16 v[42:45], v[160:163], v[176:179], v[42:45]
	v_mfma_f32_16x16x32_bf16 v[46:49], v[122:125], v[184:187], v[46:49]
	v_mfma_f32_16x16x32_bf16 v[50:53], v[160:163], v[184:187], v[50:53]
	v_mfma_f32_16x16x32_bf16 v[54:57], v[122:125], v[192:195], v[54:57]
	v_mfma_f32_16x16x32_bf16 v[58:61], v[160:163], v[192:195], v[58:61]
	v_mfma_f32_16x16x32_bf16 v[98:101], v[132:135], v[172:175], v[98:101]
	v_mfma_f32_16x16x32_bf16 v[34:37], v[164:167], v[172:175], v[34:37]
	v_mfma_f32_16x16x32_bf16 v[38:41], v[132:135], v[180:183], v[38:41]
	v_mfma_f32_16x16x32_bf16 v[42:45], v[164:167], v[180:183], v[42:45]
	v_mfma_f32_16x16x32_bf16 v[46:49], v[132:135], v[188:191], v[46:49]
	v_mfma_f32_16x16x32_bf16 v[50:53], v[164:167], v[188:191], v[50:53]
	v_mfma_f32_16x16x32_bf16 v[54:57], v[132:135], v[196:199], v[54:57]
	v_mfma_f32_16x16x32_bf16 v[58:61], v[164:167], v[196:199], v[58:61]
	s_setprio 0
	s_barrier
	s_mov_b64 s[62:63], 0x180
	s_add_i32 s56, s56, s18
	v_lshl_add_u64 v[200:201], v[126:127], 0, s[62:63]
	s_mov_b32 m0, s56
	s_mov_b64 s[52:53], 0x20180
	s_add_i32 s49, s56, 0x2000
	ds_read_b128 v[168:171], v131 offset:49152
	ds_read_b128 v[172:175], v131 offset:50176
	ds_read_b128 v[176:179], v131 offset:51200
	ds_read_b128 v[180:183], v131 offset:52224
	ds_read_b128 v[184:187], v131 offset:53248
	ds_read_b128 v[188:191], v131 offset:54272
	ds_read_b128 v[192:195], v131 offset:55296
	ds_read_b128 v[196:199], v131 offset:56320
	global_load_lds_dwordx4 v[200:201], off
	v_lshl_add_u64 v[200:201], v[126:127], 0, s[52:53]
	s_mov_b32 m0, s49
	s_mov_b64 s[52:53], 0x40180
	global_load_lds_dwordx4 v[200:201], off
	v_lshl_add_u64 v[200:201], v[126:127], 0, s[52:53]
	s_add_i32 s52, s57, s18
	s_mov_b32 m0, s52
	s_mov_b64 s[58:59], 0x60180
	s_add_i32 s53, s52, 0x2000
	global_load_lds_dwordx4 v[200:201], off
	v_lshl_add_u64 v[126:127], v[126:127], 0, s[58:59]
	s_mov_b32 m0, s53
	s_mov_b64 s[58:59], 0x8180
	global_load_lds_dwordx4 v[126:127], off
	v_lshl_add_u64 v[126:127], v[0:1], 0, s[62:63]
	s_mov_b32 m0, s33
	s_nop 0
	global_load_lds_dwordx4 v[126:127], off
	v_lshl_add_u64 v[126:127], v[0:1], 0, s[58:59]
	s_mov_b32 m0, s34
	s_nop 0
	global_load_lds_dwordx4 v[126:127], off
	s_waitcnt vmcnt(8)
	s_waitcnt lgkmcnt(0)
	s_barrier
; #define PG8_STAGE(bufoff, gbase, voff) do { _Pragma("unroll") for (int _i = 0; _i < 2; ++_i) \
;         __builtin_amdgcn_global_load_lds((const GAS unsigned*)((const GAS char*)(gbase) + (size_t)_i * r64##voff + (vo##voff)), (LAS unsigned*)(lds + (bufoff) + ldsw + _i * 8192), 16, 0, 0); } while (0)
; #define PG8_LDA(dst, b, h) do { _Pragma("unroll") for (int m = 0; m < 4; ++m) _Pragma("unroll") for (int k = 0; k < 2; ++k) dst[m][k] = *(const LAS bf16x8*)(lds + PG8_SA(b, h) + aoff + m * 2048 + k * 1024); } while (0)
; #define PG8_LDB(dst, b, h) do { _Pragma("unroll") for (int n = 0; n < 2; ++n) _Pragma("unroll") for (int k = 0; k < 2; ++k) dst[n][k] = *(const LAS bf16x8*)(lds + PG8_SB(b, h) + boff + n * 2048 + k * 1024); } while (0)
; #define PG8_MMA(ai, bj, At, Bt) do { __builtin_amdgcn_s_setprio(1); _Pragma("unroll") for (int m = 0; m < 4; ++m) _Pragma("unroll") for (int n = 0; n < 2; ++n) _Pragma("unroll") for (int k = 0; k < 2; ++k) \
;         acc[ai][bj][m][n] = __builtin_amdgcn_mfma_f32_16x16x32_bf16(Bt[n][k], At[m][k], acc[ai][bj][m][n], 0, 0, 0); __builtin_amdgcn_s_setprio(0); } while (0)
; #define PG8_WAIT_V(n) asm volatile("s_waitcnt vmcnt(" #n ")" ::: "memory")
; #define PG8_WAIT_L(n) asm volatile("s_waitcnt lgkmcnt(" #n ")" ::: "memory")
; #define PG8_BAR __builtin_amdgcn_s_barrier()
; #define PG8_SCHED __builtin_amdgcn_sched_barrier(0)
; template <class Epi, class Map, bool ALIGN_EPI>
; __device__ __forceinline__ void gemm_phase(const int tid, LAS unsigned char* lds, const int lda, const int ldb, const int K, const Map& MP, const StaticOrder& S, const Epi& E) {
;     ...
;             PG8_LDB(B0, 0, 0); PG8_LDB(B1, 0, 1); PG8_SCHED; PG8_LDA(At, 0, 0); PG8_STAGE(PG8_SA(1, 1), a1 + hstepA, A);
;             PG8_WAIT_V(8); PG8_WAIT_L(0); PG8_BAR; PG8_MMA(0, 0, At, B0); PG8_MMA(0, 1, At, B1); PG8_BAR; PG8_SCHED;
;             PG8_LDA(At, 0, 1); PG8_STAGE(PG8_SB(0, 0), b2, B); PG8_STAGE(PG8_SB(0, 1), b2 + hstepB, B); PG8_STAGE(PG8_SA(0, 0), a2, A);
;             PG8_WAIT_V(8); PG8_WAIT_L(0); PG8_BAR; PG8_MMA(1, 0, At, B0); PG8_MMA(1, 1, At, B1); PG8_BAR; PG8_SCHED;
;     ...
;             PG8_WAIT_V(8); PG8_WAIT_L(0); PG8_BAR; PG8_MMA(1, 0, At, B0); PG8_MMA(1, 1, At, B1); PG8_BAR; PG8_SCHED;
	s_setprio 1
	v_mfma_f32_16x16x32_bf16 v[2:5], v[26:29], v[192:195], v[2:5]
	v_mfma_f32_16x16x32_bf16 v[6:9], v[114:117], v[192:195], v[6:9]
	v_mfma_f32_16x16x32_bf16 v[136:139], v[26:29], v[168:171], v[136:139]
	v_mfma_f32_16x16x32_bf16 v[140:143], v[114:117], v[168:171], v[140:143]
	v_mfma_f32_16x16x32_bf16 v[144:147], v[26:29], v[176:179], v[144:147]
	v_mfma_f32_16x16x32_bf16 v[148:151], v[114:117], v[176:179], v[148:151]
	v_mfma_f32_16x16x32_bf16 v[152:155], v[26:29], v[184:187], v[152:155]
	v_mfma_f32_16x16x32_bf16 v[156:159], v[114:117], v[184:187], v[156:159]
	v_mfma_f32_16x16x32_bf16 v[2:5], v[30:33], v[196:199], v[2:5]
	v_mfma_f32_16x16x32_bf16 v[6:9], v[118:121], v[196:199], v[6:9]
	v_mfma_f32_16x16x32_bf16 v[136:139], v[30:33], v[172:175], v[136:139]
	v_mfma_f32_16x16x32_bf16 v[140:143], v[118:121], v[172:175], v[140:143]
	v_mfma_f32_16x16x32_bf16 v[144:147], v[30:33], v[180:183], v[144:147]
	v_mfma_f32_16x16x32_bf16 v[148:151], v[118:121], v[180:183], v[148:151]
	v_mfma_f32_16x16x32_bf16 v[152:155], v[30:33], v[188:191], v[152:155]
	v_mfma_f32_16x16x32_bf16 v[156:159], v[118:121], v[188:191], v[156:159]
	s_setprio 0
	s_setprio 1
	v_mfma_f32_16x16x32_bf16 v[10:13], v[122:125], v[168:171], v[10:13]
	v_mfma_f32_16x16x32_bf16 v[14:17], v[160:163], v[168:171], v[14:17]
	v_mfma_f32_16x16x32_bf16 v[26:29], v[122:125], v[176:179], v[62:65]
	v_mfma_f32_16x16x32_bf16 v[30:33], v[160:163], v[176:179], v[102:105]
	v_mfma_f32_16x16x32_bf16 v[62:65], v[122:125], v[184:187], v[106:109]
	v_mfma_f32_16x16x32_bf16 v[102:105], v[160:163], v[184:187], v[110:113]
	v_mfma_f32_16x16x32_bf16 v[18:21], v[122:125], v[192:195], v[18:21]
	v_mfma_f32_16x16x32_bf16 v[22:25], v[160:163], v[192:195], v[22:25]
	v_mfma_f32_16x16x32_bf16 v[10:13], v[132:135], v[172:175], v[10:13]
	v_mfma_f32_16x16x32_bf16 v[14:17], v[164:167], v[172:175], v[14:17]
	v_mfma_f32_16x16x32_bf16 v[26:29], v[132:135], v[180:183], v[26:29]
	v_mfma_f32_16x16x32_bf16 v[30:33], v[164:167], v[180:183], v[30:33]
	v_mfma_f32_16x16x32_bf16 v[62:65], v[132:135], v[188:191], v[62:65]
	v_mfma_f32_16x16x32_bf16 v[102:105], v[164:167], v[188:191], v[102:105]
	v_mfma_f32_16x16x32_bf16 v[18:21], v[132:135], v[196:199], v[18:21]
	v_mfma_f32_16x16x32_bf16 v[22:25], v[164:167], v[196:199], v[22:25]
	s_setprio 0
	s_barrier
	ds_read_b128 v[106:109], v202
	ds_read_b128 v[110:113], v202 offset:1024
	ds_read_b128 v[114:117], v202 offset:2048
	ds_read_b128 v[118:121], v202 offset:3072
	ds_read_b128 v[122:125], v203
	ds_read_b128 v[132:135], v203 offset:1024
	ds_read_b128 v[160:163], v203 offset:2048
	ds_read_b128 v[164:167], v203 offset:3072
	s_mov_b64 s[58:59], 0x10180
	s_mov_b32 m0, s48
	v_lshl_add_u64 v[126:127], v[0:1], 0, s[58:59]
	s_mov_b64 s[58:59], 0x18180
	ds_read_b128 v[168:171], v131
	ds_read_b128 v[172:175], v131 offset:1024
	ds_read_b128 v[176:179], v131 offset:2048
	ds_read_b128 v[180:183], v131 offset:3072
	ds_read_b128 v[184:187], v131 offset:4096
	ds_read_b128 v[188:191], v131 offset:5120
	ds_read_b128 v[192:195], v131 offset:6144
	ds_read_b128 v[196:199], v131 offset:7168
	global_load_lds_dwordx4 v[126:127], off
	v_lshl_add_u64 v[0:1], v[0:1], 0, s[58:59]
	s_mov_b32 m0, s17
	s_nop 0
	global_load_lds_dwordx4 v[0:1], off
	s_waitcnt vmcnt(8)
	s_waitcnt lgkmcnt(0)
	s_barrier
	s_setprio 1
	v_mfma_f32_16x16x32_bf16 v[66:69], v[106:109], v[168:171], v[66:69]
	v_mfma_f32_16x16x32_bf16 v[70:73], v[114:117], v[168:171], v[70:73]
	v_mfma_f32_16x16x32_bf16 v[74:77], v[106:109], v[176:179], v[74:77]
	v_mfma_f32_16x16x32_bf16 v[78:81], v[114:117], v[176:179], v[78:81]
	v_mfma_f32_16x16x32_bf16 v[82:85], v[106:109], v[184:187], v[82:85]
	v_mfma_f32_16x16x32_bf16 v[86:89], v[114:117], v[184:187], v[86:89]
	v_mfma_f32_16x16x32_bf16 v[90:93], v[106:109], v[192:195], v[90:93]
	v_mfma_f32_16x16x32_bf16 v[66:69], v[110:113], v[172:175], v[66:69]
	v_mfma_f32_16x16x32_bf16 v[70:73], v[118:121], v[172:175], v[70:73]
	v_mfma_f32_16x16x32_bf16 v[74:77], v[110:113], v[180:183], v[74:77]
	v_mfma_f32_16x16x32_bf16 v[78:81], v[118:121], v[180:183], v[78:81]
	v_mfma_f32_16x16x32_bf16 v[82:85], v[110:113], v[188:191], v[82:85]
	v_mfma_f32_16x16x32_bf16 v[86:89], v[118:121], v[188:191], v[86:89]
	v_mfma_f32_16x16x32_bf16 v[200:203], v[110:113], v[196:199], v[90:93]
	v_mfma_f32_16x16x32_bf16 v[90:93], v[114:117], v[192:195], v[94:97]
	v_mfma_f32_16x16x32_bf16 v[204:207], v[118:121], v[196:199], v[90:93]
	s_setprio 0
	s_setprio 1
	v_mfma_f32_16x16x32_bf16 v[90:93], v[122:125], v[168:171], v[98:101]
	v_mfma_f32_16x16x32_bf16 v[34:37], v[160:163], v[168:171], v[34:37]
	v_mfma_f32_16x16x32_bf16 v[38:41], v[122:125], v[176:179], v[38:41]
	v_mfma_f32_16x16x32_bf16 v[42:45], v[160:163], v[176:179], v[42:45]
	v_mfma_f32_16x16x32_bf16 v[46:49], v[122:125], v[184:187], v[46:49]
	v_mfma_f32_16x16x32_bf16 v[50:53], v[160:163], v[184:187], v[50:53]
	v_mfma_f32_16x16x32_bf16 v[54:57], v[122:125], v[192:195], v[54:57]
	v_mfma_f32_16x16x32_bf16 v[96:99], v[132:135], v[172:175], v[90:93]
	v_mfma_f32_16x16x32_bf16 v[34:37], v[164:167], v[172:175], v[34:37]
	v_mfma_f32_16x16x32_bf16 v[38:41], v[132:135], v[180:183], v[38:41]
	v_mfma_f32_16x16x32_bf16 v[42:45], v[164:167], v[180:183], v[42:45]
	v_mfma_f32_16x16x32_bf16 v[46:49], v[132:135], v[188:191], v[46:49]
	v_mfma_f32_16x16x32_bf16 v[50:53], v[164:167], v[188:191], v[50:53]
	v_mfma_f32_16x16x32_bf16 v[54:57], v[132:135], v[196:199], v[54:57]
	v_mfma_f32_16x16x32_bf16 v[58:61], v[160:163], v[192:195], v[58:61]
	v_mfma_f32_16x16x32_bf16 v[168:171], v[164:167], v[196:199], v[58:61]
	s_setprio 0
	s_barrier
; #define PG8_STAGE(bufoff, gbase, voff) do { _Pragma("unroll") for (int _i = 0; _i < 2; ++_i) \
;         __builtin_amdgcn_global_load_lds((const GAS unsigned*)((const GAS char*)(gbase) + (size_t)_i * r64##voff + (vo##voff)), (LAS unsigned*)(lds + (bufoff) + ldsw + _i * 8192), 16, 0, 0); } while (0)
; #define PG8_LDA(dst, b, h) do { _Pragma("unroll") for (int m = 0; m < 4; ++m) _Pragma("unroll") for (int k = 0; k < 2; ++k) dst[m][k] = *(const LAS bf16x8*)(lds + PG8_SA(b, h) + aoff + m * 2048 + k * 1024); } while (0)
; #define PG8_LDB(dst, b, h) do { _Pragma("unroll") for (int n = 0; n < 2; ++n) _Pragma("unroll") for (int k = 0; k < 2; ++k) dst[n][k] = *(const LAS bf16x8*)(lds + PG8_SB(b, h) + boff + n * 2048 + k * 1024); } while (0)
; #define PG8_MMA(ai, bj, At, Bt) do { __builtin_amdgcn_s_setprio(1); _Pragma("unroll") for (int m = 0; m < 4; ++m) _Pragma("unroll") for (int n = 0; n < 2; ++n) _Pragma("unroll") for (int k = 0; k < 2; ++k) \
;         acc[ai][bj][m][n] = __builtin_amdgcn_mfma_f32_16x16x32_bf16(Bt[n][k], At[m][k], acc[ai][bj][m][n], 0, 0, 0); __builtin_amdgcn_s_setprio(0); } while (0)
; #define PG8_WAIT_V(n) asm volatile("s_waitcnt vmcnt(" #n ")" ::: "memory")
; #define PG8_WAIT_L(n) asm volatile("s_waitcnt lgkmcnt(" #n ")" ::: "memory")
; #define PG8_BAR __builtin_amdgcn_s_barrier()
; #define PG8_SCHED __builtin_amdgcn_sched_barrier(0)
; template <class Epi, class Map, bool ALIGN_EPI>
; __device__ __forceinline__ void gemm_phase(const int tid, LAS unsigned char* lds, const int lda, const int ldb, const int K, const Map& MP, const StaticOrder& S, const Epi& E) {
;     ...
;             PG8_LDA(At, 0, 1); PG8_STAGE(PG8_SB(0, 0), b2, B); PG8_STAGE(PG8_SB(0, 1), b2 + hstepB, B); PG8_STAGE(PG8_SA(0, 0), a2, A);
;             PG8_WAIT_V(8); PG8_WAIT_L(0); PG8_BAR; PG8_MMA(1, 0, At, B0); PG8_MMA(1, 1, At, B1); PG8_BAR; PG8_SCHED;
;             PG8_LDB(B0, 1, 0); PG8_LDB(B1, 1, 1); PG8_SCHED; PG8_LDA(At, 1, 0); PG8_STAGE(PG8_SA(0, 1), a2 + hstepA, A);
;             PG8_WAIT_V(8); PG8_WAIT_L(0); PG8_BAR; PG8_MMA(0, 0, At, B0); PG8_MMA(0, 1, At, B1); PG8_BAR; PG8_SCHED;
	s_mov_b32 m0, s47
	v_lshl_add_u64 v[230:231], s[22:23], 0, v[216:217]
	s_nop 2
	ds_read_b128 v[58:61], v131 offset:16384
	ds_read_b128 v[90:93], v131 offset:17408
	ds_read_b128 v[172:175], v131 offset:18432
	ds_read_b128 v[176:179], v131 offset:19456
	ds_read_b128 v[180:183], v131 offset:20480
	ds_read_b128 v[184:187], v131 offset:21504
	ds_read_b128 v[188:191], v131 offset:22528
	ds_read_b128 v[192:195], v131 offset:23552
	global_load_lds_dwordx4 v[230:231], off
	v_lshl_add_u64 v[0:1], v[230:231], 0, s[90:91]
	s_mov_b32 m0, s44
	v_lshl_add_u64 v[222:223], s[20:21], 0, v[128:129]
	global_load_lds_dwordx4 v[0:1], off
	v_lshl_add_u64 v[0:1], v[230:231], 0, s[74:75]
	s_mov_b32 m0, s45
	s_mov_b64 s[44:45], 0x8000
	global_load_lds_dwordx4 v[0:1], off
	v_lshl_add_u64 v[0:1], v[230:231], 0, s[94:95]
	s_mov_b32 m0, s46
	s_nop 0
	global_load_lds_dwordx4 v[0:1], off
	s_mov_b32 m0, s19
	v_lshl_add_u64 v[0:1], v[222:223], 0, s[44:45]
	global_load_lds_dwordx4 v[222:223], off
	s_mov_b32 m0, s24
	s_nop 0
	global_load_lds_dwordx4 v[0:1], off
	s_waitcnt vmcnt(8)
	s_waitcnt lgkmcnt(0)
	s_barrier
	s_setprio 1
	v_mfma_f32_16x16x32_bf16 v[0:3], v[106:109], v[188:191], v[2:5]
	v_mfma_f32_16x16x32_bf16 v[4:7], v[114:117], v[188:191], v[6:9]
	v_mfma_f32_16x16x32_bf16 v[136:139], v[106:109], v[58:61], v[136:139]
	v_mfma_f32_16x16x32_bf16 v[140:143], v[114:117], v[58:61], v[140:143]
	v_mfma_f32_16x16x32_bf16 v[144:147], v[106:109], v[172:175], v[144:147]
	v_mfma_f32_16x16x32_bf16 v[148:151], v[114:117], v[172:175], v[148:151]
	v_mfma_f32_16x16x32_bf16 v[152:155], v[106:109], v[180:183], v[152:155]
	v_mfma_f32_16x16x32_bf16 v[156:159], v[114:117], v[180:183], v[156:159]
	v_mfma_f32_16x16x32_bf16 v[0:3], v[110:113], v[192:195], v[0:3]
	v_mfma_f32_16x16x32_bf16 v[4:7], v[118:121], v[192:195], v[4:7]
	v_mfma_f32_16x16x32_bf16 v[136:139], v[110:113], v[90:93], v[136:139]
	v_mfma_f32_16x16x32_bf16 v[140:143], v[118:121], v[90:93], v[140:143]
	v_mfma_f32_16x16x32_bf16 v[144:147], v[110:113], v[176:179], v[144:147]
	v_mfma_f32_16x16x32_bf16 v[148:151], v[118:121], v[176:179], v[148:151]
	v_mfma_f32_16x16x32_bf16 v[152:155], v[110:113], v[184:187], v[152:155]
	v_mfma_f32_16x16x32_bf16 v[156:159], v[118:121], v[184:187], v[156:159]
	s_setprio 0
	s_setprio 1
	v_mfma_f32_16x16x32_bf16 v[8:11], v[122:125], v[58:61], v[10:13]
	v_mfma_f32_16x16x32_bf16 v[196:199], v[132:135], v[90:93], v[8:11]
	v_mfma_f32_16x16x32_bf16 v[8:11], v[160:163], v[58:61], v[14:17]
	v_mfma_f32_16x16x32_bf16 v[208:211], v[164:167], v[90:93], v[8:11]
	v_mfma_f32_16x16x32_bf16 v[8:11], v[122:125], v[172:175], v[26:29]
	v_mfma_f32_16x16x32_bf16 v[212:215], v[132:135], v[176:179], v[8:11]
	v_mfma_f32_16x16x32_bf16 v[8:11], v[160:163], v[172:175], v[30:33]
	v_mfma_f32_16x16x32_bf16 v[172:175], v[164:167], v[176:179], v[8:11]
	v_mfma_f32_16x16x32_bf16 v[8:11], v[122:125], v[180:183], v[62:65]
	v_mfma_f32_16x16x32_bf16 v[176:179], v[132:135], v[184:187], v[8:11]
	v_mfma_f32_16x16x32_bf16 v[8:11], v[160:163], v[180:183], v[102:105]
	v_mfma_f32_16x16x32_bf16 v[180:183], v[164:167], v[184:187], v[8:11]
	v_mfma_f32_16x16x32_bf16 v[8:11], v[122:125], v[188:191], v[18:21]
	v_mfma_f32_16x16x32_bf16 v[132:135], v[132:135], v[192:195], v[8:11]
	v_mfma_f32_16x16x32_bf16 v[8:11], v[160:163], v[188:191], v[22:25]
	v_mfma_f32_16x16x32_bf16 v[160:163], v[164:167], v[192:195], v[8:11]
	s_setprio 0
	s_barrier
	s_nop 4
	ds_read_b128 v[8:11], v218
	ds_read_b128 v[12:15], v218 offset:1024
	ds_read_b128 v[16:19], v218 offset:2048
	ds_read_b128 v[20:23], v218 offset:3072
	ds_read_b128 v[164:167], v219
	ds_read_b128 v[184:187], v219 offset:1024
	ds_read_b128 v[188:191], v219 offset:2048
	ds_read_b128 v[192:195], v219 offset:3072
	s_mov_b64 s[44:45], 0x10000
	s_mov_b32 m0, s28
	v_lshl_add_u64 v[32:33], v[222:223], 0, s[44:45]
	s_mov_b64 s[44:45], 0x18000
	ds_read_b128 v[24:27], v131 offset:32768
	ds_read_b128 v[28:31], v131 offset:33792
	ds_read_b128 v[240:243], v131 offset:34816
	ds_read_b128 v[244:247], v131 offset:35840
	ds_read_b128 v[248:251], v131 offset:36864
	ds_read_b128 v[218:221], v131 offset:37888
	ds_read_b128 v[226:229], v131 offset:38912
	ds_read_b128 v[236:239], v131 offset:39936
	global_load_lds_dwordx4 v[32:33], off
	v_lshl_add_u64 v[32:33], v[222:223], 0, s[44:45]
	s_mov_b32 m0, s29
	s_nop 0
	global_load_lds_dwordx4 v[32:33], off
	s_waitcnt vmcnt(8)
	s_waitcnt lgkmcnt(0)
	s_barrier
; #define PG8_STAGE(bufoff, gbase, voff) do { _Pragma("unroll") for (int _i = 0; _i < 2; ++_i) \
;         __builtin_amdgcn_global_load_lds((const GAS unsigned*)((const GAS char*)(gbase) + (size_t)_i * r64##voff + (vo##voff)), (LAS unsigned*)(lds + (bufoff) + ldsw + _i * 8192), 16, 0, 0); } while (0)
; #define PG8_LDA(dst, b, h) do { _Pragma("unroll") for (int m = 0; m < 4; ++m) _Pragma("unroll") for (int k = 0; k < 2; ++k) dst[m][k] = *(const LAS bf16x8*)(lds + PG8_SA(b, h) + aoff + m * 2048 + k * 1024); } while (0)
; #define PG8_LDB(dst, b, h) do { _Pragma("unroll") for (int n = 0; n < 2; ++n) _Pragma("unroll") for (int k = 0; k < 2; ++k) dst[n][k] = *(const LAS bf16x8*)(lds + PG8_SB(b, h) + boff + n * 2048 + k * 1024); } while (0)
; #define PG8_MMA(ai, bj, At, Bt) do { __builtin_amdgcn_s_setprio(1); _Pragma("unroll") for (int m = 0; m < 4; ++m) _Pragma("unroll") for (int n = 0; n < 2; ++n) _Pragma("unroll") for (int k = 0; k < 2; ++k) \
;         acc[ai][bj][m][n] = __builtin_amdgcn_mfma_f32_16x16x32_bf16(Bt[n][k], At[m][k], acc[ai][bj][m][n], 0, 0, 0); __builtin_amdgcn_s_setprio(0); } while (0)
; #define PG8_WAIT_V(n) asm volatile("s_waitcnt vmcnt(" #n ")" ::: "memory")
; #define PG8_WAIT_L(n) asm volatile("s_waitcnt lgkmcnt(" #n ")" ::: "memory")
; #define PG8_BAR __builtin_amdgcn_s_barrier()
; #define PG8_SCHED __builtin_amdgcn_sched_barrier(0)
; template <class Epi, class Map, bool ALIGN_EPI>
; __device__ __forceinline__ void gemm_phase(const int tid, LAS unsigned char* lds, const int lda, const int ldb, const int K, const Map& MP, const StaticOrder& S, const Epi& E) {
;     ...
;             PG8_LDB(B0, 1, 0); PG8_LDB(B1, 1, 1); PG8_SCHED; PG8_LDA(At, 1, 0); PG8_STAGE(PG8_SA(0, 1), a2 + hstepA, A);
;             PG8_WAIT_V(8); PG8_WAIT_L(0); PG8_BAR; PG8_MMA(0, 0, At, B0); PG8_MMA(0, 1, At, B1); PG8_BAR; PG8_SCHED;
;             PG8_LDA(At, 1, 1); PG8_STAGE(PG8_SB(1, 0), b3, B); PG8_STAGE(PG8_SB(1, 1), b3 + hstepB, B); PG8_STAGE(PG8_SA(1, 0), a3, A);
;             PG8_WAIT_V(8); PG8_WAIT_L(0); PG8_BAR; PG8_MMA(1, 0, At, B0); PG8_MMA(1, 1, At, B1); PG8_BAR; PG8_SCHED;
;         }
;         if constexpr (ALIGN_EPI) { if (wr == 0) PG8_BAR; }
	s_setprio 1
	v_mfma_f32_16x16x32_bf16 v[58:61], v[8:11], v[24:27], v[66:69]
	v_mfma_f32_16x16x32_bf16 v[124:127], v[12:15], v[28:31], v[58:61]
	v_mfma_f32_16x16x32_bf16 v[58:61], v[16:19], v[24:27], v[70:73]
	v_mfma_f32_16x16x32_bf16 v[120:123], v[20:23], v[28:31], v[58:61]
	v_mfma_f32_16x16x32_bf16 v[58:61], v[8:11], v[240:243], v[74:77]
	v_mfma_f32_16x16x32_bf16 v[108:111], v[12:15], v[244:247], v[58:61]
	v_mfma_f32_16x16x32_bf16 v[58:61], v[16:19], v[240:243], v[78:81]
	v_mfma_f32_16x16x32_bf16 v[104:107], v[20:23], v[244:247], v[58:61]
	v_mfma_f32_16x16x32_bf16 v[58:61], v[8:11], v[248:251], v[82:85]
	v_mfma_f32_16x16x32_bf16 v[92:95], v[12:15], v[218:221], v[58:61]
	v_mfma_f32_16x16x32_bf16 v[58:61], v[16:19], v[248:251], v[86:89]
	v_mfma_f32_16x16x32_bf16 v[88:91], v[20:23], v[218:221], v[58:61]
	v_mfma_f32_16x16x32_bf16 v[58:61], v[8:11], v[226:229], v[200:203]
	v_mfma_f32_16x16x32_bf16 v[68:71], v[12:15], v[236:239], v[58:61]
	v_mfma_f32_16x16x32_bf16 v[58:61], v[16:19], v[226:229], v[204:207]
	v_mfma_f32_16x16x32_bf16 v[60:63], v[20:23], v[236:239], v[58:61]
	s_setprio 0
	s_setprio 1
	v_mfma_f32_16x16x32_bf16 v[64:67], v[164:167], v[24:27], v[96:99]
	v_mfma_f32_16x16x32_bf16 v[24:27], v[188:191], v[24:27], v[34:37]
	v_mfma_f32_16x16x32_bf16 v[112:115], v[192:195], v[28:31], v[24:27]
	v_mfma_f32_16x16x32_bf16 v[24:27], v[164:167], v[240:243], v[38:41]
	v_mfma_f32_16x16x32_bf16 v[100:103], v[184:187], v[244:247], v[24:27]
	v_mfma_f32_16x16x32_bf16 v[24:27], v[188:191], v[240:243], v[42:45]
	v_mfma_f32_16x16x32_bf16 v[96:99], v[192:195], v[244:247], v[24:27]
	v_mfma_f32_16x16x32_bf16 v[24:27], v[164:167], v[248:251], v[46:49]
	v_mfma_f32_16x16x32_bf16 v[84:87], v[184:187], v[218:221], v[24:27]
	v_mfma_f32_16x16x32_bf16 v[24:27], v[188:191], v[248:251], v[50:53]
	v_mfma_f32_16x16x32_bf16 v[80:83], v[192:195], v[218:221], v[24:27]
	v_mfma_f32_16x16x32_bf16 v[24:27], v[164:167], v[226:229], v[54:57]
	v_mfma_f32_16x16x32_bf16 v[52:55], v[184:187], v[236:239], v[24:27]
	v_mfma_f32_16x16x32_bf16 v[24:27], v[188:191], v[226:229], v[168:171]
	v_mfma_f32_16x16x32_bf16 v[116:119], v[184:187], v[28:31], v[64:67]
	v_mfma_f32_16x16x32_bf16 v[48:51], v[192:195], v[236:239], v[24:27]
	s_setprio 0
	s_barrier
	s_mov_b32 m0, s56
	s_nop 2
	v_lshl_add_u64 v[24:25], v[230:231], 0, s[50:51]
	ds_read_b128 v[32:35], v131 offset:49152
	ds_read_b128 v[36:39], v131 offset:50176
	ds_read_b128 v[168:171], v131 offset:51200
	ds_read_b128 v[200:203], v131 offset:52224
	ds_read_b128 v[204:207], v131 offset:53248
	ds_read_b128 v[218:221], v131 offset:54272
	ds_read_b128 v[226:229], v131 offset:55296
	ds_read_b128 v[236:239], v131 offset:56320
	global_load_lds_dwordx4 v[24:25], off
	v_lshl_add_u64 v[24:25], v[230:231], 0, s[54:55]
	s_mov_b32 m0, s49
	s_mov_b64 s[44:45], 0x8080
	global_load_lds_dwordx4 v[24:25], off
	v_lshl_add_u64 v[24:25], v[230:231], 0, s[96:97]
	s_mov_b32 m0, s52
	s_nop 0
	global_load_lds_dwordx4 v[24:25], off
	v_lshl_add_u64 v[24:25], v[230:231], 0, s[6:7]
	s_mov_b32 m0, s53
	s_nop 0
	global_load_lds_dwordx4 v[24:25], off
	v_lshl_add_u64 v[24:25], v[222:223], 0, s[50:51]
	s_mov_b32 m0, s33
	s_nop 0
	global_load_lds_dwordx4 v[24:25], off
	v_lshl_add_u64 v[24:25], v[222:223], 0, s[44:45]
	s_mov_b32 m0, s34
	s_nop 0
	global_load_lds_dwordx4 v[24:25], off
	s_waitcnt vmcnt(8)
	s_waitcnt lgkmcnt(0)
	s_barrier
	s_setprio 1
	v_mfma_f32_16x16x32_bf16 v[24:27], v[8:11], v[32:35], v[136:139]
	v_mfma_f32_16x16x32_bf16 v[76:79], v[12:15], v[36:39], v[24:27]
	v_mfma_f32_16x16x32_bf16 v[24:27], v[16:19], v[32:35], v[140:143]
	v_mfma_f32_16x16x32_bf16 v[72:75], v[20:23], v[36:39], v[24:27]
	v_mfma_f32_16x16x32_bf16 v[24:27], v[8:11], v[168:171], v[144:147]
	v_mfma_f32_16x16x32_bf16 v[44:47], v[12:15], v[200:203], v[24:27]
	v_mfma_f32_16x16x32_bf16 v[24:27], v[16:19], v[168:171], v[148:151]
	v_mfma_f32_16x16x32_bf16 v[40:43], v[20:23], v[200:203], v[24:27]
	v_mfma_f32_16x16x32_bf16 v[24:27], v[8:11], v[204:207], v[152:155]
	v_mfma_f32_16x16x32_bf16 v[0:3], v[8:11], v[226:229], v[0:3]
	v_mfma_f32_16x16x32_bf16 v[28:31], v[12:15], v[218:221], v[24:27]
	v_mfma_f32_16x16x32_bf16 v[24:27], v[16:19], v[204:207], v[156:159]
	v_mfma_f32_16x16x32_bf16 v[12:15], v[12:15], v[236:239], v[0:3]
	v_mfma_f32_16x16x32_bf16 v[0:3], v[16:19], v[226:229], v[4:7]
	v_mfma_f32_16x16x32_bf16 v[24:27], v[20:23], v[218:221], v[24:27]
	v_mfma_f32_16x16x32_bf16 v[8:11], v[20:23], v[236:239], v[0:3]
	s_setprio 0
	s_setprio 1
	v_mfma_f32_16x16x32_bf16 v[0:3], v[164:167], v[32:35], v[196:199]
	v_mfma_f32_16x16x32_bf16 v[64:67], v[184:187], v[36:39], v[0:3]
	v_mfma_f32_16x16x32_bf16 v[0:3], v[188:191], v[32:35], v[208:211]
	v_mfma_f32_16x16x32_bf16 v[56:59], v[192:195], v[36:39], v[0:3]
	v_mfma_f32_16x16x32_bf16 v[0:3], v[164:167], v[168:171], v[212:215]
	v_mfma_f32_16x16x32_bf16 v[36:39], v[184:187], v[200:203], v[0:3]
	v_mfma_f32_16x16x32_bf16 v[0:3], v[188:191], v[168:171], v[172:175]
	v_mfma_f32_16x16x32_bf16 v[32:35], v[192:195], v[200:203], v[0:3]
	v_mfma_f32_16x16x32_bf16 v[0:3], v[164:167], v[204:207], v[176:179]
	v_mfma_f32_16x16x32_bf16 v[20:23], v[184:187], v[218:221], v[0:3]
	v_mfma_f32_16x16x32_bf16 v[0:3], v[188:191], v[204:207], v[180:183]
	v_mfma_f32_16x16x32_bf16 v[16:19], v[192:195], v[218:221], v[0:3]
	v_mfma_f32_16x16x32_bf16 v[0:3], v[164:167], v[226:229], v[132:135]
	v_mfma_f32_16x16x32_bf16 v[4:7], v[184:187], v[236:239], v[0:3]
	v_mfma_f32_16x16x32_bf16 v[0:3], v[188:191], v[226:229], v[160:163]
	v_mfma_f32_16x16x32_bf16 v[0:3], v[192:195], v[236:239], v[0:3]
	s_setprio 0
	s_barrier
	s_andn2_b64 vcc, exec, s[4:5]
	s_cbranch_vccnz .LBB0_675
	s_barrier

; #define PG8_STAGE(bufoff, gbase, voff) do { _Pragma("unroll") for (int _i = 0; _i < 2; ++_i) \
;         __builtin_amdgcn_global_load_lds((const GAS unsigned*)((const GAS char*)(gbase) + (size_t)_i * r64##voff + (vo##voff)), (LAS unsigned*)(lds + (bufoff) + ldsw + _i * 8192), 16, 0, 0); } while (0)
; #define PG8_LDA(dst, b, h) do { _Pragma("unroll") for (int m = 0; m < 4; ++m) _Pragma("unroll") for (int k = 0; k < 2; ++k) dst[m][k] = *(const LAS bf16x8*)(lds + PG8_SA(b, h) + aoff + m * 2048 + k * 1024); } while (0)
; #define PG8_LDB(dst, b, h) do { _Pragma("unroll") for (int n = 0; n < 2; ++n) _Pragma("unroll") for (int k = 0; k < 2; ++k) dst[n][k] = *(const LAS bf16x8*)(lds + PG8_SB(b, h) + boff + n * 2048 + k * 1024); } while (0)
; #define PG8_MMA(ai, bj, At, Bt) do { __builtin_amdgcn_s_setprio(1); _Pragma("unroll") for (int m = 0; m < 4; ++m) _Pragma("unroll") for (int n = 0; n < 2; ++n) _Pragma("unroll") for (int k = 0; k < 2; ++k) \
;         acc[ai][bj][m][n] = __builtin_amdgcn_mfma_f32_16x16x32_bf16(Bt[n][k], At[m][k], acc[ai][bj][m][n], 0, 0, 0); __builtin_amdgcn_s_setprio(0); } while (0)
; #define PG8_WAIT_V(n) asm volatile("s_waitcnt vmcnt(" #n ")" ::: "memory")
; #define PG8_WAIT_L(n) asm volatile("s_waitcnt lgkmcnt(" #n ")" ::: "memory")
; #define PG8_BAR __builtin_amdgcn_s_barrier()
; template <class Epi, class Map, bool ALIGN_EPI>
; __device__ __forceinline__ void gemm_phase(const int tid, LAS unsigned char* lds, const int lda, const int ldb, const int K, const Map& MP, const StaticOrder& S, const Epi& E) {
;     ...
;             const bool last = (t == nt - 2);
;             const char* a1 = cA + (size_t)(t + 1) * kstep;
;             const char* a2 = last ? nA : cA + (size_t)(t + 2) * kstep; const char* b2 = last ? nB : cB + (size_t)(t + 2) * kstep;
;             const char* a3 = a2 + kstep; const char* b3 = b2 + kstep;
;             PG8_LDB(B0, 0, 0); PG8_LDB(B1, 0, 1); PG8_SCHED; PG8_LDA(At, 0, 0); PG8_STAGE(PG8_SA(1, 1), a1 + hstepA, A);
;             PG8_WAIT_V(8); PG8_WAIT_L(0); PG8_BAR; PG8_MMA(0, 0, At, B0); PG8_MMA(0, 1, At, B1); PG8_BAR; PG8_SCHED;
;             PG8_LDA(At, 0, 1); PG8_STAGE(PG8_SB(0, 0), b2, B); PG8_STAGE(PG8_SB(0, 1), b2 + hstepB, B); PG8_STAGE(PG8_SA(0, 0), a2, A);
;             PG8_WAIT_V(8); PG8_WAIT_L(0); PG8_BAR; PG8_MMA(1, 0, At, B0); PG8_MMA(1, 1, At, B1); PG8_BAR; PG8_SCHED;
.LBB0_751:
	s_add_u32 s42, s10, 0xfff00080
	s_addc_u32 s43, s11, -1
	s_add_i32 s47, 0, 0x10000
	s_cmp_eq_u32 s46, 28
	s_cselect_b32 s43, s89, s43
	s_cselect_b32 s42, s88, s42
	s_cselect_b32 s81, s93, s79
	s_cselect_b32 s80, s92, s71
	s_add_i32 s82, 0, 0x14000
	v_add_u32_e32 v144, s47, v160
	v_add_u32_e32 v162, s82, v160
	ds_read_b128 v[128:131], v144
	ds_read_b128 v[132:135], v144 offset:1024
	ds_read_b128 v[140:143], v144 offset:2048
	ds_read_b128 v[144:147], v144 offset:3072
	ds_read_b128 v[148:151], v162
	ds_read_b128 v[152:155], v162 offset:1024
	ds_read_b128 v[156:159], v162 offset:2048
	ds_read_b128 v[162:165], v162 offset:3072
	v_lshl_add_u64 v[198:199], s[10:11], 0, v[138:139]
	s_add_i32 m0, s19, 0xc000
	ds_read_b128 v[166:169], v161
	ds_read_b128 v[170:173], v161 offset:1024
	ds_read_b128 v[174:177], v161 offset:2048
	ds_read_b128 v[178:181], v161 offset:3072
	ds_read_b128 v[182:185], v161 offset:4096
	ds_read_b128 v[186:189], v161 offset:5120
	ds_read_b128 v[190:193], v161 offset:6144
	ds_read_b128 v[194:197], v161 offset:7168
	global_load_lds_dwordx4 v[198:199], off
	v_lshl_add_u64 v[198:199], v[198:199], 0, s[0:1]
	s_add_i32 m0, s19, 0xe000
	s_nop 0
	global_load_lds_dwordx4 v[198:199], off
	s_waitcnt vmcnt(8)
	s_waitcnt lgkmcnt(0)
	s_barrier
	s_setprio 1
	v_mfma_f32_16x16x32_bf16 v[124:127], v[128:131], v[166:169], v[124:127]
	v_mfma_f32_16x16x32_bf16 v[120:123], v[140:143], v[166:169], v[120:123]
	v_mfma_f32_16x16x32_bf16 v[116:119], v[128:131], v[174:177], v[116:119]
	v_mfma_f32_16x16x32_bf16 v[112:115], v[140:143], v[174:177], v[112:115]
	v_mfma_f32_16x16x32_bf16 v[108:111], v[128:131], v[182:185], v[108:111]
	v_mfma_f32_16x16x32_bf16 v[104:107], v[140:143], v[182:185], v[104:107]
	v_mfma_f32_16x16x32_bf16 v[100:103], v[128:131], v[190:193], v[100:103]
	v_mfma_f32_16x16x32_bf16 v[96:99], v[140:143], v[190:193], v[96:99]
	v_mfma_f32_16x16x32_bf16 v[124:127], v[132:135], v[170:173], v[124:127]
	v_mfma_f32_16x16x32_bf16 v[120:123], v[144:147], v[170:173], v[120:123]
	v_mfma_f32_16x16x32_bf16 v[116:119], v[132:135], v[178:181], v[116:119]
	v_mfma_f32_16x16x32_bf16 v[112:115], v[144:147], v[178:181], v[112:115]
	v_mfma_f32_16x16x32_bf16 v[108:111], v[132:135], v[186:189], v[108:111]
	v_mfma_f32_16x16x32_bf16 v[104:107], v[144:147], v[186:189], v[104:107]
	v_mfma_f32_16x16x32_bf16 v[100:103], v[132:135], v[194:197], v[100:103]
	v_mfma_f32_16x16x32_bf16 v[96:99], v[144:147], v[194:197], v[96:99]
	s_setprio 0
	s_setprio 1
	v_mfma_f32_16x16x32_bf16 v[92:95], v[148:151], v[166:169], v[92:95]
	v_mfma_f32_16x16x32_bf16 v[88:91], v[156:159], v[166:169], v[88:91]
	v_mfma_f32_16x16x32_bf16 v[84:87], v[148:151], v[174:177], v[84:87]
	v_mfma_f32_16x16x32_bf16 v[80:83], v[156:159], v[174:177], v[80:83]
	v_mfma_f32_16x16x32_bf16 v[76:79], v[148:151], v[182:185], v[76:79]
	v_mfma_f32_16x16x32_bf16 v[72:75], v[156:159], v[182:185], v[72:75]
	v_mfma_f32_16x16x32_bf16 v[68:71], v[148:151], v[190:193], v[68:71]
	v_mfma_f32_16x16x32_bf16 v[64:67], v[156:159], v[190:193], v[64:67]
	v_mfma_f32_16x16x32_bf16 v[92:95], v[152:155], v[170:173], v[92:95]
	v_mfma_f32_16x16x32_bf16 v[88:91], v[162:165], v[170:173], v[88:91]
	v_mfma_f32_16x16x32_bf16 v[84:87], v[152:155], v[178:181], v[84:87]
	v_mfma_f32_16x16x32_bf16 v[80:83], v[162:165], v[178:181], v[80:83]
	v_mfma_f32_16x16x32_bf16 v[76:79], v[152:155], v[186:189], v[76:79]
	v_mfma_f32_16x16x32_bf16 v[72:75], v[162:165], v[186:189], v[72:75]
	v_mfma_f32_16x16x32_bf16 v[68:71], v[152:155], v[194:197], v[68:71]
	v_mfma_f32_16x16x32_bf16 v[64:67], v[162:165], v[194:197], v[64:67]
	s_setprio 0
	s_barrier
	s_add_i32 s47, s47, s14
	v_lshl_add_u64 v[198:199], s[80:81], 0, v[136:137]
	s_mov_b32 m0, s47
	ds_read_b128 v[166:169], v161 offset:16384
	ds_read_b128 v[170:173], v161 offset:17408
	ds_read_b128 v[174:177], v161 offset:18432
	ds_read_b128 v[178:181], v161 offset:19456
	ds_read_b128 v[182:185], v161 offset:20480
	ds_read_b128 v[186:189], v161 offset:21504
	ds_read_b128 v[190:193], v161 offset:22528
	ds_read_b128 v[194:197], v161 offset:23552
	global_load_lds_dwordx4 v[198:199], off
	v_lshl_add_u64 v[200:201], v[198:199], 0, s[0:1]
	s_add_i32 m0, s47, 0x2000
	s_add_i32 s47, s82, s14
	global_load_lds_dwordx4 v[200:201], off
	v_lshl_add_u64 v[200:201], v[198:199], 0, vcc
	s_mov_b32 m0, s47
	s_nop 0
	global_load_lds_dwordx4 v[200:201], off
	v_lshl_add_u64 v[200:201], v[198:199], 0, s[16:17]
	s_add_i32 m0, s47, 0x2000
	s_nop 0
	global_load_lds_dwordx4 v[200:201], off
	v_lshl_add_u64 v[200:201], s[42:43], 0, v[138:139]
	s_mov_b32 m0, s19
	v_lshl_add_u64 v[202:203], v[200:201], 0, s[0:1]
	global_load_lds_dwordx4 v[200:201], off
	s_mov_b32 m0, s24
	s_nop 0
	global_load_lds_dwordx4 v[202:203], off
	s_waitcnt vmcnt(8)
	s_waitcnt lgkmcnt(0)
	s_barrier
; #define PG8_STAGE(bufoff, gbase, voff) do { _Pragma("unroll") for (int _i = 0; _i < 2; ++_i) \
;         __builtin_amdgcn_global_load_lds((const GAS unsigned*)((const GAS char*)(gbase) + (size_t)_i * r64##voff + (vo##voff)), (LAS unsigned*)(lds + (bufoff) + ldsw + _i * 8192), 16, 0, 0); } while (0)
; #define PG8_LDA(dst, b, h) do { _Pragma("unroll") for (int m = 0; m < 4; ++m) _Pragma("unroll") for (int k = 0; k < 2; ++k) dst[m][k] = *(const LAS bf16x8*)(lds + PG8_SA(b, h) + aoff + m * 2048 + k * 1024); } while (0)
; #define PG8_LDB(dst, b, h) do { _Pragma("unroll") for (int n = 0; n < 2; ++n) _Pragma("unroll") for (int k = 0; k < 2; ++k) dst[n][k] = *(const LAS bf16x8*)(lds + PG8_SB(b, h) + boff + n * 2048 + k * 1024); } while (0)
; #define PG8_MMA(ai, bj, At, Bt) do { __builtin_amdgcn_s_setprio(1); _Pragma("unroll") for (int m = 0; m < 4; ++m) _Pragma("unroll") for (int n = 0; n < 2; ++n) _Pragma("unroll") for (int k = 0; k < 2; ++k) \
;         acc[ai][bj][m][n] = __builtin_amdgcn_mfma_f32_16x16x32_bf16(Bt[n][k], At[m][k], acc[ai][bj][m][n], 0, 0, 0); __builtin_amdgcn_s_setprio(0); } while (0)
; #define PG8_WAIT_V(n) asm volatile("s_waitcnt vmcnt(" #n ")" ::: "memory")
; #define PG8_WAIT_L(n) asm volatile("s_waitcnt lgkmcnt(" #n ")" ::: "memory")
; #define PG8_BAR __builtin_amdgcn_s_barrier()
; #define PG8_SCHED __builtin_amdgcn_sched_barrier(0)
; template <class Epi, class Map, bool ALIGN_EPI>
; __device__ __forceinline__ void gemm_phase(const int tid, LAS unsigned char* lds, const int lda, const int ldb, const int K, const Map& MP, const StaticOrder& S, const Epi& E) {
;     ...
;             PG8_WAIT_V(8); PG8_WAIT_L(0); PG8_BAR; PG8_MMA(1, 0, At, B0); PG8_MMA(1, 1, At, B1); PG8_BAR; PG8_SCHED;
;             PG8_LDB(B0, 1, 0); PG8_LDB(B1, 1, 1); PG8_SCHED; PG8_LDA(At, 1, 0); PG8_STAGE(PG8_SA(0, 1), a2 + hstepA, A);
;             PG8_WAIT_V(8); PG8_WAIT_L(0); PG8_BAR; PG8_MMA(0, 0, At, B0); PG8_MMA(0, 1, At, B1); PG8_BAR; PG8_SCHED;
	s_setprio 1
	v_mfma_f32_16x16x32_bf16 v[60:63], v[128:131], v[166:169], v[60:63]
	v_mfma_f32_16x16x32_bf16 v[56:59], v[140:143], v[166:169], v[56:59]
	v_mfma_f32_16x16x32_bf16 v[52:55], v[128:131], v[174:177], v[52:55]
	v_mfma_f32_16x16x32_bf16 v[48:51], v[140:143], v[174:177], v[48:51]
	v_mfma_f32_16x16x32_bf16 v[44:47], v[128:131], v[182:185], v[44:47]
	v_mfma_f32_16x16x32_bf16 v[40:43], v[140:143], v[182:185], v[40:43]
	v_mfma_f32_16x16x32_bf16 v[36:39], v[128:131], v[190:193], v[36:39]
	v_mfma_f32_16x16x32_bf16 v[32:35], v[140:143], v[190:193], v[32:35]
	v_mfma_f32_16x16x32_bf16 v[60:63], v[132:135], v[170:173], v[60:63]
	v_mfma_f32_16x16x32_bf16 v[56:59], v[144:147], v[170:173], v[56:59]
	v_mfma_f32_16x16x32_bf16 v[52:55], v[132:135], v[178:181], v[52:55]
	v_mfma_f32_16x16x32_bf16 v[48:51], v[144:147], v[178:181], v[48:51]
	v_mfma_f32_16x16x32_bf16 v[44:47], v[132:135], v[186:189], v[44:47]
	v_mfma_f32_16x16x32_bf16 v[40:43], v[144:147], v[186:189], v[40:43]
	v_mfma_f32_16x16x32_bf16 v[36:39], v[132:135], v[194:197], v[36:39]
	v_mfma_f32_16x16x32_bf16 v[32:35], v[144:147], v[194:197], v[32:35]
	s_setprio 0
	s_setprio 1
	v_mfma_f32_16x16x32_bf16 v[28:31], v[148:151], v[166:169], v[28:31]
	v_mfma_f32_16x16x32_bf16 v[24:27], v[156:159], v[166:169], v[24:27]
	v_mfma_f32_16x16x32_bf16 v[20:23], v[148:151], v[174:177], v[20:23]
	v_mfma_f32_16x16x32_bf16 v[16:19], v[156:159], v[174:177], v[16:19]
	v_mfma_f32_16x16x32_bf16 v[12:15], v[148:151], v[182:185], v[12:15]
	v_mfma_f32_16x16x32_bf16 v[8:11], v[156:159], v[182:185], v[8:11]
	v_mfma_f32_16x16x32_bf16 v[4:7], v[148:151], v[190:193], v[4:7]
	v_mfma_f32_16x16x32_bf16 v[0:3], v[156:159], v[190:193], v[0:3]
	v_mfma_f32_16x16x32_bf16 v[28:31], v[152:155], v[170:173], v[28:31]
	v_mfma_f32_16x16x32_bf16 v[24:27], v[162:165], v[170:173], v[24:27]
	v_mfma_f32_16x16x32_bf16 v[20:23], v[152:155], v[178:181], v[20:23]
	v_mfma_f32_16x16x32_bf16 v[16:19], v[162:165], v[178:181], v[16:19]
	v_mfma_f32_16x16x32_bf16 v[12:15], v[152:155], v[186:189], v[12:15]
	v_mfma_f32_16x16x32_bf16 v[8:11], v[162:165], v[186:189], v[8:11]
	v_mfma_f32_16x16x32_bf16 v[4:7], v[152:155], v[194:197], v[4:7]
	v_mfma_f32_16x16x32_bf16 v[0:3], v[162:165], v[194:197], v[0:3]
	s_setprio 0
	s_barrier
	s_add_i32 s42, 0, 0x18000
	s_add_i32 s43, 0, 0x1c000
	v_add_u32_e32 v144, s42, v160
	v_add_u32_e32 v162, s43, v160
	ds_read_b128 v[128:131], v144
	ds_read_b128 v[132:135], v144 offset:1024
	ds_read_b128 v[140:143], v144 offset:2048
	ds_read_b128 v[144:147], v144 offset:3072
	ds_read_b128 v[148:151], v162
	ds_read_b128 v[152:155], v162 offset:1024
	ds_read_b128 v[156:159], v162 offset:2048
	ds_read_b128 v[162:165], v162 offset:3072
	s_mov_b32 m0, s28
	v_lshl_add_u64 v[202:203], v[200:201], 0, vcc
	ds_read_b128 v[166:169], v161 offset:32768
	ds_read_b128 v[170:173], v161 offset:33792
	ds_read_b128 v[174:177], v161 offset:34816
	ds_read_b128 v[178:181], v161 offset:35840
	ds_read_b128 v[182:185], v161 offset:36864
	ds_read_b128 v[186:189], v161 offset:37888
	ds_read_b128 v[190:193], v161 offset:38912
	ds_read_b128 v[194:197], v161 offset:39936
	global_load_lds_dwordx4 v[202:203], off
	v_lshl_add_u64 v[202:203], v[200:201], 0, s[16:17]
	s_mov_b32 m0, s29
	s_nop 0
	global_load_lds_dwordx4 v[202:203], off
	s_waitcnt vmcnt(8)
	s_waitcnt lgkmcnt(0)
	s_barrier
	s_setprio 1
	v_mfma_f32_16x16x32_bf16 v[124:127], v[128:131], v[166:169], v[124:127]
	v_mfma_f32_16x16x32_bf16 v[120:123], v[140:143], v[166:169], v[120:123]
	v_mfma_f32_16x16x32_bf16 v[116:119], v[128:131], v[174:177], v[116:119]
	v_mfma_f32_16x16x32_bf16 v[112:115], v[140:143], v[174:177], v[112:115]
	v_mfma_f32_16x16x32_bf16 v[108:111], v[128:131], v[182:185], v[108:111]
	v_mfma_f32_16x16x32_bf16 v[104:107], v[140:143], v[182:185], v[104:107]
	v_mfma_f32_16x16x32_bf16 v[100:103], v[128:131], v[190:193], v[100:103]
	v_mfma_f32_16x16x32_bf16 v[96:99], v[140:143], v[190:193], v[96:99]
	v_mfma_f32_16x16x32_bf16 v[124:127], v[132:135], v[170:173], v[124:127]
	v_mfma_f32_16x16x32_bf16 v[120:123], v[144:147], v[170:173], v[120:123]
	v_mfma_f32_16x16x32_bf16 v[116:119], v[132:135], v[178:181], v[116:119]
	v_mfma_f32_16x16x32_bf16 v[112:115], v[144:147], v[178:181], v[112:115]
	v_mfma_f32_16x16x32_bf16 v[108:111], v[132:135], v[186:189], v[108:111]
	v_mfma_f32_16x16x32_bf16 v[104:107], v[144:147], v[186:189], v[104:107]
	v_mfma_f32_16x16x32_bf16 v[100:103], v[132:135], v[194:197], v[100:103]
	v_mfma_f32_16x16x32_bf16 v[96:99], v[144:147], v[194:197], v[96:99]
	s_setprio 0
	s_setprio 1
	v_mfma_f32_16x16x32_bf16 v[92:95], v[148:151], v[166:169], v[92:95]
	v_mfma_f32_16x16x32_bf16 v[88:91], v[156:159], v[166:169], v[88:91]
	v_mfma_f32_16x16x32_bf16 v[84:87], v[148:151], v[174:177], v[84:87]
	v_mfma_f32_16x16x32_bf16 v[80:83], v[156:159], v[174:177], v[80:83]
	v_mfma_f32_16x16x32_bf16 v[76:79], v[148:151], v[182:185], v[76:79]
	v_mfma_f32_16x16x32_bf16 v[72:75], v[156:159], v[182:185], v[72:75]
	v_mfma_f32_16x16x32_bf16 v[68:71], v[148:151], v[190:193], v[68:71]
	v_mfma_f32_16x16x32_bf16 v[64:67], v[156:159], v[190:193], v[64:67]
	v_mfma_f32_16x16x32_bf16 v[92:95], v[152:155], v[170:173], v[92:95]
	v_mfma_f32_16x16x32_bf16 v[88:91], v[162:165], v[170:173], v[88:91]
	v_mfma_f32_16x16x32_bf16 v[84:87], v[152:155], v[178:181], v[84:87]
	v_mfma_f32_16x16x32_bf16 v[80:83], v[162:165], v[178:181], v[80:83]
	v_mfma_f32_16x16x32_bf16 v[76:79], v[152:155], v[186:189], v[76:79]
	v_mfma_f32_16x16x32_bf16 v[72:75], v[162:165], v[186:189], v[72:75]
	v_mfma_f32_16x16x32_bf16 v[68:71], v[152:155], v[194:197], v[68:71]
	v_mfma_f32_16x16x32_bf16 v[64:67], v[162:165], v[194:197], v[64:67]
	s_setprio 0
	s_barrier
; #define PG8_STAGE(bufoff, gbase, voff) do { _Pragma("unroll") for (int _i = 0; _i < 2; ++_i) \
;         __builtin_amdgcn_global_load_lds((const GAS unsigned*)((const GAS char*)(gbase) + (size_t)_i * r64##voff + (vo##voff)), (LAS unsigned*)(lds + (bufoff) + ldsw + _i * 8192), 16, 0, 0); } while (0)
; #define PG8_LDA(dst, b, h) do { _Pragma("unroll") for (int m = 0; m < 4; ++m) _Pragma("unroll") for (int k = 0; k < 2; ++k) dst[m][k] = *(const LAS bf16x8*)(lds + PG8_SA(b, h) + aoff + m * 2048 + k * 1024); } while (0)
; #define PG8_MMA(ai, bj, At, Bt) do { __builtin_amdgcn_s_setprio(1); _Pragma("unroll") for (int m = 0; m < 4; ++m) _Pragma("unroll") for (int n = 0; n < 2; ++n) _Pragma("unroll") for (int k = 0; k < 2; ++k) \
;         acc[ai][bj][m][n] = __builtin_amdgcn_mfma_f32_16x16x32_bf16(Bt[n][k], At[m][k], acc[ai][bj][m][n], 0, 0, 0); __builtin_amdgcn_s_setprio(0); } while (0)
; #define PG8_WAIT_V(n) asm volatile("s_waitcnt vmcnt(" #n ")" ::: "memory")
; #define PG8_WAIT_L(n) asm volatile("s_waitcnt lgkmcnt(" #n ")" ::: "memory")
; #define PG8_BAR __builtin_amdgcn_s_barrier()
; #define PG8_SCHED __builtin_amdgcn_sched_barrier(0)
; template <class Epi, class Map, bool ALIGN_EPI>
; __device__ __forceinline__ void gemm_phase(const int tid, LAS unsigned char* lds, const int lda, const int ldb, const int K, const Map& MP, const StaticOrder& S, const Epi& E) {
;     ...
;             PG8_LDA(At, 1, 1); PG8_STAGE(PG8_SB(1, 0), b3, B); PG8_STAGE(PG8_SB(1, 1), b3 + hstepB, B); PG8_STAGE(PG8_SA(1, 0), a3, A);
;             PG8_WAIT_V(8); PG8_WAIT_L(0); PG8_BAR; PG8_MMA(1, 0, At, B0); PG8_MMA(1, 1, At, B1); PG8_BAR; PG8_SCHED;
;         }
;         if constexpr (ALIGN_EPI) { if (wr == 0) PG8_BAR; }
	s_add_i32 s42, s42, s14
	v_lshl_add_u64 v[202:203], v[198:199], 0, s[50:51]
	s_mov_b32 m0, s42
	ds_read_b128 v[166:169], v161 offset:49152
	ds_read_b128 v[170:173], v161 offset:50176
	ds_read_b128 v[174:177], v161 offset:51200
	ds_read_b128 v[178:181], v161 offset:52224
	ds_read_b128 v[182:185], v161 offset:53248
	ds_read_b128 v[186:189], v161 offset:54272
	ds_read_b128 v[190:193], v161 offset:55296
	ds_read_b128 v[194:197], v161 offset:56320
	global_load_lds_dwordx4 v[202:203], off
	v_lshl_add_u64 v[202:203], v[198:199], 0, s[20:21]
	s_add_i32 m0, s42, 0x2000
	s_add_i32 s42, s43, s14
	global_load_lds_dwordx4 v[202:203], off
	v_lshl_add_u64 v[202:203], v[198:199], 0, s[22:23]
	s_mov_b32 m0, s42
	v_lshl_add_u64 v[198:199], v[198:199], 0, s[44:45]
	global_load_lds_dwordx4 v[202:203], off
	s_add_i32 m0, s42, 0x2000
	s_nop 0
	global_load_lds_dwordx4 v[198:199], off
	v_lshl_add_u64 v[198:199], v[200:201], 0, s[50:51]
	s_mov_b32 m0, s35
	s_nop 0
	global_load_lds_dwordx4 v[198:199], off
	v_lshl_add_u64 v[198:199], v[200:201], 0, s[20:21]
	s_mov_b32 m0, s36
	s_nop 0
	global_load_lds_dwordx4 v[198:199], off
	s_waitcnt vmcnt(8)
	s_waitcnt lgkmcnt(0)
	s_barrier
	s_setprio 1
	v_mfma_f32_16x16x32_bf16 v[60:63], v[128:131], v[166:169], v[60:63]
	v_mfma_f32_16x16x32_bf16 v[56:59], v[140:143], v[166:169], v[56:59]
	v_mfma_f32_16x16x32_bf16 v[52:55], v[128:131], v[174:177], v[52:55]
	v_mfma_f32_16x16x32_bf16 v[48:51], v[140:143], v[174:177], v[48:51]
	v_mfma_f32_16x16x32_bf16 v[44:47], v[128:131], v[182:185], v[44:47]
	v_mfma_f32_16x16x32_bf16 v[40:43], v[140:143], v[182:185], v[40:43]
	v_mfma_f32_16x16x32_bf16 v[36:39], v[128:131], v[190:193], v[36:39]
	v_mfma_f32_16x16x32_bf16 v[32:35], v[140:143], v[190:193], v[32:35]
	v_mfma_f32_16x16x32_bf16 v[60:63], v[132:135], v[170:173], v[60:63]
	v_mfma_f32_16x16x32_bf16 v[56:59], v[144:147], v[170:173], v[56:59]
	v_mfma_f32_16x16x32_bf16 v[52:55], v[132:135], v[178:181], v[52:55]
	v_mfma_f32_16x16x32_bf16 v[48:51], v[144:147], v[178:181], v[48:51]
	v_mfma_f32_16x16x32_bf16 v[44:47], v[132:135], v[186:189], v[44:47]
	v_mfma_f32_16x16x32_bf16 v[40:43], v[144:147], v[186:189], v[40:43]
	v_mfma_f32_16x16x32_bf16 v[36:39], v[132:135], v[194:197], v[36:39]
	v_mfma_f32_16x16x32_bf16 v[32:35], v[144:147], v[194:197], v[32:35]
	s_setprio 0
	s_setprio 1
	v_mfma_f32_16x16x32_bf16 v[28:31], v[148:151], v[166:169], v[28:31]
	v_mfma_f32_16x16x32_bf16 v[24:27], v[156:159], v[166:169], v[24:27]
	v_mfma_f32_16x16x32_bf16 v[20:23], v[148:151], v[174:177], v[20:23]
	v_mfma_f32_16x16x32_bf16 v[16:19], v[156:159], v[174:177], v[16:19]
	v_mfma_f32_16x16x32_bf16 v[12:15], v[148:151], v[182:185], v[12:15]
	v_mfma_f32_16x16x32_bf16 v[8:11], v[156:159], v[182:185], v[8:11]
	v_mfma_f32_16x16x32_bf16 v[4:7], v[148:151], v[190:193], v[4:7]
	v_mfma_f32_16x16x32_bf16 v[0:3], v[156:159], v[190:193], v[0:3]
	v_mfma_f32_16x16x32_bf16 v[28:31], v[152:155], v[170:173], v[28:31]
	v_mfma_f32_16x16x32_bf16 v[24:27], v[162:165], v[170:173], v[24:27]
	v_mfma_f32_16x16x32_bf16 v[20:23], v[152:155], v[178:181], v[20:23]
	v_mfma_f32_16x16x32_bf16 v[16:19], v[162:165], v[178:181], v[16:19]
	v_mfma_f32_16x16x32_bf16 v[12:15], v[152:155], v[186:189], v[12:15]
	v_mfma_f32_16x16x32_bf16 v[8:11], v[162:165], v[186:189], v[8:11]
	v_mfma_f32_16x16x32_bf16 v[4:7], v[152:155], v[194:197], v[4:7]
	v_mfma_f32_16x16x32_bf16 v[0:3], v[162:165], v[194:197], v[0:3]
	s_setprio 0
	s_barrier
	s_add_i32 s46, s46, 2
	s_add_u32 s71, s71, 0x100
	s_addc_u32 s79, s79, 0
	s_add_u32 s10, s10, 0x100
	s_addc_u32 s11, s11, 0
	s_cmp_gt_u32 s46, 29
	s_cbranch_scc0 .LBB0_751
	s_and_b64 vcc, exec, s[4:5]
	s_cbranch_vccz .LBB0_754
	s_barrier

; #define PG8_STAGE(bufoff, gbase, voff) do { _Pragma("unroll") for (int _i = 0; _i < 2; ++_i) \
;         __builtin_amdgcn_global_load_lds((const GAS unsigned*)((const GAS char*)(gbase) + (size_t)_i * r64##voff + (vo##voff)), (LAS unsigned*)(lds + (bufoff) + ldsw + _i * 8192), 16, 0, 0); } while (0)
; #define PG8_LDA(dst, b, h) do { _Pragma("unroll") for (int m = 0; m < 4; ++m) _Pragma("unroll") for (int k = 0; k < 2; ++k) dst[m][k] = *(const LAS bf16x8*)(lds + PG8_SA(b, h) + aoff + m * 2048 + k * 1024); } while (0)
; #define PG8_LDB(dst, b, h) do { _Pragma("unroll") for (int n = 0; n < 2; ++n) _Pragma("unroll") for (int k = 0; k < 2; ++k) dst[n][k] = *(const LAS bf16x8*)(lds + PG8_SB(b, h) + boff + n * 2048 + k * 1024); } while (0)
; #define PG8_MMA(ai, bj, At, Bt) do { __builtin_amdgcn_s_setprio(1); _Pragma("unroll") for (int m = 0; m < 4; ++m) _Pragma("unroll") for (int n = 0; n < 2; ++n) _Pragma("unroll") for (int k = 0; k < 2; ++k) \
;         acc[ai][bj][m][n] = __builtin_amdgcn_mfma_f32_16x16x32_bf16(Bt[n][k], At[m][k], acc[ai][bj][m][n], 0, 0, 0); __builtin_amdgcn_s_setprio(0); } while (0)
; #define PG8_WAIT_V(n) asm volatile("s_waitcnt vmcnt(" #n ")" ::: "memory")
; #define PG8_WAIT_L(n) asm volatile("s_waitcnt lgkmcnt(" #n ")" ::: "memory")
; #define PG8_BAR __builtin_amdgcn_s_barrier()
; template <class Epi, class Map, bool ALIGN_EPI>
; __device__ __forceinline__ void gemm_phase(const int tid, LAS unsigned char* lds, const int lda, const int ldb, const int K, const Map& MP, const StaticOrder& S, const Epi& E) {
;     ...
;             const bool last = (t == nt - 2);
;             const char* a1 = cA + (size_t)(t + 1) * kstep;
;             const char* a2 = last ? nA : cA + (size_t)(t + 2) * kstep; const char* b2 = last ? nB : cB + (size_t)(t + 2) * kstep;
;             const char* a3 = a2 + kstep; const char* b3 = b2 + kstep;
;             PG8_LDB(B0, 0, 0); PG8_LDB(B1, 0, 1); PG8_SCHED; PG8_LDA(At, 0, 0); PG8_STAGE(PG8_SA(1, 1), a1 + hstepA, A);
;             PG8_WAIT_V(8); PG8_WAIT_L(0); PG8_BAR; PG8_MMA(0, 0, At, B0); PG8_MMA(0, 1, At, B1); PG8_BAR; PG8_SCHED;
;             PG8_LDA(At, 0, 1); PG8_STAGE(PG8_SB(0, 0), b2, B); PG8_STAGE(PG8_SB(0, 1), b2 + hstepB, B); PG8_STAGE(PG8_SA(0, 0), a2, A);
;             PG8_WAIT_V(8); PG8_WAIT_L(0); PG8_BAR; PG8_MMA(1, 0, At, B0); PG8_MMA(1, 1, At, B1); PG8_BAR; PG8_SCHED;
.LBB0_835:
	s_add_u32 s44, s42, 0xfffc0080
	s_addc_u32 s45, s43, -1
	s_add_i32 s47, 0, 0x10000
	s_cmp_eq_u32 s46, 12
	s_cselect_b32 s45, s23, s45
	s_cselect_b32 s44, s22, s44
	s_cselect_b32 s57, s49, s21
	s_cselect_b32 s56, s48, s17
	s_add_i32 s53, 0, 0x14000
	s_waitcnt vmcnt(0)
	v_add_u32_e32 v60, s47, v150
	v_add_u32_e32 v148, s53, v150
	ds_read_b128 v[48:51], v60
	ds_read_b128 v[52:55], v60 offset:1024
	ds_read_b128 v[56:59], v60 offset:2048
	ds_read_b128 v[60:63], v60 offset:3072
	ds_read_b128 v[152:155], v148
	ds_read_b128 v[156:159], v148 offset:1024
	ds_read_b128 v[160:163], v148 offset:2048
	ds_read_b128 v[164:167], v148 offset:3072
	v_lshl_add_u64 v[148:149], s[42:43], 0, v[146:147]
	s_add_i32 m0, s19, 0xc000
	ds_read_b128 v[168:171], v151
	ds_read_b128 v[172:175], v151 offset:1024
	ds_read_b128 v[176:179], v151 offset:2048
	ds_read_b128 v[180:183], v151 offset:3072
	ds_read_b128 v[184:187], v151 offset:4096
	ds_read_b128 v[188:191], v151 offset:5120
	ds_read_b128 v[192:195], v151 offset:6144
	ds_read_b128 v[196:199], v151 offset:7168
	global_load_lds_dwordx4 v[148:149], off
	v_lshl_add_u64 v[148:149], v[148:149], 0, s[90:91]
	s_add_i32 m0, s19, 0xe000
	s_nop 0
	global_load_lds_dwordx4 v[148:149], off
	s_waitcnt vmcnt(8)
	s_waitcnt lgkmcnt(0)
	s_barrier
	s_setprio 1
	v_mfma_f32_16x16x32_bf16 v[136:139], v[48:51], v[168:171], v[136:139]
	v_mfma_f32_16x16x32_bf16 v[140:143], v[56:59], v[168:171], v[140:143]
	v_mfma_f32_16x16x32_bf16 v[120:123], v[48:51], v[176:179], v[120:123]
	v_mfma_f32_16x16x32_bf16 v[124:127], v[56:59], v[176:179], v[124:127]
	v_mfma_f32_16x16x32_bf16 v[104:107], v[48:51], v[184:187], v[104:107]
	v_mfma_f32_16x16x32_bf16 v[108:111], v[56:59], v[184:187], v[108:111]
	v_mfma_f32_16x16x32_bf16 v[88:91], v[48:51], v[192:195], v[88:91]
	v_mfma_f32_16x16x32_bf16 v[92:95], v[56:59], v[192:195], v[92:95]
	v_mfma_f32_16x16x32_bf16 v[136:139], v[52:55], v[172:175], v[136:139]
	v_mfma_f32_16x16x32_bf16 v[140:143], v[60:63], v[172:175], v[140:143]
	v_mfma_f32_16x16x32_bf16 v[120:123], v[52:55], v[180:183], v[120:123]
	v_mfma_f32_16x16x32_bf16 v[124:127], v[60:63], v[180:183], v[124:127]
	v_mfma_f32_16x16x32_bf16 v[104:107], v[52:55], v[188:191], v[104:107]
	v_mfma_f32_16x16x32_bf16 v[108:111], v[60:63], v[188:191], v[108:111]
	v_mfma_f32_16x16x32_bf16 v[88:91], v[52:55], v[196:199], v[88:91]
	v_mfma_f32_16x16x32_bf16 v[92:95], v[60:63], v[196:199], v[92:95]
	s_setprio 0
	s_setprio 1
	v_mfma_f32_16x16x32_bf16 v[132:135], v[152:155], v[168:171], v[132:135]
	v_mfma_f32_16x16x32_bf16 v[128:131], v[160:163], v[168:171], v[128:131]
	v_mfma_f32_16x16x32_bf16 v[116:119], v[152:155], v[176:179], v[116:119]
	v_mfma_f32_16x16x32_bf16 v[112:115], v[160:163], v[176:179], v[112:115]
	v_mfma_f32_16x16x32_bf16 v[100:103], v[152:155], v[184:187], v[100:103]
	v_mfma_f32_16x16x32_bf16 v[96:99], v[160:163], v[184:187], v[96:99]
	v_mfma_f32_16x16x32_bf16 v[84:87], v[152:155], v[192:195], v[84:87]
	v_mfma_f32_16x16x32_bf16 v[80:83], v[160:163], v[192:195], v[80:83]
	v_mfma_f32_16x16x32_bf16 v[132:135], v[156:159], v[172:175], v[132:135]
	v_mfma_f32_16x16x32_bf16 v[128:131], v[164:167], v[172:175], v[128:131]
	v_mfma_f32_16x16x32_bf16 v[116:119], v[156:159], v[180:183], v[116:119]
	v_mfma_f32_16x16x32_bf16 v[112:115], v[164:167], v[180:183], v[112:115]
	v_mfma_f32_16x16x32_bf16 v[100:103], v[156:159], v[188:191], v[100:103]
	v_mfma_f32_16x16x32_bf16 v[96:99], v[164:167], v[188:191], v[96:99]
	v_mfma_f32_16x16x32_bf16 v[84:87], v[156:159], v[196:199], v[84:87]
	v_mfma_f32_16x16x32_bf16 v[80:83], v[164:167], v[196:199], v[80:83]
	s_setprio 0
	s_barrier
	s_add_i32 s47, s47, s18
	v_lshl_add_u64 v[148:149], s[56:57], 0, v[144:145]
	s_mov_b32 m0, s47
	ds_read_b128 v[168:171], v151 offset:16384
	ds_read_b128 v[172:175], v151 offset:17408
	ds_read_b128 v[176:179], v151 offset:18432
	ds_read_b128 v[180:183], v151 offset:19456
	ds_read_b128 v[184:187], v151 offset:20480
	ds_read_b128 v[188:191], v151 offset:21504
	ds_read_b128 v[192:195], v151 offset:22528
	ds_read_b128 v[196:199], v151 offset:23552
	global_load_lds_dwordx4 v[148:149], off
	v_lshl_add_u64 v[200:201], v[148:149], 0, s[90:91]
	s_add_i32 m0, s47, 0x2000
	s_add_i32 s47, s53, s18
	global_load_lds_dwordx4 v[200:201], off
	v_lshl_add_u64 v[200:201], v[148:149], 0, s[74:75]
	s_mov_b32 m0, s47
	s_nop 0
	global_load_lds_dwordx4 v[200:201], off
	v_lshl_add_u64 v[200:201], v[148:149], 0, s[94:95]
	s_add_i32 m0, s47, 0x2000
	s_nop 0
	global_load_lds_dwordx4 v[200:201], off
	v_lshl_add_u64 v[200:201], s[44:45], 0, v[146:147]
	s_mov_b32 m0, s19
	v_lshl_add_u64 v[202:203], v[200:201], 0, s[90:91]
	global_load_lds_dwordx4 v[200:201], off
	s_mov_b32 m0, s24
	s_nop 0
	global_load_lds_dwordx4 v[202:203], off
	s_waitcnt vmcnt(8)
	s_waitcnt lgkmcnt(0)
	s_barrier
; #define PG8_STAGE(bufoff, gbase, voff) do { _Pragma("unroll") for (int _i = 0; _i < 2; ++_i) \
;         __builtin_amdgcn_global_load_lds((const GAS unsigned*)((const GAS char*)(gbase) + (size_t)_i * r64##voff + (vo##voff)), (LAS unsigned*)(lds + (bufoff) + ldsw + _i * 8192), 16, 0, 0); } while (0)
; #define PG8_LDA(dst, b, h) do { _Pragma("unroll") for (int m = 0; m < 4; ++m) _Pragma("unroll") for (int k = 0; k < 2; ++k) dst[m][k] = *(const LAS bf16x8*)(lds + PG8_SA(b, h) + aoff + m * 2048 + k * 1024); } while (0)
; #define PG8_LDB(dst, b, h) do { _Pragma("unroll") for (int n = 0; n < 2; ++n) _Pragma("unroll") for (int k = 0; k < 2; ++k) dst[n][k] = *(const LAS bf16x8*)(lds + PG8_SB(b, h) + boff + n * 2048 + k * 1024); } while (0)
; #define PG8_MMA(ai, bj, At, Bt) do { __builtin_amdgcn_s_setprio(1); _Pragma("unroll") for (int m = 0; m < 4; ++m) _Pragma("unroll") for (int n = 0; n < 2; ++n) _Pragma("unroll") for (int k = 0; k < 2; ++k) \
;         acc[ai][bj][m][n] = __builtin_amdgcn_mfma_f32_16x16x32_bf16(Bt[n][k], At[m][k], acc[ai][bj][m][n], 0, 0, 0); __builtin_amdgcn_s_setprio(0); } while (0)
; #define PG8_WAIT_V(n) asm volatile("s_waitcnt vmcnt(" #n ")" ::: "memory")
; #define PG8_WAIT_L(n) asm volatile("s_waitcnt lgkmcnt(" #n ")" ::: "memory")
; #define PG8_BAR __builtin_amdgcn_s_barrier()
; #define PG8_SCHED __builtin_amdgcn_sched_barrier(0)
; template <class Epi, class Map, bool ALIGN_EPI>
; __device__ __forceinline__ void gemm_phase(const int tid, LAS unsigned char* lds, const int lda, const int ldb, const int K, const Map& MP, const StaticOrder& S, const Epi& E) {
;     ...
;             PG8_WAIT_V(8); PG8_WAIT_L(0); PG8_BAR; PG8_MMA(1, 0, At, B0); PG8_MMA(1, 1, At, B1); PG8_BAR; PG8_SCHED;
;             PG8_LDB(B0, 1, 0); PG8_LDB(B1, 1, 1); PG8_SCHED; PG8_LDA(At, 1, 0); PG8_STAGE(PG8_SA(0, 1), a2 + hstepA, A);
;             PG8_WAIT_V(8); PG8_WAIT_L(0); PG8_BAR; PG8_MMA(0, 0, At, B0); PG8_MMA(0, 1, At, B1); PG8_BAR; PG8_SCHED;
	s_setprio 1
	v_mfma_f32_16x16x32_bf16 v[72:75], v[48:51], v[168:171], v[72:75]
	v_mfma_f32_16x16x32_bf16 v[76:79], v[56:59], v[168:171], v[76:79]
	v_mfma_f32_16x16x32_bf16 v[40:43], v[48:51], v[176:179], v[40:43]
	v_mfma_f32_16x16x32_bf16 v[44:47], v[56:59], v[176:179], v[44:47]
	v_mfma_f32_16x16x32_bf16 v[24:27], v[48:51], v[184:187], v[24:27]
	v_mfma_f32_16x16x32_bf16 v[28:31], v[56:59], v[184:187], v[28:31]
	v_mfma_f32_16x16x32_bf16 v[8:11], v[48:51], v[192:195], v[8:11]
	v_mfma_f32_16x16x32_bf16 v[12:15], v[56:59], v[192:195], v[12:15]
	v_mfma_f32_16x16x32_bf16 v[72:75], v[52:55], v[172:175], v[72:75]
	v_mfma_f32_16x16x32_bf16 v[76:79], v[60:63], v[172:175], v[76:79]
	v_mfma_f32_16x16x32_bf16 v[40:43], v[52:55], v[180:183], v[40:43]
	v_mfma_f32_16x16x32_bf16 v[44:47], v[60:63], v[180:183], v[44:47]
	v_mfma_f32_16x16x32_bf16 v[24:27], v[52:55], v[188:191], v[24:27]
	v_mfma_f32_16x16x32_bf16 v[28:31], v[60:63], v[188:191], v[28:31]
	v_mfma_f32_16x16x32_bf16 v[8:11], v[52:55], v[196:199], v[8:11]
	v_mfma_f32_16x16x32_bf16 v[12:15], v[60:63], v[196:199], v[12:15]
	s_setprio 0
	s_setprio 1
	v_mfma_f32_16x16x32_bf16 v[36:39], v[152:155], v[176:179], v[36:39]
	v_mfma_f32_16x16x32_bf16 v[32:35], v[160:163], v[176:179], v[32:35]
	v_mfma_f32_16x16x32_bf16 v[20:23], v[152:155], v[184:187], v[20:23]
	v_mfma_f32_16x16x32_bf16 v[16:19], v[160:163], v[184:187], v[16:19]
	v_mfma_f32_16x16x32_bf16 v[4:7], v[152:155], v[192:195], v[4:7]
	v_mfma_f32_16x16x32_bf16 v[0:3], v[160:163], v[192:195], v[0:3]
	v_mfma_f32_16x16x32_bf16 v[48:51], v[152:155], v[168:171], v[68:71]
	v_mfma_f32_16x16x32_bf16 v[52:55], v[160:163], v[168:171], v[64:67]
	v_mfma_f32_16x16x32_bf16 v[36:39], v[156:159], v[180:183], v[36:39]
	v_mfma_f32_16x16x32_bf16 v[32:35], v[164:167], v[180:183], v[32:35]
	v_mfma_f32_16x16x32_bf16 v[20:23], v[156:159], v[188:191], v[20:23]
	v_mfma_f32_16x16x32_bf16 v[16:19], v[164:167], v[188:191], v[16:19]
	v_mfma_f32_16x16x32_bf16 v[4:7], v[156:159], v[196:199], v[4:7]
	v_mfma_f32_16x16x32_bf16 v[0:3], v[164:167], v[196:199], v[0:3]
	v_mfma_f32_16x16x32_bf16 v[48:51], v[156:159], v[172:175], v[48:51]
	v_mfma_f32_16x16x32_bf16 v[52:55], v[164:167], v[172:175], v[52:55]
	s_setprio 0
	s_barrier
	s_add_i32 s44, 0, 0x18000
	s_add_i32 s45, 0, 0x1c000
	v_add_u32_e32 v68, s44, v150
	v_add_u32_e32 v164, s45, v150
	ds_read_b128 v[56:59], v68
	ds_read_b128 v[60:63], v68 offset:1024
	ds_read_b128 v[64:67], v68 offset:2048
	ds_read_b128 v[68:71], v68 offset:3072
	ds_read_b128 v[152:155], v164
	ds_read_b128 v[156:159], v164 offset:1024
	ds_read_b128 v[160:163], v164 offset:2048
	ds_read_b128 v[164:167], v164 offset:3072
	s_mov_b32 m0, s28
	v_lshl_add_u64 v[202:203], v[200:201], 0, s[74:75]
	ds_read_b128 v[168:171], v151 offset:32768
	ds_read_b128 v[172:175], v151 offset:33792
	ds_read_b128 v[176:179], v151 offset:34816
	ds_read_b128 v[180:183], v151 offset:35840
	ds_read_b128 v[184:187], v151 offset:36864
	ds_read_b128 v[188:191], v151 offset:37888
	ds_read_b128 v[192:195], v151 offset:38912
	ds_read_b128 v[196:199], v151 offset:39936
	global_load_lds_dwordx4 v[202:203], off
	v_lshl_add_u64 v[202:203], v[200:201], 0, s[94:95]
	s_mov_b32 m0, s29
	s_nop 0
	global_load_lds_dwordx4 v[202:203], off
	s_waitcnt vmcnt(8)
	s_waitcnt lgkmcnt(0)
	s_barrier
	s_setprio 1
	v_mfma_f32_16x16x32_bf16 v[136:139], v[56:59], v[168:171], v[136:139]
	v_mfma_f32_16x16x32_bf16 v[140:143], v[64:67], v[168:171], v[140:143]
	v_mfma_f32_16x16x32_bf16 v[120:123], v[56:59], v[176:179], v[120:123]
	v_mfma_f32_16x16x32_bf16 v[124:127], v[64:67], v[176:179], v[124:127]
	v_mfma_f32_16x16x32_bf16 v[104:107], v[56:59], v[184:187], v[104:107]
	v_mfma_f32_16x16x32_bf16 v[108:111], v[64:67], v[184:187], v[108:111]
	v_mfma_f32_16x16x32_bf16 v[88:91], v[56:59], v[192:195], v[88:91]
	v_mfma_f32_16x16x32_bf16 v[92:95], v[64:67], v[192:195], v[92:95]
	v_mfma_f32_16x16x32_bf16 v[136:139], v[60:63], v[172:175], v[136:139]
	v_mfma_f32_16x16x32_bf16 v[140:143], v[68:71], v[172:175], v[140:143]
	v_mfma_f32_16x16x32_bf16 v[120:123], v[60:63], v[180:183], v[120:123]
	v_mfma_f32_16x16x32_bf16 v[124:127], v[68:71], v[180:183], v[124:127]
	v_mfma_f32_16x16x32_bf16 v[104:107], v[60:63], v[188:191], v[104:107]
	v_mfma_f32_16x16x32_bf16 v[108:111], v[68:71], v[188:191], v[108:111]
	v_mfma_f32_16x16x32_bf16 v[88:91], v[60:63], v[196:199], v[88:91]
	v_mfma_f32_16x16x32_bf16 v[92:95], v[68:71], v[196:199], v[92:95]
	s_setprio 0
	s_setprio 1
	v_mfma_f32_16x16x32_bf16 v[132:135], v[152:155], v[168:171], v[132:135]
	v_mfma_f32_16x16x32_bf16 v[128:131], v[160:163], v[168:171], v[128:131]
	v_mfma_f32_16x16x32_bf16 v[116:119], v[152:155], v[176:179], v[116:119]
	v_mfma_f32_16x16x32_bf16 v[112:115], v[160:163], v[176:179], v[112:115]
	v_mfma_f32_16x16x32_bf16 v[100:103], v[152:155], v[184:187], v[100:103]
	v_mfma_f32_16x16x32_bf16 v[96:99], v[160:163], v[184:187], v[96:99]
	v_mfma_f32_16x16x32_bf16 v[84:87], v[152:155], v[192:195], v[84:87]
	v_mfma_f32_16x16x32_bf16 v[80:83], v[160:163], v[192:195], v[80:83]
	v_mfma_f32_16x16x32_bf16 v[132:135], v[156:159], v[172:175], v[132:135]
	v_mfma_f32_16x16x32_bf16 v[128:131], v[164:167], v[172:175], v[128:131]
	v_mfma_f32_16x16x32_bf16 v[116:119], v[156:159], v[180:183], v[116:119]
	v_mfma_f32_16x16x32_bf16 v[112:115], v[164:167], v[180:183], v[112:115]
	v_mfma_f32_16x16x32_bf16 v[100:103], v[156:159], v[188:191], v[100:103]
	v_mfma_f32_16x16x32_bf16 v[96:99], v[164:167], v[188:191], v[96:99]
	v_mfma_f32_16x16x32_bf16 v[84:87], v[156:159], v[196:199], v[84:87]
	v_mfma_f32_16x16x32_bf16 v[80:83], v[164:167], v[196:199], v[80:83]
	s_setprio 0
	s_barrier
; #define PG8_STAGE(bufoff, gbase, voff) do { _Pragma("unroll") for (int _i = 0; _i < 2; ++_i) \
;         __builtin_amdgcn_global_load_lds((const GAS unsigned*)((const GAS char*)(gbase) + (size_t)_i * r64##voff + (vo##voff)), (LAS unsigned*)(lds + (bufoff) + ldsw + _i * 8192), 16, 0, 0); } while (0)
; #define PG8_LDA(dst, b, h) do { _Pragma("unroll") for (int m = 0; m < 4; ++m) _Pragma("unroll") for (int k = 0; k < 2; ++k) dst[m][k] = *(const LAS bf16x8*)(lds + PG8_SA(b, h) + aoff + m * 2048 + k * 1024); } while (0)
; #define PG8_MMA(ai, bj, At, Bt) do { __builtin_amdgcn_s_setprio(1); _Pragma("unroll") for (int m = 0; m < 4; ++m) _Pragma("unroll") for (int n = 0; n < 2; ++n) _Pragma("unroll") for (int k = 0; k < 2; ++k) \
;         acc[ai][bj][m][n] = __builtin_amdgcn_mfma_f32_16x16x32_bf16(Bt[n][k], At[m][k], acc[ai][bj][m][n], 0, 0, 0); __builtin_amdgcn_s_setprio(0); } while (0)
; #define PG8_WAIT_V(n) asm volatile("s_waitcnt vmcnt(" #n ")" ::: "memory")
; #define PG8_WAIT_L(n) asm volatile("s_waitcnt lgkmcnt(" #n ")" ::: "memory")
; #define PG8_BAR __builtin_amdgcn_s_barrier()
; #define PG8_SCHED __builtin_amdgcn_sched_barrier(0)
; template <class Epi, class Map, bool ALIGN_EPI>
; __device__ __forceinline__ void gemm_phase(const int tid, LAS unsigned char* lds, const int lda, const int ldb, const int K, const Map& MP, const StaticOrder& S, const Epi& E) {
;     ...
;             PG8_LDA(At, 1, 1); PG8_STAGE(PG8_SB(1, 0), b3, B); PG8_STAGE(PG8_SB(1, 1), b3 + hstepB, B); PG8_STAGE(PG8_SA(1, 0), a3, A);
;             PG8_WAIT_V(8); PG8_WAIT_L(0); PG8_BAR; PG8_MMA(1, 0, At, B0); PG8_MMA(1, 1, At, B1); PG8_BAR; PG8_SCHED;
;         }
;         if constexpr (ALIGN_EPI) { if (wr == 0) PG8_BAR; }
	s_add_i32 s44, s44, s18
	v_lshl_add_u64 v[202:203], v[148:149], 0, s[50:51]
	s_mov_b32 m0, s44
	ds_read_b128 v[168:171], v151 offset:49152
	ds_read_b128 v[172:175], v151 offset:50176
	ds_read_b128 v[176:179], v151 offset:51200
	ds_read_b128 v[180:183], v151 offset:52224
	ds_read_b128 v[184:187], v151 offset:53248
	ds_read_b128 v[188:191], v151 offset:54272
	ds_read_b128 v[192:195], v151 offset:55296
	ds_read_b128 v[196:199], v151 offset:56320
	global_load_lds_dwordx4 v[202:203], off
	v_lshl_add_u64 v[202:203], v[148:149], 0, s[54:55]
	s_add_i32 m0, s44, 0x2000
	s_add_i32 s44, s45, s18
	global_load_lds_dwordx4 v[202:203], off
	v_lshl_add_u64 v[202:203], v[148:149], 0, s[96:97]
	s_mov_b32 m0, s44
	v_lshl_add_u64 v[148:149], v[148:149], 0, s[6:7]
	global_load_lds_dwordx4 v[202:203], off
	s_add_i32 m0, s44, 0x2000
	s_nop 0
	global_load_lds_dwordx4 v[148:149], off
	v_lshl_add_u64 v[148:149], v[200:201], 0, s[50:51]
	s_mov_b32 m0, s33
	s_nop 0
	global_load_lds_dwordx4 v[148:149], off
	v_lshl_add_u64 v[148:149], v[200:201], 0, s[54:55]
	s_mov_b32 m0, s34
	s_nop 0
	global_load_lds_dwordx4 v[148:149], off
	s_waitcnt vmcnt(8)
	s_waitcnt lgkmcnt(0)
	s_barrier
	s_setprio 1
	v_mfma_f32_16x16x32_bf16 v[72:75], v[56:59], v[168:171], v[72:75]
	v_mfma_f32_16x16x32_bf16 v[76:79], v[64:67], v[168:171], v[76:79]
	v_mfma_f32_16x16x32_bf16 v[40:43], v[56:59], v[176:179], v[40:43]
	v_mfma_f32_16x16x32_bf16 v[44:47], v[64:67], v[176:179], v[44:47]
	v_mfma_f32_16x16x32_bf16 v[24:27], v[56:59], v[184:187], v[24:27]
	v_mfma_f32_16x16x32_bf16 v[28:31], v[64:67], v[184:187], v[28:31]
	v_mfma_f32_16x16x32_bf16 v[8:11], v[56:59], v[192:195], v[8:11]
	v_mfma_f32_16x16x32_bf16 v[12:15], v[64:67], v[192:195], v[12:15]
	v_mfma_f32_16x16x32_bf16 v[72:75], v[60:63], v[172:175], v[72:75]
	v_mfma_f32_16x16x32_bf16 v[76:79], v[68:71], v[172:175], v[76:79]
	v_mfma_f32_16x16x32_bf16 v[40:43], v[60:63], v[180:183], v[40:43]
	v_mfma_f32_16x16x32_bf16 v[44:47], v[68:71], v[180:183], v[44:47]
	v_mfma_f32_16x16x32_bf16 v[24:27], v[60:63], v[188:191], v[24:27]
	v_mfma_f32_16x16x32_bf16 v[28:31], v[68:71], v[188:191], v[28:31]
	v_mfma_f32_16x16x32_bf16 v[8:11], v[60:63], v[196:199], v[8:11]
	v_mfma_f32_16x16x32_bf16 v[12:15], v[68:71], v[196:199], v[12:15]
	s_setprio 0
	s_setprio 1
	v_mfma_f32_16x16x32_bf16 v[48:51], v[152:155], v[168:171], v[48:51]
	v_mfma_f32_16x16x32_bf16 v[68:71], v[156:159], v[172:175], v[48:51]
	v_mfma_f32_16x16x32_bf16 v[48:51], v[160:163], v[168:171], v[52:55]
	v_mfma_f32_16x16x32_bf16 v[36:39], v[152:155], v[176:179], v[36:39]
	v_mfma_f32_16x16x32_bf16 v[32:35], v[160:163], v[176:179], v[32:35]
	v_mfma_f32_16x16x32_bf16 v[20:23], v[152:155], v[184:187], v[20:23]
	v_mfma_f32_16x16x32_bf16 v[16:19], v[160:163], v[184:187], v[16:19]
	v_mfma_f32_16x16x32_bf16 v[4:7], v[152:155], v[192:195], v[4:7]
	v_mfma_f32_16x16x32_bf16 v[0:3], v[160:163], v[192:195], v[0:3]
	v_mfma_f32_16x16x32_bf16 v[64:67], v[164:167], v[172:175], v[48:51]
	v_mfma_f32_16x16x32_bf16 v[36:39], v[156:159], v[180:183], v[36:39]
	v_mfma_f32_16x16x32_bf16 v[32:35], v[164:167], v[180:183], v[32:35]
	v_mfma_f32_16x16x32_bf16 v[20:23], v[156:159], v[188:191], v[20:23]
	v_mfma_f32_16x16x32_bf16 v[16:19], v[164:167], v[188:191], v[16:19]
	v_mfma_f32_16x16x32_bf16 v[4:7], v[156:159], v[196:199], v[4:7]
	v_mfma_f32_16x16x32_bf16 v[0:3], v[164:167], v[196:199], v[0:3]
	s_setprio 0
	s_barrier
	s_add_i32 s46, s46, 2
	s_add_u32 s17, s17, 0x100
	s_addc_u32 s21, s21, 0
	s_add_u32 s42, s42, 0x100
	s_addc_u32 s43, s43, 0
	s_cmp_gt_u32 s46, 13
	s_cbranch_scc0 .LBB0_835
	s_and_b64 vcc, exec, s[10:11]
	s_cbranch_vccz .LBB0_838
	s_barrier

; #define PG8_STAGE(bufoff, gbase, voff) do { _Pragma("unroll") for (int _i = 0; _i < 2; ++_i) \
;         __builtin_amdgcn_global_load_lds((const GAS unsigned*)((const GAS char*)(gbase) + (size_t)_i * r64##voff + (vo##voff)), (LAS unsigned*)(lds + (bufoff) + ldsw + _i * 8192), 16, 0, 0); } while (0)
; #define PG8_LDA(dst, b, h) do { _Pragma("unroll") for (int m = 0; m < 4; ++m) _Pragma("unroll") for (int k = 0; k < 2; ++k) dst[m][k] = *(const LAS bf16x8*)(lds + PG8_SA(b, h) + aoff + m * 2048 + k * 1024); } while (0)
; #define PG8_LDB(dst, b, h) do { _Pragma("unroll") for (int n = 0; n < 2; ++n) _Pragma("unroll") for (int k = 0; k < 2; ++k) dst[n][k] = *(const LAS bf16x8*)(lds + PG8_SB(b, h) + boff + n * 2048 + k * 1024); } while (0)
; #define PG8_MMA(ai, bj, At, Bt) do { __builtin_amdgcn_s_setprio(1); _Pragma("unroll") for (int m = 0; m < 4; ++m) _Pragma("unroll") for (int n = 0; n < 2; ++n) _Pragma("unroll") for (int k = 0; k < 2; ++k) \
;         acc[ai][bj][m][n] = __builtin_amdgcn_mfma_f32_16x16x32_bf16(Bt[n][k], At[m][k], acc[ai][bj][m][n], 0, 0, 0); __builtin_amdgcn_s_setprio(0); } while (0)
; #define PG8_WAIT_V(n) asm volatile("s_waitcnt vmcnt(" #n ")" ::: "memory")
; #define PG8_WAIT_L(n) asm volatile("s_waitcnt lgkmcnt(" #n ")" ::: "memory")
; #define PG8_BAR __builtin_amdgcn_s_barrier()
; template <class Epi, class Map, bool ALIGN_EPI>
; __device__ __forceinline__ void gemm_phase(const int tid, LAS unsigned char* lds, const int lda, const int ldb, const int K, const Map& MP, const StaticOrder& S, const Epi& E) {
;     ...
;             const bool last = (t == nt - 2);
;             const char* a1 = cA + (size_t)(t + 1) * kstep;
;             const char* a2 = last ? nA : cA + (size_t)(t + 2) * kstep; const char* b2 = last ? nB : cB + (size_t)(t + 2) * kstep;
;             const char* a3 = a2 + kstep; const char* b3 = b2 + kstep;
;             PG8_LDB(B0, 0, 0); PG8_LDB(B1, 0, 1); PG8_SCHED; PG8_LDA(At, 0, 0); PG8_STAGE(PG8_SA(1, 1), a1 + hstepA, A);
;             PG8_WAIT_V(8); PG8_WAIT_L(0); PG8_BAR; PG8_MMA(0, 0, At, B0); PG8_MMA(0, 1, At, B1); PG8_BAR; PG8_SCHED;
;             PG8_LDA(At, 0, 1); PG8_STAGE(PG8_SB(0, 0), b2, B); PG8_STAGE(PG8_SB(0, 1), b2 + hstepB, B); PG8_STAGE(PG8_SA(0, 0), a2, A);
;             PG8_WAIT_V(8); PG8_WAIT_L(0); PG8_BAR; PG8_MMA(1, 0, At, B0); PG8_MMA(1, 1, At, B1); PG8_BAR; PG8_SCHED;
.LBB0_1042:
	s_add_i32 s47, s42, 2
	s_add_u32 s78, s10, 0x80
	s_addc_u32 s43, s11, 0
	s_add_i32 s80, 0, 0x10000
	s_cmp_eq_u32 s24, s42
	s_cselect_b32 s43, s69, s43
	s_cselect_b32 s42, s68, s78
	s_cselect_b32 s79, s77, s46
	s_cselect_b32 s78, s76, s45
	s_add_i32 s81, 0, 0x14000
	v_add_u32_e32 v140, s80, v178
	v_add_u32_e32 v156, s81, v178
	ds_read_b128 v[128:131], v140
	ds_read_b128 v[132:135], v140 offset:1024
	ds_read_b128 v[136:139], v140 offset:2048
	ds_read_b128 v[140:143], v140 offset:3072
	ds_read_b128 v[144:147], v156
	ds_read_b128 v[148:151], v156 offset:1024
	ds_read_b128 v[152:155], v156 offset:2048
	ds_read_b128 v[156:159], v156 offset:3072
	v_lshl_add_u64 v[176:177], s[10:11], 0, v[164:165]
	s_add_i32 m0, s34, 0xc000
	ds_read_b128 v[168:171], v179
	ds_read_b128 v[172:175], v179 offset:1024
	ds_read_b128 v[180:183], v179 offset:2048
	ds_read_b128 v[184:187], v179 offset:3072
	ds_read_b128 v[188:191], v179 offset:4096
	ds_read_b128 v[192:195], v179 offset:5120
	ds_read_b128 v[196:199], v179 offset:6144
	ds_read_b128 v[200:203], v179 offset:7168
	global_load_lds_dwordx4 v[176:177], off
	v_lshl_add_u64 v[176:177], s[10:11], 0, v[166:167]
	s_add_i32 m0, s34, 0xe000
	s_nop 0
	global_load_lds_dwordx4 v[176:177], off
	s_waitcnt vmcnt(8)
	s_waitcnt lgkmcnt(0)
	s_barrier
	s_setprio 1
	v_mfma_f32_16x16x32_bf16 v[40:43], v[128:131], v[168:171], v[40:43]
	v_mfma_f32_16x16x32_bf16 v[24:27], v[136:139], v[168:171], v[24:27]
	v_mfma_f32_16x16x32_bf16 v[32:35], v[128:131], v[180:183], v[32:35]
	v_mfma_f32_16x16x32_bf16 v[28:31], v[136:139], v[180:183], v[28:31]
	v_mfma_f32_16x16x32_bf16 v[52:55], v[128:131], v[188:191], v[52:55]
	v_mfma_f32_16x16x32_bf16 v[48:51], v[136:139], v[188:191], v[48:51]
	v_mfma_f32_16x16x32_bf16 v[68:71], v[128:131], v[196:199], v[68:71]
	v_mfma_f32_16x16x32_bf16 v[64:67], v[136:139], v[196:199], v[64:67]
	v_mfma_f32_16x16x32_bf16 v[40:43], v[132:135], v[172:175], v[40:43]
	v_mfma_f32_16x16x32_bf16 v[24:27], v[140:143], v[172:175], v[24:27]
	v_mfma_f32_16x16x32_bf16 v[32:35], v[132:135], v[184:187], v[32:35]
	v_mfma_f32_16x16x32_bf16 v[28:31], v[140:143], v[184:187], v[28:31]
	v_mfma_f32_16x16x32_bf16 v[52:55], v[132:135], v[192:195], v[52:55]
	v_mfma_f32_16x16x32_bf16 v[48:51], v[140:143], v[192:195], v[48:51]
	v_mfma_f32_16x16x32_bf16 v[68:71], v[132:135], v[200:203], v[68:71]
	v_mfma_f32_16x16x32_bf16 v[64:67], v[140:143], v[200:203], v[64:67]
	s_setprio 0
	s_setprio 1
	v_mfma_f32_16x16x32_bf16 v[0:3], v[144:147], v[168:171], v[0:3]
	v_mfma_f32_16x16x32_bf16 v[4:7], v[152:155], v[168:171], v[4:7]
	v_mfma_f32_16x16x32_bf16 v[8:11], v[144:147], v[180:183], v[8:11]
	v_mfma_f32_16x16x32_bf16 v[12:15], v[152:155], v[180:183], v[12:15]
	v_mfma_f32_16x16x32_bf16 v[16:19], v[144:147], v[188:191], v[16:19]
	v_mfma_f32_16x16x32_bf16 v[20:23], v[152:155], v[188:191], v[20:23]
	v_mfma_f32_16x16x32_bf16 v[36:39], v[144:147], v[196:199], v[36:39]
	v_mfma_f32_16x16x32_bf16 v[44:47], v[152:155], v[196:199], v[44:47]
	v_mfma_f32_16x16x32_bf16 v[0:3], v[148:151], v[172:175], v[0:3]
	v_mfma_f32_16x16x32_bf16 v[4:7], v[156:159], v[172:175], v[4:7]
	v_mfma_f32_16x16x32_bf16 v[8:11], v[148:151], v[184:187], v[8:11]
	v_mfma_f32_16x16x32_bf16 v[12:15], v[156:159], v[184:187], v[12:15]
	v_mfma_f32_16x16x32_bf16 v[16:19], v[148:151], v[192:195], v[16:19]
	v_mfma_f32_16x16x32_bf16 v[20:23], v[156:159], v[192:195], v[20:23]
	v_mfma_f32_16x16x32_bf16 v[36:39], v[148:151], v[200:203], v[36:39]
	v_mfma_f32_16x16x32_bf16 v[44:47], v[156:159], v[200:203], v[44:47]
	s_setprio 0
	s_barrier
	s_add_i32 s80, s80, s14
	v_lshl_add_u64 v[176:177], s[78:79], 0, v[160:161]
	s_mov_b32 m0, s80
	ds_read_b128 v[168:171], v179 offset:16384
	ds_read_b128 v[172:175], v179 offset:17408
	ds_read_b128 v[180:183], v179 offset:18432
	ds_read_b128 v[184:187], v179 offset:19456
	ds_read_b128 v[188:191], v179 offset:20480
	ds_read_b128 v[192:195], v179 offset:21504
	ds_read_b128 v[196:199], v179 offset:22528
	ds_read_b128 v[200:203], v179 offset:23552
	global_load_lds_dwordx4 v[176:177], off
	s_add_i32 m0, s80, 0x2000
	s_add_u32 s78, s78, s72
	v_lshl_add_u64 v[204:205], v[176:177], 0, s[2:3]
	s_addc_u32 s79, s79, 0
	global_load_lds_dwordx4 v[204:205], off
	v_lshl_add_u64 v[204:205], s[78:79], 0, v[160:161]
	s_add_i32 s78, s81, s14
	s_mov_b32 m0, s78
	v_lshl_add_u64 v[206:207], v[204:205], 0, s[2:3]
	global_load_lds_dwordx4 v[204:205], off
	s_add_i32 m0, s78, 0x2000
	s_nop 0
	global_load_lds_dwordx4 v[206:207], off
	v_lshl_add_u64 v[206:207], s[42:43], 0, v[162:163]
	s_mov_b32 m0, s34
	v_lshl_add_u64 v[208:209], v[206:207], 0, s[2:3]
	global_load_lds_dwordx4 v[206:207], off
	s_mov_b32 m0, s35
	s_nop 0
	global_load_lds_dwordx4 v[208:209], off
	s_waitcnt vmcnt(8)
	s_waitcnt lgkmcnt(0)
	s_barrier
; #define PG8_STAGE(bufoff, gbase, voff) do { _Pragma("unroll") for (int _i = 0; _i < 2; ++_i) \
;         __builtin_amdgcn_global_load_lds((const GAS unsigned*)((const GAS char*)(gbase) + (size_t)_i * r64##voff + (vo##voff)), (LAS unsigned*)(lds + (bufoff) + ldsw + _i * 8192), 16, 0, 0); } while (0)
; #define PG8_LDA(dst, b, h) do { _Pragma("unroll") for (int m = 0; m < 4; ++m) _Pragma("unroll") for (int k = 0; k < 2; ++k) dst[m][k] = *(const LAS bf16x8*)(lds + PG8_SA(b, h) + aoff + m * 2048 + k * 1024); } while (0)
; #define PG8_LDB(dst, b, h) do { _Pragma("unroll") for (int n = 0; n < 2; ++n) _Pragma("unroll") for (int k = 0; k < 2; ++k) dst[n][k] = *(const LAS bf16x8*)(lds + PG8_SB(b, h) + boff + n * 2048 + k * 1024); } while (0)
; #define PG8_MMA(ai, bj, At, Bt) do { __builtin_amdgcn_s_setprio(1); _Pragma("unroll") for (int m = 0; m < 4; ++m) _Pragma("unroll") for (int n = 0; n < 2; ++n) _Pragma("unroll") for (int k = 0; k < 2; ++k) \
;         acc[ai][bj][m][n] = __builtin_amdgcn_mfma_f32_16x16x32_bf16(Bt[n][k], At[m][k], acc[ai][bj][m][n], 0, 0, 0); __builtin_amdgcn_s_setprio(0); } while (0)
; #define PG8_WAIT_V(n) asm volatile("s_waitcnt vmcnt(" #n ")" ::: "memory")
; #define PG8_WAIT_L(n) asm volatile("s_waitcnt lgkmcnt(" #n ")" ::: "memory")
; #define PG8_BAR __builtin_amdgcn_s_barrier()
; #define PG8_SCHED __builtin_amdgcn_sched_barrier(0)
; template <class Epi, class Map, bool ALIGN_EPI>
; __device__ __forceinline__ void gemm_phase(const int tid, LAS unsigned char* lds, const int lda, const int ldb, const int K, const Map& MP, const StaticOrder& S, const Epi& E) {
;     ...
;             PG8_WAIT_V(8); PG8_WAIT_L(0); PG8_BAR; PG8_MMA(1, 0, At, B0); PG8_MMA(1, 1, At, B1); PG8_BAR; PG8_SCHED;
;             PG8_LDB(B0, 1, 0); PG8_LDB(B1, 1, 1); PG8_SCHED; PG8_LDA(At, 1, 0); PG8_STAGE(PG8_SA(0, 1), a2 + hstepA, A);
;             PG8_WAIT_V(8); PG8_WAIT_L(0); PG8_BAR; PG8_MMA(0, 0, At, B0); PG8_MMA(0, 1, At, B1); PG8_BAR; PG8_SCHED;
	s_setprio 1
	v_mfma_f32_16x16x32_bf16 v[84:87], v[128:131], v[168:171], v[84:87]
	v_mfma_f32_16x16x32_bf16 v[80:83], v[136:139], v[168:171], v[80:83]
	v_mfma_f32_16x16x32_bf16 v[116:119], v[128:131], v[180:183], v[116:119]
	v_mfma_f32_16x16x32_bf16 v[96:99], v[136:139], v[180:183], v[96:99]
	v_mfma_f32_16x16x32_bf16 v[124:127], v[128:131], v[188:191], v[124:127]
	v_mfma_f32_16x16x32_bf16 v[120:123], v[136:139], v[188:191], v[120:123]
	v_mfma_f32_16x16x32_bf16 v[108:111], v[128:131], v[196:199], v[108:111]
	v_mfma_f32_16x16x32_bf16 v[112:115], v[136:139], v[196:199], v[112:115]
	v_mfma_f32_16x16x32_bf16 v[84:87], v[132:135], v[172:175], v[84:87]
	v_mfma_f32_16x16x32_bf16 v[80:83], v[140:143], v[172:175], v[80:83]
	v_mfma_f32_16x16x32_bf16 v[116:119], v[132:135], v[184:187], v[116:119]
	v_mfma_f32_16x16x32_bf16 v[96:99], v[140:143], v[184:187], v[96:99]
	v_mfma_f32_16x16x32_bf16 v[124:127], v[132:135], v[192:195], v[124:127]
	v_mfma_f32_16x16x32_bf16 v[120:123], v[140:143], v[192:195], v[120:123]
	v_mfma_f32_16x16x32_bf16 v[108:111], v[132:135], v[200:203], v[108:111]
	v_mfma_f32_16x16x32_bf16 v[112:115], v[140:143], v[200:203], v[112:115]
	s_setprio 0
	s_setprio 1
	v_mfma_f32_16x16x32_bf16 v[56:59], v[144:147], v[168:171], v[56:59]
	v_mfma_f32_16x16x32_bf16 v[60:63], v[152:155], v[168:171], v[60:63]
	v_mfma_f32_16x16x32_bf16 v[72:75], v[144:147], v[180:183], v[72:75]
	v_mfma_f32_16x16x32_bf16 v[76:79], v[152:155], v[180:183], v[76:79]
	v_mfma_f32_16x16x32_bf16 v[92:95], v[144:147], v[188:191], v[92:95]
	v_mfma_f32_16x16x32_bf16 v[100:103], v[152:155], v[188:191], v[100:103]
	v_mfma_f32_16x16x32_bf16 v[104:107], v[144:147], v[196:199], v[104:107]
	v_mfma_f32_16x16x32_bf16 v[88:91], v[152:155], v[196:199], v[88:91]
	v_mfma_f32_16x16x32_bf16 v[56:59], v[148:151], v[172:175], v[56:59]
	v_mfma_f32_16x16x32_bf16 v[60:63], v[156:159], v[172:175], v[60:63]
	v_mfma_f32_16x16x32_bf16 v[72:75], v[148:151], v[184:187], v[72:75]
	v_mfma_f32_16x16x32_bf16 v[76:79], v[156:159], v[184:187], v[76:79]
	v_mfma_f32_16x16x32_bf16 v[92:95], v[148:151], v[192:195], v[92:95]
	v_mfma_f32_16x16x32_bf16 v[100:103], v[156:159], v[192:195], v[100:103]
	v_mfma_f32_16x16x32_bf16 v[104:107], v[148:151], v[200:203], v[104:107]
	v_mfma_f32_16x16x32_bf16 v[88:91], v[156:159], v[200:203], v[88:91]
	s_setprio 0
	s_barrier
	s_add_i32 s78, 0, 0x18000
	s_add_i32 s79, 0, 0x1c000
	v_add_u32_e32 v140, s78, v178
	v_add_u32_e32 v156, s79, v178
	ds_read_b128 v[128:131], v140
	ds_read_b128 v[132:135], v140 offset:1024
	ds_read_b128 v[136:139], v140 offset:2048
	ds_read_b128 v[140:143], v140 offset:3072
	ds_read_b128 v[144:147], v156
	ds_read_b128 v[148:151], v156 offset:1024
	ds_read_b128 v[152:155], v156 offset:2048
	ds_read_b128 v[156:159], v156 offset:3072
	s_add_u32 s42, s42, s72
	s_addc_u32 s43, s43, 0
	s_mov_b32 m0, s36
	v_lshl_add_u64 v[210:211], s[42:43], 0, v[162:163]
	ds_read_b128 v[168:171], v179 offset:32768
	ds_read_b128 v[172:175], v179 offset:33792
	ds_read_b128 v[180:183], v179 offset:34816
	ds_read_b128 v[184:187], v179 offset:35840
	ds_read_b128 v[188:191], v179 offset:36864
	ds_read_b128 v[192:195], v179 offset:37888
	ds_read_b128 v[196:199], v179 offset:38912
	ds_read_b128 v[200:203], v179 offset:39936
	global_load_lds_dwordx4 v[210:211], off
	v_lshl_add_u64 v[210:211], v[210:211], 0, s[2:3]
	s_mov_b32 m0, s37
	s_nop 0
	global_load_lds_dwordx4 v[210:211], off
	s_waitcnt vmcnt(8)
	s_waitcnt lgkmcnt(0)
	s_barrier
	s_setprio 1
	v_mfma_f32_16x16x32_bf16 v[40:43], v[128:131], v[168:171], v[40:43]
	v_mfma_f32_16x16x32_bf16 v[24:27], v[136:139], v[168:171], v[24:27]
	v_mfma_f32_16x16x32_bf16 v[32:35], v[128:131], v[180:183], v[32:35]
	v_mfma_f32_16x16x32_bf16 v[28:31], v[136:139], v[180:183], v[28:31]
	v_mfma_f32_16x16x32_bf16 v[52:55], v[128:131], v[188:191], v[52:55]
	v_mfma_f32_16x16x32_bf16 v[48:51], v[136:139], v[188:191], v[48:51]
	v_mfma_f32_16x16x32_bf16 v[68:71], v[128:131], v[196:199], v[68:71]
	v_mfma_f32_16x16x32_bf16 v[64:67], v[136:139], v[196:199], v[64:67]
	v_mfma_f32_16x16x32_bf16 v[40:43], v[132:135], v[172:175], v[40:43]
	v_mfma_f32_16x16x32_bf16 v[24:27], v[140:143], v[172:175], v[24:27]
	v_mfma_f32_16x16x32_bf16 v[32:35], v[132:135], v[184:187], v[32:35]
	v_mfma_f32_16x16x32_bf16 v[28:31], v[140:143], v[184:187], v[28:31]
	v_mfma_f32_16x16x32_bf16 v[52:55], v[132:135], v[192:195], v[52:55]
	v_mfma_f32_16x16x32_bf16 v[48:51], v[140:143], v[192:195], v[48:51]
	v_mfma_f32_16x16x32_bf16 v[68:71], v[132:135], v[200:203], v[68:71]
	v_mfma_f32_16x16x32_bf16 v[64:67], v[140:143], v[200:203], v[64:67]
	s_setprio 0
	s_setprio 1
	v_mfma_f32_16x16x32_bf16 v[0:3], v[144:147], v[168:171], v[0:3]
	v_mfma_f32_16x16x32_bf16 v[4:7], v[152:155], v[168:171], v[4:7]
	v_mfma_f32_16x16x32_bf16 v[8:11], v[144:147], v[180:183], v[8:11]
	v_mfma_f32_16x16x32_bf16 v[12:15], v[152:155], v[180:183], v[12:15]
	v_mfma_f32_16x16x32_bf16 v[16:19], v[144:147], v[188:191], v[16:19]
	v_mfma_f32_16x16x32_bf16 v[20:23], v[152:155], v[188:191], v[20:23]
	v_mfma_f32_16x16x32_bf16 v[36:39], v[144:147], v[196:199], v[36:39]
	v_mfma_f32_16x16x32_bf16 v[44:47], v[152:155], v[196:199], v[44:47]
	v_mfma_f32_16x16x32_bf16 v[0:3], v[148:151], v[172:175], v[0:3]
	v_mfma_f32_16x16x32_bf16 v[4:7], v[156:159], v[172:175], v[4:7]
	v_mfma_f32_16x16x32_bf16 v[8:11], v[148:151], v[184:187], v[8:11]
	v_mfma_f32_16x16x32_bf16 v[12:15], v[156:159], v[184:187], v[12:15]
	v_mfma_f32_16x16x32_bf16 v[16:19], v[148:151], v[192:195], v[16:19]
	v_mfma_f32_16x16x32_bf16 v[20:23], v[156:159], v[192:195], v[20:23]
	v_mfma_f32_16x16x32_bf16 v[36:39], v[148:151], v[200:203], v[36:39]
	v_mfma_f32_16x16x32_bf16 v[44:47], v[156:159], v[200:203], v[44:47]
	s_setprio 0
	s_barrier
; #define PG8_STAGE(bufoff, gbase, voff) do { _Pragma("unroll") for (int _i = 0; _i < 2; ++_i) \
;         __builtin_amdgcn_global_load_lds((const GAS unsigned*)((const GAS char*)(gbase) + (size_t)_i * r64##voff + (vo##voff)), (LAS unsigned*)(lds + (bufoff) + ldsw + _i * 8192), 16, 0, 0); } while (0)
; #define PG8_LDA(dst, b, h) do { _Pragma("unroll") for (int m = 0; m < 4; ++m) _Pragma("unroll") for (int k = 0; k < 2; ++k) dst[m][k] = *(const LAS bf16x8*)(lds + PG8_SA(b, h) + aoff + m * 2048 + k * 1024); } while (0)
; #define PG8_MMA(ai, bj, At, Bt) do { __builtin_amdgcn_s_setprio(1); _Pragma("unroll") for (int m = 0; m < 4; ++m) _Pragma("unroll") for (int n = 0; n < 2; ++n) _Pragma("unroll") for (int k = 0; k < 2; ++k) \
;         acc[ai][bj][m][n] = __builtin_amdgcn_mfma_f32_16x16x32_bf16(Bt[n][k], At[m][k], acc[ai][bj][m][n], 0, 0, 0); __builtin_amdgcn_s_setprio(0); } while (0)
; #define PG8_WAIT_V(n) asm volatile("s_waitcnt vmcnt(" #n ")" ::: "memory")
; #define PG8_WAIT_L(n) asm volatile("s_waitcnt lgkmcnt(" #n ")" ::: "memory")
; #define PG8_BAR __builtin_amdgcn_s_barrier()
; #define PG8_SCHED __builtin_amdgcn_sched_barrier(0)
; template <class Epi, class Map, bool ALIGN_EPI>
; __device__ __forceinline__ void gemm_phase(const int tid, LAS unsigned char* lds, const int lda, const int ldb, const int K, const Map& MP, const StaticOrder& S, const Epi& E) {
;     ...
;             PG8_LDA(At, 1, 1); PG8_STAGE(PG8_SB(1, 0), b3, B); PG8_STAGE(PG8_SB(1, 1), b3 + hstepB, B); PG8_STAGE(PG8_SA(1, 0), a3, A);
;             PG8_WAIT_V(8); PG8_WAIT_L(0); PG8_BAR; PG8_MMA(1, 0, At, B0); PG8_MMA(1, 1, At, B1); PG8_BAR; PG8_SCHED;
;         }
;         if constexpr (ALIGN_EPI) { if (wr == 0) PG8_BAR; }
	s_add_i32 s42, s78, s14
	v_lshl_add_u64 v[176:177], v[176:177], 0, s[50:51]
	s_mov_b32 m0, s42
	ds_read_b128 v[168:171], v179 offset:49152
	ds_read_b128 v[172:175], v179 offset:50176
	ds_read_b128 v[180:183], v179 offset:51200
	ds_read_b128 v[184:187], v179 offset:52224
	ds_read_b128 v[188:191], v179 offset:53248
	ds_read_b128 v[192:195], v179 offset:54272
	ds_read_b128 v[196:199], v179 offset:55296
	ds_read_b128 v[200:203], v179 offset:56320
	global_load_lds_dwordx4 v[176:177], off
	v_lshl_add_u64 v[176:177], v[176:177], 0, s[2:3]
	s_add_i32 m0, s42, 0x2000
	s_add_i32 s42, s79, s14
	global_load_lds_dwordx4 v[176:177], off
	v_lshl_add_u64 v[176:177], v[204:205], 0, s[50:51]
	s_mov_b32 m0, s42
	s_nop 0
	global_load_lds_dwordx4 v[176:177], off
	v_lshl_add_u64 v[176:177], v[176:177], 0, s[2:3]
	s_add_i32 m0, s42, 0x2000
	s_nop 0
	global_load_lds_dwordx4 v[176:177], off
	v_lshl_add_u64 v[176:177], v[206:207], 0, s[50:51]
	s_mov_b32 m0, s28
	s_nop 0
	global_load_lds_dwordx4 v[176:177], off
	v_lshl_add_u64 v[176:177], v[208:209], 0, s[50:51]
	s_mov_b32 m0, s29
	s_nop 0
	global_load_lds_dwordx4 v[176:177], off
	s_waitcnt vmcnt(8)
	s_waitcnt lgkmcnt(0)
	s_barrier
	s_setprio 1
	v_mfma_f32_16x16x32_bf16 v[84:87], v[128:131], v[168:171], v[84:87]
	v_mfma_f32_16x16x32_bf16 v[80:83], v[136:139], v[168:171], v[80:83]
	v_mfma_f32_16x16x32_bf16 v[116:119], v[128:131], v[180:183], v[116:119]
	v_mfma_f32_16x16x32_bf16 v[96:99], v[136:139], v[180:183], v[96:99]
	v_mfma_f32_16x16x32_bf16 v[124:127], v[128:131], v[188:191], v[124:127]
	v_mfma_f32_16x16x32_bf16 v[120:123], v[136:139], v[188:191], v[120:123]
	v_mfma_f32_16x16x32_bf16 v[108:111], v[128:131], v[196:199], v[108:111]
	v_mfma_f32_16x16x32_bf16 v[112:115], v[136:139], v[196:199], v[112:115]
	v_mfma_f32_16x16x32_bf16 v[84:87], v[132:135], v[172:175], v[84:87]
	v_mfma_f32_16x16x32_bf16 v[80:83], v[140:143], v[172:175], v[80:83]
	v_mfma_f32_16x16x32_bf16 v[116:119], v[132:135], v[184:187], v[116:119]
	v_mfma_f32_16x16x32_bf16 v[96:99], v[140:143], v[184:187], v[96:99]
	v_mfma_f32_16x16x32_bf16 v[124:127], v[132:135], v[192:195], v[124:127]
	v_mfma_f32_16x16x32_bf16 v[120:123], v[140:143], v[192:195], v[120:123]
	v_mfma_f32_16x16x32_bf16 v[108:111], v[132:135], v[200:203], v[108:111]
	v_mfma_f32_16x16x32_bf16 v[112:115], v[140:143], v[200:203], v[112:115]
	s_setprio 0
	s_setprio 1
	v_mfma_f32_16x16x32_bf16 v[56:59], v[144:147], v[168:171], v[56:59]
	v_mfma_f32_16x16x32_bf16 v[60:63], v[152:155], v[168:171], v[60:63]
	v_mfma_f32_16x16x32_bf16 v[72:75], v[144:147], v[180:183], v[72:75]
	v_mfma_f32_16x16x32_bf16 v[76:79], v[152:155], v[180:183], v[76:79]
	v_mfma_f32_16x16x32_bf16 v[92:95], v[144:147], v[188:191], v[92:95]
	v_mfma_f32_16x16x32_bf16 v[100:103], v[152:155], v[188:191], v[100:103]
	v_mfma_f32_16x16x32_bf16 v[104:107], v[144:147], v[196:199], v[104:107]
	v_mfma_f32_16x16x32_bf16 v[88:91], v[152:155], v[196:199], v[88:91]
	v_mfma_f32_16x16x32_bf16 v[56:59], v[148:151], v[172:175], v[56:59]
	v_mfma_f32_16x16x32_bf16 v[60:63], v[156:159], v[172:175], v[60:63]
	v_mfma_f32_16x16x32_bf16 v[72:75], v[148:151], v[184:187], v[72:75]
	v_mfma_f32_16x16x32_bf16 v[76:79], v[156:159], v[184:187], v[76:79]
	v_mfma_f32_16x16x32_bf16 v[92:95], v[148:151], v[192:195], v[92:95]
	v_mfma_f32_16x16x32_bf16 v[100:103], v[156:159], v[192:195], v[100:103]
	v_mfma_f32_16x16x32_bf16 v[104:107], v[148:151], v[200:203], v[104:107]
	v_mfma_f32_16x16x32_bf16 v[88:91], v[156:159], v[200:203], v[88:91]
	s_setprio 0
	s_barrier
	s_add_u32 s10, s10, 0x100
	s_addc_u32 s11, s11, 0
	s_add_u32 s45, s45, 0x100
	s_addc_u32 s46, s46, 0
	s_cmp_ge_u32 s47, s30
	s_mov_b32 s42, s47
	s_cbranch_scc0 .LBB0_1042
	s_and_b64 vcc, exec, s[56:57]
	s_cbranch_vccz .LBB0_1045
	s_barrier
